# gate epilogue LA/BT stores with nt hint
# speedup vs baseline: 1.0039x; 1.0039x over previous
; #define PG8_STAGE(bufoff, gbase, voff) do { _Pragma("unroll") for (int _i = 0; _i < 2; ++_i) \
;         __builtin_amdgcn_global_load_lds((const __attribute__((address_space(1))) unsigned*)((const char*)(gbase) + (voff)[_i]), (LAS unsigned*)(lds + (bufoff) + ldsw + _i * 8192), 16, 0, 0); } while (0)
; #define PG8_LDA(dst, b, h) do { _Pragma("unroll") for (int m = 0; m < 4; ++m) _Pragma("unroll") for (int k = 0; k < 2; ++k) dst[m][k] = *(const LAS bf16x8*)(lds + PG8_SA(b, h) + aoff + m * 2048 + k * 1024); } while (0)
; #define PG8_LDB(dst, b, h) do { _Pragma("unroll") for (int n = 0; n < 2; ++n) _Pragma("unroll") for (int k = 0; k < 2; ++k) dst[n][k] = *(const LAS bf16x8*)(lds + PG8_SB(b, h) + boff + n * 2048 + k * 1024); } while (0)
; #define PG8_MMA(ai, bj, At, Bt) do { __builtin_amdgcn_s_setprio(1); _Pragma("unroll") for (int m = 0; m < 4; ++m) _Pragma("unroll") for (int n = 0; n < 2; ++n) _Pragma("unroll") for (int k = 0; k < 2; ++k) \
;         acc[ai][bj][m][n] = __builtin_amdgcn_mfma_f32_16x16x32_bf16(Bt[n][k], At[m][k], acc[ai][bj][m][n], 0, 0, 0); __builtin_amdgcn_s_setprio(0); } while (0)
; #define PG8_WAIT_L(n) asm volatile("s_waitcnt lgkmcnt(" #n ")" ::: "memory")
; template <class Epi>
; __device__ __forceinline__ void gemm_phase(LAS unsigned char* lds, const Gemm g, const StaticOrder& S_in, const Epi& E, int sw) {
;     ...
;         const bool has_next = S.next(ui + 1, nxt);
;         const char* nA = has_next ? PG8_ABASE(nxt) : cA; const char* nB = has_next ? PG8_BBASE(nxt) : cB;
;         for (int t = 0; t < nt; t += 2) {
;             const bool last = (t == nt - 2);
;             const char* a1 = cA + (size_t)(t + 1) * kstep;
;             const char* a2 = last ? nA : cA + (size_t)(t + 2) * kstep; const char* b2 = last ? nB : cB + (size_t)(t + 2) * kstep;
;             const char* a3 = a2 + kstep; const char* b3 = b2 + kstep;
;             PG8_LDB(B0, 0, 0); PG8_SCHED; PG8_LDA(At, 0, 0); PG8_STAGE(PG8_SA(1, 1), a1 + hstepA, voffA);
;             PG8_WAIT_L(8); PG8_BAR; PG8_WAIT_L(0); PG8_MMA(0, 0, At, B0); PG8_BAR; PG8_SCHED;
;             PG8_LDB(B1, 0, 1); PG8_STAGE(PG8_SB(0, 0), b2, voffB);
;             PG8_BAR; PG8_WAIT_L(0); PG8_MMA(0, 1, At, B1); PG8_BAR;
;             PG8_LDA(At, 0, 1); PG8_STAGE(PG8_SA(0, 0), a2, voffA);
;             PG8_BAR; PG8_WAIT_L(0); PG8_MMA(1, 0, At, B0); PG8_BAR; PG8_SCHED;
.Lgate_ord_keep:
.LBB0_428:
	s_ashr_i32 s18, s12, 1
	s_ashr_i32 s17, s16, 31
	s_ashr_i32 s19, s18, 31
	s_lshl_b64 s[18:19], s[18:19], 9
	s_lshl_b64 s[20:21], s[16:17], 20
	s_add_u32 s13, s39, s20
	s_addc_u32 s17, s40, s21
	s_add_u32 s18, s13, s18
	s_addc_u32 s19, s17, s19
	s_and_b64 s[20:21], s[4:5], exec
	s_cselect_b32 s35, s19, s27
	s_cselect_b32 s34, s18, s26
	s_ashr_i32 s13, s12, 31
	s_lshl_b64 s[20:21], s[12:13], 17
	s_add_u32 s20, s41, s20
	s_addc_u32 s21, s42, s21
	s_and_b64 s[30:31], s[4:5], exec
	s_cselect_b32 s31, s21, s29
	s_cselect_b32 s30, s20, s28
	s_add_i32 s17, 0, 0x10000
	v_add_u32_e32 v175, s17, v171
	ds_read_b128 v[18:21], v175
	ds_read_b128 v[22:25], v175 offset:1024
	ds_read_b128 v[26:29], v175 offset:2048
	ds_read_b128 v[30:33], v175 offset:3072
	s_add_u32 s48, s26, 0x80080
	s_addc_u32 s49, s27, 0
	s_add_i32 s50, s23, 0xc000
	v_lshl_add_u64 v[66:67], s[48:49], 0, v[130:131]
	s_mov_b32 m0, s50
	s_add_i32 s13, s23, 0xe000
	ds_read_b128 v[34:37], v174
	ds_read_b128 v[38:41], v174 offset:1024
	ds_read_b128 v[42:45], v174 offset:2048
	ds_read_b128 v[46:49], v174 offset:3072
	ds_read_b128 v[50:53], v174 offset:4096
	ds_read_b128 v[54:57], v174 offset:5120
	ds_read_b128 v[58:61], v174 offset:6144
	ds_read_b128 v[62:65], v174 offset:7168
	global_load_lds_dwordx4 v[66:67], off
	v_lshl_add_u64 v[66:67], s[48:49], 0, v[132:133]
	s_mov_b32 m0, s13
	s_nop 0
	global_load_lds_dwordx4 v[66:67], off
	s_waitcnt lgkmcnt(8)
	s_barrier
	s_waitcnt lgkmcnt(0)
	s_setprio 1
	s_waitcnt lgkmcnt(0)
	v_mfma_f32_16x16x32_bf16 v[66:69], v[18:21], v[34:37], v[10:13]
	v_mfma_f32_16x16x32_bf16 v[70:73], v[26:29], v[34:37], v[14:17]
	v_mfma_f32_16x16x32_bf16 v[74:77], v[18:21], v[42:45], v[10:13]
	v_mfma_f32_16x16x32_bf16 v[78:81], v[26:29], v[42:45], v[14:17]
	v_mfma_f32_16x16x32_bf16 v[82:85], v[18:21], v[50:53], v[10:13]
	v_mfma_f32_16x16x32_bf16 v[86:89], v[26:29], v[50:53], v[14:17]
	v_mfma_f32_16x16x32_bf16 v[90:93], v[18:21], v[58:61], v[10:13]
	v_mfma_f32_16x16x32_bf16 v[94:97], v[26:29], v[58:61], v[14:17]
	v_mfma_f32_16x16x32_bf16 v[66:69], v[22:25], v[38:41], v[66:69]
	v_mfma_f32_16x16x32_bf16 v[70:73], v[30:33], v[38:41], v[70:73]
	v_mfma_f32_16x16x32_bf16 v[74:77], v[22:25], v[46:49], v[74:77]
	v_mfma_f32_16x16x32_bf16 v[78:81], v[30:33], v[46:49], v[78:81]
	v_mfma_f32_16x16x32_bf16 v[82:85], v[22:25], v[54:57], v[82:85]
	v_mfma_f32_16x16x32_bf16 v[86:89], v[30:33], v[54:57], v[86:89]
	v_mfma_f32_16x16x32_bf16 v[90:93], v[22:25], v[62:65], v[90:93]
	v_mfma_f32_16x16x32_bf16 v[94:97], v[30:33], v[62:65], v[94:97]
	s_setprio 0
	s_barrier
	s_add_i32 s51, 0, 0x14000
	v_lshl_add_u64 v[168:169], s[28:29], 0, v[0:1]
	s_mov_b64 s[52:53], 0x100
	s_add_i32 s49, s17, s38
	v_add_u32_e32 v212, s51, v171
	v_lshl_add_u64 v[114:115], v[168:169], 0, s[52:53]
	s_mov_b32 m0, s49
	v_lshl_add_u64 v[172:173], s[28:29], 0, v[134:135]
	s_add_i32 s17, s49, 0x2000
	ds_read_b128 v[98:101], v212
	ds_read_b128 v[102:105], v212 offset:1024
	ds_read_b128 v[106:109], v212 offset:2048
	ds_read_b128 v[110:113], v212 offset:3072
	global_load_lds_dwordx4 v[114:115], off
	v_lshl_add_u64 v[114:115], v[172:173], 0, s[52:53]
	s_mov_b32 m0, s17
	s_nop 0
	global_load_lds_dwordx4 v[114:115], off
	s_barrier
	s_waitcnt lgkmcnt(0)
	s_setprio 1
	s_waitcnt lgkmcnt(0)
	v_mfma_f32_16x16x32_bf16 v[114:117], v[98:101], v[34:37], v[2:5]
	v_mfma_f32_16x16x32_bf16 v[34:37], v[106:109], v[34:37], v[6:9]
	v_mfma_f32_16x16x32_bf16 v[114:117], v[102:105], v[38:41], v[114:117]
	v_mfma_f32_16x16x32_bf16 v[34:37], v[110:113], v[38:41], v[34:37]
	v_mfma_f32_16x16x32_bf16 v[38:41], v[98:101], v[42:45], v[2:5]
	v_mfma_f32_16x16x32_bf16 v[42:45], v[106:109], v[42:45], v[6:9]
	v_mfma_f32_16x16x32_bf16 v[38:41], v[102:105], v[46:49], v[38:41]
	v_mfma_f32_16x16x32_bf16 v[42:45], v[110:113], v[46:49], v[42:45]
	v_mfma_f32_16x16x32_bf16 v[46:49], v[98:101], v[50:53], v[2:5]
	v_mfma_f32_16x16x32_bf16 v[50:53], v[106:109], v[50:53], v[6:9]
	v_mfma_f32_16x16x32_bf16 v[46:49], v[102:105], v[54:57], v[46:49]
	v_mfma_f32_16x16x32_bf16 v[50:53], v[110:113], v[54:57], v[50:53]
	v_mfma_f32_16x16x32_bf16 v[54:57], v[98:101], v[58:61], v[2:5]
	v_mfma_f32_16x16x32_bf16 v[58:61], v[106:109], v[58:61], v[6:9]
	v_mfma_f32_16x16x32_bf16 v[54:57], v[102:105], v[62:65], v[54:57]
	v_mfma_f32_16x16x32_bf16 v[58:61], v[110:113], v[62:65], v[58:61]
	s_setprio 0
	v_lshl_add_u64 v[208:209], s[26:27], 0, v[130:131]
	s_mov_b32 m0, s23
	v_lshl_add_u64 v[152:153], v[208:209], 0, s[52:53]
	v_lshl_add_u64 v[210:211], s[26:27], 0, v[132:133]
	s_barrier
	ds_read_b128 v[62:65], v174 offset:16384
	ds_read_b128 v[118:121], v174 offset:17408
	ds_read_b128 v[122:125], v174 offset:18432
	ds_read_b128 v[126:129], v174 offset:19456
	ds_read_b128 v[136:139], v174 offset:20480
	ds_read_b128 v[140:143], v174 offset:21504
	ds_read_b128 v[144:147], v174 offset:22528
	ds_read_b128 v[148:151], v174 offset:23552
	global_load_lds_dwordx4 v[152:153], off
	v_lshl_add_u64 v[152:153], v[210:211], 0, s[52:53]
	s_mov_b32 m0, s25
	s_nop 0
	global_load_lds_dwordx4 v[152:153], off
	s_barrier
; #define PG8_STAGE(bufoff, gbase, voff) do { _Pragma("unroll") for (int _i = 0; _i < 2; ++_i) \
;         __builtin_amdgcn_global_load_lds((const __attribute__((address_space(1))) unsigned*)((const char*)(gbase) + (voff)[_i]), (LAS unsigned*)(lds + (bufoff) + ldsw + _i * 8192), 16, 0, 0); } while (0)
; #define PG8_LDA(dst, b, h) do { _Pragma("unroll") for (int m = 0; m < 4; ++m) _Pragma("unroll") for (int k = 0; k < 2; ++k) dst[m][k] = *(const LAS bf16x8*)(lds + PG8_SA(b, h) + aoff + m * 2048 + k * 1024); } while (0)
; #define PG8_LDB(dst, b, h) do { _Pragma("unroll") for (int n = 0; n < 2; ++n) _Pragma("unroll") for (int k = 0; k < 2; ++k) dst[n][k] = *(const LAS bf16x8*)(lds + PG8_SB(b, h) + boff + n * 2048 + k * 1024); } while (0)
; #define PG8_MMA(ai, bj, At, Bt) do { __builtin_amdgcn_s_setprio(1); _Pragma("unroll") for (int m = 0; m < 4; ++m) _Pragma("unroll") for (int n = 0; n < 2; ++n) _Pragma("unroll") for (int k = 0; k < 2; ++k) \
;         acc[ai][bj][m][n] = __builtin_amdgcn_mfma_f32_16x16x32_bf16(Bt[n][k], At[m][k], acc[ai][bj][m][n], 0, 0, 0); __builtin_amdgcn_s_setprio(0); } while (0)
; #define PG8_WAIT_V(n) asm volatile("s_waitcnt vmcnt(" #n ")" ::: "memory")
; #define PG8_WAIT_L(n) asm volatile("s_waitcnt lgkmcnt(" #n ")" ::: "memory")
; #define PG8_BAR __builtin_amdgcn_s_barrier()
; #define PG8_SCHED __builtin_amdgcn_sched_barrier(0)
; template <class Epi>
; __device__ __forceinline__ void gemm_phase(LAS unsigned char* lds, const Gemm g, const StaticOrder& S_in, const Epi& E, int sw) {
;     ...
;             PG8_BAR; PG8_WAIT_L(0); PG8_MMA(1, 0, At, B0); PG8_BAR; PG8_SCHED;
;             PG8_STAGE(PG8_SB(0, 1), b2 + hstepB, voffB);
;             PG8_WAIT_V(6); PG8_BAR; PG8_MMA(1, 1, At, B1); PG8_BAR;
;             PG8_LDB(B0, 1, 0); PG8_SCHED; PG8_LDA(At, 1, 0); PG8_STAGE(PG8_SA(0, 1), a2 + hstepA, voffA);
;             PG8_WAIT_L(8); PG8_BAR; PG8_WAIT_L(0); PG8_MMA(0, 0, At, B0); PG8_BAR; PG8_SCHED;
;             PG8_LDB(B1, 1, 1); PG8_STAGE(PG8_SB(1, 0), b3, voffB);
	s_waitcnt lgkmcnt(0)
	s_setprio 1
	s_waitcnt lgkmcnt(0)
	v_mfma_f32_16x16x32_bf16 v[152:155], v[18:21], v[62:65], v[10:13]
	v_mfma_f32_16x16x32_bf16 v[156:159], v[26:29], v[62:65], v[14:17]
	v_mfma_f32_16x16x32_bf16 v[160:163], v[18:21], v[122:125], v[10:13]
	v_mfma_f32_16x16x32_bf16 v[164:167], v[26:29], v[122:125], v[14:17]
	v_mfma_f32_16x16x32_bf16 v[176:179], v[18:21], v[136:139], v[10:13]
	v_mfma_f32_16x16x32_bf16 v[180:183], v[26:29], v[136:139], v[14:17]
	v_mfma_f32_16x16x32_bf16 v[10:13], v[18:21], v[144:147], v[10:13]
	v_mfma_f32_16x16x32_bf16 v[14:17], v[26:29], v[144:147], v[14:17]
	v_mfma_f32_16x16x32_bf16 v[152:155], v[22:25], v[118:121], v[152:155]
	v_mfma_f32_16x16x32_bf16 v[156:159], v[30:33], v[118:121], v[156:159]
	v_mfma_f32_16x16x32_bf16 v[160:163], v[22:25], v[126:129], v[160:163]
	v_mfma_f32_16x16x32_bf16 v[164:167], v[30:33], v[126:129], v[164:167]
	v_mfma_f32_16x16x32_bf16 v[10:13], v[22:25], v[148:151], v[10:13]
	v_mfma_f32_16x16x32_bf16 v[14:17], v[30:33], v[148:151], v[14:17]
	v_mfma_f32_16x16x32_bf16 v[176:179], v[22:25], v[140:143], v[176:179]
	v_mfma_f32_16x16x32_bf16 v[180:183], v[30:33], v[140:143], v[180:183]
	s_setprio 0
	s_barrier
	s_add_u32 s52, s28, 0x10100
	s_addc_u32 s53, s29, 0
	s_add_i32 s51, s51, s38
	v_lshl_add_u64 v[18:19], s[52:53], 0, v[0:1]
	s_mov_b32 m0, s51
	s_add_i32 s48, s51, 0x2000
	global_load_lds_dwordx4 v[18:19], off
	v_lshl_add_u64 v[18:19], s[52:53], 0, v[134:135]
	s_mov_b32 m0, s48
	s_nop 0
	global_load_lds_dwordx4 v[18:19], off
	s_waitcnt vmcnt(6)
	s_barrier
	s_setprio 1
	v_mfma_f32_16x16x32_bf16 v[18:21], v[98:101], v[62:65], v[2:5]
	v_mfma_f32_16x16x32_bf16 v[22:25], v[106:109], v[62:65], v[6:9]
	v_mfma_f32_16x16x32_bf16 v[18:21], v[102:105], v[118:121], v[18:21]
	v_mfma_f32_16x16x32_bf16 v[22:25], v[110:113], v[118:121], v[22:25]
	v_mfma_f32_16x16x32_bf16 v[26:29], v[98:101], v[122:125], v[2:5]
	v_mfma_f32_16x16x32_bf16 v[30:33], v[106:109], v[122:125], v[6:9]
	v_mfma_f32_16x16x32_bf16 v[62:65], v[98:101], v[136:139], v[2:5]
	v_mfma_f32_16x16x32_bf16 v[118:121], v[106:109], v[136:139], v[6:9]
	v_mfma_f32_16x16x32_bf16 v[2:5], v[98:101], v[144:147], v[2:5]
	v_mfma_f32_16x16x32_bf16 v[6:9], v[106:109], v[144:147], v[6:9]
	v_mfma_f32_16x16x32_bf16 v[26:29], v[102:105], v[126:129], v[26:29]
	v_mfma_f32_16x16x32_bf16 v[30:33], v[110:113], v[126:129], v[30:33]
	v_mfma_f32_16x16x32_bf16 v[62:65], v[102:105], v[140:143], v[62:65]
	v_mfma_f32_16x16x32_bf16 v[118:121], v[110:113], v[140:143], v[118:121]
	v_mfma_f32_16x16x32_bf16 v[2:5], v[102:105], v[148:151], v[2:5]
	v_mfma_f32_16x16x32_bf16 v[6:9], v[110:113], v[148:151], v[6:9]
	s_setprio 0
	s_add_i32 s54, 0, 0x18000
	v_add_u32_e32 v220, s54, v171
	s_barrier
	ds_read_b128 v[98:101], v220
	ds_read_b128 v[102:105], v220 offset:1024
	ds_read_b128 v[106:109], v220 offset:2048
	ds_read_b128 v[110:113], v220 offset:3072
	s_add_u32 s52, s26, 0x80100
	s_addc_u32 s53, s27, 0
	s_mov_b32 m0, s43
	v_lshl_add_u64 v[192:193], s[52:53], 0, v[130:131]
	ds_read_b128 v[122:125], v174 offset:32768
	ds_read_b128 v[126:129], v174 offset:33792
	ds_read_b128 v[136:139], v174 offset:34816
	ds_read_b128 v[140:143], v174 offset:35840
	ds_read_b128 v[144:147], v174 offset:36864
	ds_read_b128 v[148:151], v174 offset:37888
	ds_read_b128 v[184:187], v174 offset:38912
	ds_read_b128 v[188:191], v174 offset:39936
	global_load_lds_dwordx4 v[192:193], off
	v_lshl_add_u64 v[192:193], s[52:53], 0, v[132:133]
	s_mov_b32 m0, s44
	s_nop 0
	global_load_lds_dwordx4 v[192:193], off
	s_waitcnt lgkmcnt(8)
	s_barrier
	s_waitcnt lgkmcnt(0)
	s_setprio 1
	s_waitcnt lgkmcnt(0)
	v_mfma_f32_16x16x32_bf16 v[66:69], v[98:101], v[122:125], v[66:69]
	v_mfma_f32_16x16x32_bf16 v[70:73], v[106:109], v[122:125], v[70:73]
	v_mfma_f32_16x16x32_bf16 v[74:77], v[98:101], v[136:139], v[74:77]
	v_mfma_f32_16x16x32_bf16 v[78:81], v[106:109], v[136:139], v[78:81]
	v_mfma_f32_16x16x32_bf16 v[82:85], v[98:101], v[144:147], v[82:85]
	v_mfma_f32_16x16x32_bf16 v[86:89], v[106:109], v[144:147], v[86:89]
	v_mfma_f32_16x16x32_bf16 v[90:93], v[98:101], v[184:187], v[90:93]
	v_mfma_f32_16x16x32_bf16 v[94:97], v[106:109], v[184:187], v[94:97]
	v_mfma_f32_16x16x32_bf16 v[66:69], v[102:105], v[126:129], v[66:69]
	v_mfma_f32_16x16x32_bf16 v[70:73], v[110:113], v[126:129], v[70:73]
	v_mfma_f32_16x16x32_bf16 v[74:77], v[102:105], v[140:143], v[74:77]
	v_mfma_f32_16x16x32_bf16 v[78:81], v[110:113], v[140:143], v[78:81]
	v_mfma_f32_16x16x32_bf16 v[82:85], v[102:105], v[148:151], v[82:85]
	v_mfma_f32_16x16x32_bf16 v[86:89], v[110:113], v[148:151], v[86:89]
	v_mfma_f32_16x16x32_bf16 v[90:93], v[102:105], v[188:191], v[90:93]
	v_mfma_f32_16x16x32_bf16 v[94:97], v[110:113], v[188:191], v[94:97]
	s_setprio 0
	s_barrier
	s_add_i32 s56, 0, 0x1c000
	s_mov_b64 s[58:59], 0x180
	s_add_i32 s53, s54, s38
	v_add_u32_e32 v232, s56, v171
	v_lshl_add_u64 v[168:169], v[168:169], 0, s[58:59]
	s_mov_b32 m0, s53
	s_add_i32 s52, s53, 0x2000
	ds_read_b128 v[192:195], v232
	ds_read_b128 v[196:199], v232 offset:1024
	ds_read_b128 v[200:203], v232 offset:2048
	ds_read_b128 v[204:207], v232 offset:3072
	global_load_lds_dwordx4 v[168:169], off
	v_lshl_add_u64 v[168:169], v[172:173], 0, s[58:59]
	s_mov_b32 m0, s52
	s_nop 0
	global_load_lds_dwordx4 v[168:169], off
	s_barrier
; #define PG8_STAGE(bufoff, gbase, voff) do { _Pragma("unroll") for (int _i = 0; _i < 2; ++_i) \
;         __builtin_amdgcn_global_load_lds((const __attribute__((address_space(1))) unsigned*)((const char*)(gbase) + (voff)[_i]), (LAS unsigned*)(lds + (bufoff) + ldsw + _i * 8192), 16, 0, 0); } while (0)
; #define PG8_LDA(dst, b, h) do { _Pragma("unroll") for (int m = 0; m < 4; ++m) _Pragma("unroll") for (int k = 0; k < 2; ++k) dst[m][k] = *(const LAS bf16x8*)(lds + PG8_SA(b, h) + aoff + m * 2048 + k * 1024); } while (0)
; #define PG8_LDB(dst, b, h) do { _Pragma("unroll") for (int n = 0; n < 2; ++n) _Pragma("unroll") for (int k = 0; k < 2; ++k) dst[n][k] = *(const LAS bf16x8*)(lds + PG8_SB(b, h) + boff + n * 2048 + k * 1024); } while (0)
; #define PG8_MMA(ai, bj, At, Bt) do { __builtin_amdgcn_s_setprio(1); _Pragma("unroll") for (int m = 0; m < 4; ++m) _Pragma("unroll") for (int n = 0; n < 2; ++n) _Pragma("unroll") for (int k = 0; k < 2; ++k) \
;         acc[ai][bj][m][n] = __builtin_amdgcn_mfma_f32_16x16x32_bf16(Bt[n][k], At[m][k], acc[ai][bj][m][n], 0, 0, 0); __builtin_amdgcn_s_setprio(0); } while (0)
; #define PG8_WAIT_V(n) asm volatile("s_waitcnt vmcnt(" #n ")" ::: "memory")
; #define PG8_WAIT_L(n) asm volatile("s_waitcnt lgkmcnt(" #n ")" ::: "memory")
; #define PG8_BAR __builtin_amdgcn_s_barrier()
; #define PG8_SCHED __builtin_amdgcn_sched_barrier(0)
; template <class Epi>
; __device__ __forceinline__ void gemm_phase(LAS unsigned char* lds, const Gemm g, const StaticOrder& S_in, const Epi& E, int sw) {
;     ...
;             PG8_LDB(B0, 0, 0); PG8_SCHED; PG8_LDA(At, 0, 0); PG8_STAGE(PG8_SA(1, 1), a1 + hstepA, voffA);
;     ...
;             PG8_BAR; PG8_WAIT_L(0); PG8_MMA(0, 1, At, B1); PG8_BAR;
;             PG8_LDA(At, 1, 1); PG8_STAGE(PG8_SA(1, 0), a3, voffA);
;             PG8_BAR; PG8_WAIT_L(0); PG8_MMA(1, 0, At, B0); PG8_BAR; PG8_SCHED;
;             PG8_STAGE(PG8_SB(1, 1), b3 + hstepB, voffB);
;             PG8_WAIT_V(6); PG8_BAR; PG8_MMA(1, 1, At, B1); PG8_BAR;
	s_waitcnt lgkmcnt(0)
	s_setprio 1
	s_waitcnt lgkmcnt(0)
	v_mfma_f32_16x16x32_bf16 v[114:117], v[192:195], v[122:125], v[114:117]
	v_mfma_f32_16x16x32_bf16 v[34:37], v[200:203], v[122:125], v[34:37]
	v_mfma_f32_16x16x32_bf16 v[38:41], v[192:195], v[136:139], v[38:41]
	v_mfma_f32_16x16x32_bf16 v[42:45], v[200:203], v[136:139], v[42:45]
	v_mfma_f32_16x16x32_bf16 v[46:49], v[192:195], v[144:147], v[46:49]
	v_mfma_f32_16x16x32_bf16 v[50:53], v[200:203], v[144:147], v[50:53]
	v_mfma_f32_16x16x32_bf16 v[54:57], v[192:195], v[184:187], v[54:57]
	v_mfma_f32_16x16x32_bf16 v[58:61], v[200:203], v[184:187], v[58:61]
	v_mfma_f32_16x16x32_bf16 v[114:117], v[196:199], v[126:129], v[114:117]
	v_mfma_f32_16x16x32_bf16 v[34:37], v[204:207], v[126:129], v[34:37]
	v_mfma_f32_16x16x32_bf16 v[38:41], v[196:199], v[140:143], v[38:41]
	v_mfma_f32_16x16x32_bf16 v[42:45], v[204:207], v[140:143], v[42:45]
	v_mfma_f32_16x16x32_bf16 v[46:49], v[196:199], v[148:151], v[46:49]
	v_mfma_f32_16x16x32_bf16 v[50:53], v[204:207], v[148:151], v[50:53]
	v_mfma_f32_16x16x32_bf16 v[54:57], v[196:199], v[188:191], v[54:57]
	v_mfma_f32_16x16x32_bf16 v[58:61], v[204:207], v[188:191], v[58:61]
	s_setprio 0
	s_mov_b32 m0, s45
	v_lshl_add_u64 v[168:169], v[208:209], 0, s[58:59]
	s_barrier
	ds_read_b128 v[122:125], v174 offset:49152
	ds_read_b128 v[126:129], v174 offset:50176
	ds_read_b128 v[136:139], v174 offset:51200
	ds_read_b128 v[140:143], v174 offset:52224
	ds_read_b128 v[144:147], v174 offset:53248
	ds_read_b128 v[148:151], v174 offset:54272
	ds_read_b128 v[184:187], v174 offset:55296
	ds_read_b128 v[188:191], v174 offset:56320
	global_load_lds_dwordx4 v[168:169], off
	v_lshl_add_u64 v[168:169], v[210:211], 0, s[58:59]
	s_mov_b32 m0, s46
	s_nop 0
	global_load_lds_dwordx4 v[168:169], off
	s_barrier
	s_waitcnt lgkmcnt(0)
	s_setprio 1
	s_waitcnt lgkmcnt(0)
	v_mfma_f32_16x16x32_bf16 v[152:155], v[98:101], v[122:125], v[152:155]
	v_mfma_f32_16x16x32_bf16 v[156:159], v[106:109], v[122:125], v[156:159]
	v_mfma_f32_16x16x32_bf16 v[160:163], v[98:101], v[136:139], v[160:163]
	v_mfma_f32_16x16x32_bf16 v[164:167], v[106:109], v[136:139], v[164:167]
	v_mfma_f32_16x16x32_bf16 v[10:13], v[98:101], v[184:187], v[10:13]
	v_mfma_f32_16x16x32_bf16 v[14:17], v[106:109], v[184:187], v[14:17]
	v_mfma_f32_16x16x32_bf16 v[152:155], v[102:105], v[126:129], v[152:155]
	v_mfma_f32_16x16x32_bf16 v[156:159], v[110:113], v[126:129], v[156:159]
	v_mfma_f32_16x16x32_bf16 v[160:163], v[102:105], v[140:143], v[160:163]
	v_mfma_f32_16x16x32_bf16 v[164:167], v[110:113], v[140:143], v[164:167]
	v_mfma_f32_16x16x32_bf16 v[176:179], v[98:101], v[144:147], v[176:179]
	v_mfma_f32_16x16x32_bf16 v[180:183], v[106:109], v[144:147], v[180:183]
	v_mfma_f32_16x16x32_bf16 v[10:13], v[102:105], v[188:191], v[10:13]
	v_mfma_f32_16x16x32_bf16 v[14:17], v[110:113], v[188:191], v[14:17]
	v_mfma_f32_16x16x32_bf16 v[176:179], v[102:105], v[148:151], v[176:179]
	v_mfma_f32_16x16x32_bf16 v[180:183], v[110:113], v[148:151], v[180:183]
	s_setprio 0
	s_barrier
	s_add_u32 s54, s28, 0x10180
	s_addc_u32 s55, s29, 0
	s_add_i32 s29, s56, s38
	v_lshl_add_u64 v[98:99], s[54:55], 0, v[0:1]
	s_mov_b32 m0, s29
	s_add_i32 s28, s29, 0x2000
	global_load_lds_dwordx4 v[98:99], off
	v_lshl_add_u64 v[98:99], s[54:55], 0, v[134:135]
	s_mov_b32 m0, s28
	s_nop 0
	global_load_lds_dwordx4 v[98:99], off
	s_waitcnt vmcnt(6)
	s_barrier
	s_setprio 1
	v_mfma_f32_16x16x32_bf16 v[18:21], v[192:195], v[122:125], v[18:21]
	v_mfma_f32_16x16x32_bf16 v[22:25], v[200:203], v[122:125], v[22:25]
	v_mfma_f32_16x16x32_bf16 v[26:29], v[192:195], v[136:139], v[26:29]
	v_mfma_f32_16x16x32_bf16 v[30:33], v[200:203], v[136:139], v[30:33]
	v_mfma_f32_16x16x32_bf16 v[62:65], v[192:195], v[144:147], v[62:65]
	v_mfma_f32_16x16x32_bf16 v[98:101], v[200:203], v[144:147], v[118:121]
	v_mfma_f32_16x16x32_bf16 v[2:5], v[192:195], v[184:187], v[2:5]
	v_mfma_f32_16x16x32_bf16 v[6:9], v[200:203], v[184:187], v[6:9]
	v_mfma_f32_16x16x32_bf16 v[18:21], v[196:199], v[126:129], v[18:21]
	v_mfma_f32_16x16x32_bf16 v[22:25], v[204:207], v[126:129], v[22:25]
	v_mfma_f32_16x16x32_bf16 v[26:29], v[196:199], v[140:143], v[26:29]
	v_mfma_f32_16x16x32_bf16 v[30:33], v[204:207], v[140:143], v[30:33]
	v_mfma_f32_16x16x32_bf16 v[62:65], v[196:199], v[148:151], v[62:65]
	v_mfma_f32_16x16x32_bf16 v[98:101], v[204:207], v[148:151], v[98:101]
	v_mfma_f32_16x16x32_bf16 v[2:5], v[196:199], v[188:191], v[2:5]
	v_mfma_f32_16x16x32_bf16 v[6:9], v[204:207], v[188:191], v[6:9]
	s_setprio 0
	s_barrier
	ds_read_b128 v[102:105], v175
	ds_read_b128 v[106:109], v175 offset:1024
	ds_read_b128 v[110:113], v175 offset:2048
	ds_read_b128 v[118:121], v175 offset:3072
	s_add_u32 s26, s26, 0x80180
	s_addc_u32 s27, s27, 0
	s_mov_b32 m0, s50
	v_lshl_add_u64 v[168:169], s[26:27], 0, v[130:131]
	ds_read_b128 v[122:125], v174
	ds_read_b128 v[126:129], v174 offset:1024
	ds_read_b128 v[136:139], v174 offset:2048
	ds_read_b128 v[140:143], v174 offset:3072
	ds_read_b128 v[144:147], v174 offset:4096
	ds_read_b128 v[148:151], v174 offset:5120
	ds_read_b128 v[184:187], v174 offset:6144
	ds_read_b128 v[188:191], v174 offset:7168
	global_load_lds_dwordx4 v[168:169], off
	v_lshl_add_u64 v[168:169], s[26:27], 0, v[132:133]
	s_mov_b32 m0, s13
	s_nop 0
	global_load_lds_dwordx4 v[168:169], off
	s_waitcnt lgkmcnt(8)
	s_barrier
; #define PG8_STAGE(bufoff, gbase, voff) do { _Pragma("unroll") for (int _i = 0; _i < 2; ++_i) \
;         __builtin_amdgcn_global_load_lds((const __attribute__((address_space(1))) unsigned*)((const char*)(gbase) + (voff)[_i]), (LAS unsigned*)(lds + (bufoff) + ldsw + _i * 8192), 16, 0, 0); } while (0)
; #define PG8_LDA(dst, b, h) do { _Pragma("unroll") for (int m = 0; m < 4; ++m) _Pragma("unroll") for (int k = 0; k < 2; ++k) dst[m][k] = *(const LAS bf16x8*)(lds + PG8_SA(b, h) + aoff + m * 2048 + k * 1024); } while (0)
; #define PG8_LDB(dst, b, h) do { _Pragma("unroll") for (int n = 0; n < 2; ++n) _Pragma("unroll") for (int k = 0; k < 2; ++k) dst[n][k] = *(const LAS bf16x8*)(lds + PG8_SB(b, h) + boff + n * 2048 + k * 1024); } while (0)
; #define PG8_MMA(ai, bj, At, Bt) do { __builtin_amdgcn_s_setprio(1); _Pragma("unroll") for (int m = 0; m < 4; ++m) _Pragma("unroll") for (int n = 0; n < 2; ++n) _Pragma("unroll") for (int k = 0; k < 2; ++k) \
;         acc[ai][bj][m][n] = __builtin_amdgcn_mfma_f32_16x16x32_bf16(Bt[n][k], At[m][k], acc[ai][bj][m][n], 0, 0, 0); __builtin_amdgcn_s_setprio(0); } while (0)
; #define PG8_WAIT_V(n) asm volatile("s_waitcnt vmcnt(" #n ")" ::: "memory")
; #define PG8_WAIT_L(n) asm volatile("s_waitcnt lgkmcnt(" #n ")" ::: "memory")
; #define PG8_BAR __builtin_amdgcn_s_barrier()
; #define PG8_SCHED __builtin_amdgcn_sched_barrier(0)
; template <class Epi>
; __device__ __forceinline__ void gemm_phase(LAS unsigned char* lds, const Gemm g, const StaticOrder& S_in, const Epi& E, int sw) {
;     ...
;             PG8_WAIT_L(8); PG8_BAR; PG8_WAIT_L(0); PG8_MMA(0, 0, At, B0); PG8_BAR; PG8_SCHED;
;             PG8_LDB(B1, 0, 1); PG8_STAGE(PG8_SB(0, 0), b2, voffB);
;             PG8_BAR; PG8_WAIT_L(0); PG8_MMA(0, 1, At, B1); PG8_BAR;
;             PG8_LDA(At, 0, 1); PG8_STAGE(PG8_SA(0, 0), a2, voffA);
;             PG8_BAR; PG8_WAIT_L(0); PG8_MMA(1, 0, At, B0); PG8_BAR; PG8_SCHED;
;             PG8_STAGE(PG8_SB(0, 1), b2 + hstepB, voffB);
;             PG8_WAIT_V(6); PG8_BAR; PG8_MMA(1, 1, At, B1); PG8_BAR;
	s_waitcnt lgkmcnt(0)
	s_setprio 1
	s_waitcnt lgkmcnt(0)
	v_mfma_f32_16x16x32_bf16 v[66:69], v[102:105], v[122:125], v[66:69]
	v_mfma_f32_16x16x32_bf16 v[70:73], v[110:113], v[122:125], v[70:73]
	v_mfma_f32_16x16x32_bf16 v[74:77], v[102:105], v[136:139], v[74:77]
	v_mfma_f32_16x16x32_bf16 v[78:81], v[110:113], v[136:139], v[78:81]
	v_mfma_f32_16x16x32_bf16 v[82:85], v[102:105], v[144:147], v[82:85]
	v_mfma_f32_16x16x32_bf16 v[86:89], v[110:113], v[144:147], v[86:89]
	v_mfma_f32_16x16x32_bf16 v[90:93], v[102:105], v[184:187], v[90:93]
	v_mfma_f32_16x16x32_bf16 v[94:97], v[110:113], v[184:187], v[94:97]
	v_mfma_f32_16x16x32_bf16 v[66:69], v[106:109], v[126:129], v[66:69]
	v_mfma_f32_16x16x32_bf16 v[70:73], v[118:121], v[126:129], v[70:73]
	v_mfma_f32_16x16x32_bf16 v[74:77], v[106:109], v[140:143], v[74:77]
	v_mfma_f32_16x16x32_bf16 v[78:81], v[118:121], v[140:143], v[78:81]
	v_mfma_f32_16x16x32_bf16 v[82:85], v[106:109], v[148:151], v[82:85]
	v_mfma_f32_16x16x32_bf16 v[86:89], v[118:121], v[148:151], v[86:89]
	v_mfma_f32_16x16x32_bf16 v[90:93], v[106:109], v[188:191], v[90:93]
	v_mfma_f32_16x16x32_bf16 v[94:97], v[118:121], v[188:191], v[94:97]
	s_setprio 0
	s_barrier
	s_mov_b32 m0, s49
	v_lshl_add_u64 v[168:169], s[30:31], 0, v[0:1]
	ds_read_b128 v[192:195], v212
	ds_read_b128 v[196:199], v212 offset:1024
	ds_read_b128 v[200:203], v212 offset:2048
	ds_read_b128 v[204:207], v212 offset:3072
	global_load_lds_dwordx4 v[168:169], off
	v_lshl_add_u64 v[172:173], s[30:31], 0, v[134:135]
	s_mov_b32 m0, s17
	s_nop 0
	global_load_lds_dwordx4 v[172:173], off
	s_barrier
	s_waitcnt lgkmcnt(0)
	s_setprio 1
	s_waitcnt lgkmcnt(0)
	v_mfma_f32_16x16x32_bf16 v[50:53], v[200:203], v[144:147], v[50:53]
	v_mfma_f32_16x16x32_bf16 v[38:41], v[192:195], v[136:139], v[38:41]
	v_mfma_f32_16x16x32_bf16 v[42:45], v[200:203], v[136:139], v[42:45]
	v_mfma_f32_16x16x32_bf16 v[136:139], v[204:207], v[148:151], v[50:53]
	v_mfma_f32_16x16x32_bf16 v[50:53], v[192:195], v[184:187], v[54:57]
	v_mfma_f32_16x16x32_bf16 v[34:37], v[200:203], v[122:125], v[34:37]
	v_mfma_f32_16x16x32_bf16 v[38:41], v[196:199], v[140:143], v[38:41]
	v_mfma_f32_16x16x32_bf16 v[42:45], v[204:207], v[140:143], v[42:45]
	v_mfma_f32_16x16x32_bf16 v[46:49], v[192:195], v[144:147], v[46:49]
	v_mfma_f32_16x16x32_bf16 v[140:143], v[196:199], v[188:191], v[50:53]
	v_mfma_f32_16x16x32_bf16 v[50:53], v[200:203], v[184:187], v[58:61]
	v_mfma_f32_16x16x32_bf16 v[114:117], v[192:195], v[122:125], v[114:117]
	v_mfma_f32_16x16x32_bf16 v[34:37], v[204:207], v[126:129], v[34:37]
	v_mfma_f32_16x16x32_bf16 v[46:49], v[196:199], v[148:151], v[46:49]
	v_mfma_f32_16x16x32_bf16 v[144:147], v[204:207], v[188:191], v[50:53]
	v_mfma_f32_16x16x32_bf16 v[208:211], v[196:199], v[126:129], v[114:117]
	s_setprio 0
	s_mov_b32 m0, s23
	v_lshl_add_u64 v[240:241], s[34:35], 0, v[130:131]
	s_barrier
	ds_read_b128 v[50:53], v174 offset:16384
	ds_read_b128 v[54:57], v174 offset:17408
	ds_read_b128 v[58:61], v174 offset:18432
	ds_read_b128 v[114:117], v174 offset:19456
	ds_read_b128 v[122:125], v174 offset:20480
	ds_read_b128 v[126:129], v174 offset:21504
	ds_read_b128 v[148:151], v174 offset:22528
	ds_read_b128 v[184:187], v174 offset:23552
	global_load_lds_dwordx4 v[240:241], off
	v_lshl_add_u64 v[242:243], s[34:35], 0, v[132:133]
	s_mov_b32 m0, s25
	s_nop 0
	global_load_lds_dwordx4 v[242:243], off
	s_barrier
	s_waitcnt lgkmcnt(0)
	s_setprio 1
	s_waitcnt lgkmcnt(0)
	v_mfma_f32_16x16x32_bf16 v[152:155], v[102:105], v[50:53], v[152:155]
	v_mfma_f32_16x16x32_bf16 v[156:159], v[110:113], v[50:53], v[156:159]
	v_mfma_f32_16x16x32_bf16 v[160:163], v[102:105], v[58:61], v[160:163]
	v_mfma_f32_16x16x32_bf16 v[164:167], v[110:113], v[58:61], v[164:167]
	v_mfma_f32_16x16x32_bf16 v[10:13], v[102:105], v[148:151], v[10:13]
	v_mfma_f32_16x16x32_bf16 v[14:17], v[110:113], v[148:151], v[14:17]
	v_mfma_f32_16x16x32_bf16 v[152:155], v[106:109], v[54:57], v[152:155]
	v_mfma_f32_16x16x32_bf16 v[156:159], v[118:121], v[54:57], v[156:159]
	v_mfma_f32_16x16x32_bf16 v[160:163], v[106:109], v[114:117], v[160:163]
	v_mfma_f32_16x16x32_bf16 v[164:167], v[118:121], v[114:117], v[164:167]
	v_mfma_f32_16x16x32_bf16 v[176:179], v[102:105], v[122:125], v[176:179]
	v_mfma_f32_16x16x32_bf16 v[180:183], v[110:113], v[122:125], v[180:183]
	v_mfma_f32_16x16x32_bf16 v[10:13], v[106:109], v[184:187], v[10:13]
	v_mfma_f32_16x16x32_bf16 v[14:17], v[118:121], v[184:187], v[14:17]
	v_mfma_f32_16x16x32_bf16 v[176:179], v[106:109], v[126:129], v[176:179]
	v_mfma_f32_16x16x32_bf16 v[180:183], v[118:121], v[126:129], v[180:183]
	s_setprio 0
	s_barrier
	s_add_u32 s26, s30, 0x10000
	s_addc_u32 s27, s31, 0
	s_mov_b32 m0, s51
	v_lshl_add_u64 v[102:103], s[26:27], 0, v[0:1]
	global_load_lds_dwordx4 v[102:103], off
	v_lshl_add_u64 v[102:103], s[26:27], 0, v[134:135]
	s_mov_b32 m0, s48
	s_nop 0
	global_load_lds_dwordx4 v[102:103], off
	s_waitcnt vmcnt(6)
	s_barrier
	s_setprio 1
	v_mfma_f32_16x16x32_bf16 v[26:29], v[192:195], v[58:61], v[26:29]
	v_mfma_f32_16x16x32_bf16 v[188:191], v[196:199], v[114:117], v[26:29]
	v_mfma_f32_16x16x32_bf16 v[26:29], v[200:203], v[58:61], v[30:33]
	v_mfma_f32_16x16x32_bf16 v[18:21], v[192:195], v[50:53], v[18:21]
	v_mfma_f32_16x16x32_bf16 v[22:25], v[200:203], v[50:53], v[22:25]
	v_mfma_f32_16x16x32_bf16 v[212:215], v[204:207], v[114:117], v[26:29]
	v_mfma_f32_16x16x32_bf16 v[26:29], v[192:195], v[122:125], v[62:65]
	v_mfma_f32_16x16x32_bf16 v[2:5], v[192:195], v[148:151], v[2:5]
	v_mfma_f32_16x16x32_bf16 v[6:9], v[200:203], v[148:151], v[6:9]
	v_mfma_f32_16x16x32_bf16 v[18:21], v[196:199], v[54:57], v[18:21]
	v_mfma_f32_16x16x32_bf16 v[22:25], v[204:207], v[54:57], v[22:25]
	v_mfma_f32_16x16x32_bf16 v[62:65], v[196:199], v[126:129], v[26:29]
	v_mfma_f32_16x16x32_bf16 v[26:29], v[200:203], v[122:125], v[98:101]
	v_mfma_f32_16x16x32_bf16 v[2:5], v[196:199], v[184:187], v[2:5]
	v_mfma_f32_16x16x32_bf16 v[6:9], v[204:207], v[184:187], v[6:9]
	v_mfma_f32_16x16x32_bf16 v[216:219], v[204:207], v[126:129], v[26:29]
	s_setprio 0
	s_barrier
; #define PG8_STAGE(bufoff, gbase, voff) do { _Pragma("unroll") for (int _i = 0; _i < 2; ++_i) \
;         __builtin_amdgcn_global_load_lds((const __attribute__((address_space(1))) unsigned*)((const char*)(gbase) + (voff)[_i]), (LAS unsigned*)(lds + (bufoff) + ldsw + _i * 8192), 16, 0, 0); } while (0)
; #define PG8_LDA(dst, b, h) do { _Pragma("unroll") for (int m = 0; m < 4; ++m) _Pragma("unroll") for (int k = 0; k < 2; ++k) dst[m][k] = *(const LAS bf16x8*)(lds + PG8_SA(b, h) + aoff + m * 2048 + k * 1024); } while (0)
; #define PG8_LDB(dst, b, h) do { _Pragma("unroll") for (int n = 0; n < 2; ++n) _Pragma("unroll") for (int k = 0; k < 2; ++k) dst[n][k] = *(const LAS bf16x8*)(lds + PG8_SB(b, h) + boff + n * 2048 + k * 1024); } while (0)
; #define PG8_MMA(ai, bj, At, Bt) do { __builtin_amdgcn_s_setprio(1); _Pragma("unroll") for (int m = 0; m < 4; ++m) _Pragma("unroll") for (int n = 0; n < 2; ++n) _Pragma("unroll") for (int k = 0; k < 2; ++k) \
;         acc[ai][bj][m][n] = __builtin_amdgcn_mfma_f32_16x16x32_bf16(Bt[n][k], At[m][k], acc[ai][bj][m][n], 0, 0, 0); __builtin_amdgcn_s_setprio(0); } while (0)
; #define PG8_WAIT_V(n) asm volatile("s_waitcnt vmcnt(" #n ")" ::: "memory")
; #define PG8_WAIT_L(n) asm volatile("s_waitcnt lgkmcnt(" #n ")" ::: "memory")
; #define PG8_BAR __builtin_amdgcn_s_barrier()
; #define PG8_SCHED __builtin_amdgcn_sched_barrier(0)
; template <class Epi>
; __device__ __forceinline__ void gemm_phase(LAS unsigned char* lds, const Gemm g, const StaticOrder& S_in, const Epi& E, int sw) {
;     ...
;             PG8_LDB(B0, 1, 0); PG8_SCHED; PG8_LDA(At, 1, 0); PG8_STAGE(PG8_SA(0, 1), a2 + hstepA, voffA);
;             PG8_WAIT_L(8); PG8_BAR; PG8_WAIT_L(0); PG8_MMA(0, 0, At, B0); PG8_BAR; PG8_SCHED;
;             PG8_LDB(B1, 1, 1); PG8_STAGE(PG8_SB(1, 0), b3, voffB);
;             PG8_BAR; PG8_WAIT_L(0); PG8_MMA(0, 1, At, B1); PG8_BAR;
;             PG8_LDA(At, 1, 1); PG8_STAGE(PG8_SA(1, 0), a3, voffA);
;             PG8_BAR; PG8_WAIT_L(0); PG8_MMA(1, 0, At, B0); PG8_BAR; PG8_SCHED;
;             PG8_STAGE(PG8_SB(1, 1), b3 + hstepB, voffB);
;             PG8_WAIT_V(6); PG8_BAR; PG8_MMA(1, 1, At, B1); PG8_BAR;
	s_nop 2
	ds_read_b128 v[26:29], v220
	ds_read_b128 v[30:33], v220 offset:1024
	ds_read_b128 v[148:151], v220 offset:2048
	ds_read_b128 v[184:187], v220 offset:3072
	s_add_u32 s26, s34, 0x80000
	s_addc_u32 s27, s35, 0
	s_mov_b32 m0, s43
	v_lshl_add_u64 v[58:59], s[26:27], 0, v[130:131]
	ds_read_b128 v[50:53], v174 offset:32768
	ds_read_b128 v[54:57], v174 offset:33792
	ds_read_b128 v[98:101], v174 offset:34816
	ds_read_b128 v[102:105], v174 offset:35840
	ds_read_b128 v[110:113], v174 offset:36864
	ds_read_b128 v[192:195], v174 offset:37888
	ds_read_b128 v[196:199], v174 offset:38912
	ds_read_b128 v[200:203], v174 offset:39936
	global_load_lds_dwordx4 v[58:59], off
	v_lshl_add_u64 v[58:59], s[26:27], 0, v[132:133]
	s_mov_b32 m0, s44
	s_nop 0
	global_load_lds_dwordx4 v[58:59], off
	s_waitcnt lgkmcnt(8)
	s_barrier
	s_waitcnt lgkmcnt(0)
	s_setprio 1
	s_waitcnt lgkmcnt(0)
	v_mfma_f32_16x16x32_bf16 v[58:61], v[26:29], v[50:53], v[66:69]
	v_mfma_f32_16x16x32_bf16 v[204:207], v[30:33], v[54:57], v[58:61]
	v_mfma_f32_16x16x32_bf16 v[58:61], v[148:151], v[50:53], v[70:73]
	v_mfma_f32_16x16x32_bf16 v[220:223], v[184:187], v[54:57], v[58:61]
	v_mfma_f32_16x16x32_bf16 v[58:61], v[26:29], v[98:101], v[74:77]
	v_mfma_f32_16x16x32_bf16 v[224:227], v[30:33], v[102:105], v[58:61]
	v_mfma_f32_16x16x32_bf16 v[58:61], v[148:151], v[98:101], v[78:81]
	v_mfma_f32_16x16x32_bf16 v[126:129], v[184:187], v[102:105], v[58:61]
	v_mfma_f32_16x16x32_bf16 v[58:61], v[26:29], v[110:113], v[82:85]
	v_mfma_f32_16x16x32_bf16 v[122:125], v[30:33], v[192:195], v[58:61]
	v_mfma_f32_16x16x32_bf16 v[58:61], v[148:151], v[110:113], v[86:89]
	v_mfma_f32_16x16x32_bf16 v[118:121], v[184:187], v[192:195], v[58:61]
	v_mfma_f32_16x16x32_bf16 v[58:61], v[26:29], v[196:199], v[90:93]
	v_mfma_f32_16x16x32_bf16 v[114:117], v[30:33], v[200:203], v[58:61]
	v_mfma_f32_16x16x32_bf16 v[58:61], v[148:151], v[196:199], v[94:97]
	v_mfma_f32_16x16x32_bf16 v[106:109], v[184:187], v[200:203], v[58:61]
	s_setprio 0
	s_barrier
	s_mov_b32 m0, s53
	s_nop 3
	v_lshl_add_u64 v[58:59], v[168:169], 0, s[86:87]
	ds_read_b128 v[78:81], v232
	ds_read_b128 v[82:85], v232 offset:1024
	ds_read_b128 v[228:231], v232 offset:2048
	ds_read_b128 v[232:235], v232 offset:3072
	global_load_lds_dwordx4 v[58:59], off
	v_lshl_add_u64 v[58:59], v[172:173], 0, s[86:87]
	s_mov_b32 m0, s52
	s_nop 0
	global_load_lds_dwordx4 v[58:59], off
	s_barrier
	s_waitcnt lgkmcnt(0)
	s_setprio 1
	s_waitcnt lgkmcnt(0)
	v_mfma_f32_16x16x32_bf16 v[34:37], v[228:231], v[50:53], v[34:37]
	v_mfma_f32_16x16x32_bf16 v[66:69], v[232:235], v[54:57], v[34:37]
	v_mfma_f32_16x16x32_bf16 v[34:37], v[78:81], v[98:101], v[38:41]
	v_mfma_f32_16x16x32_bf16 v[58:61], v[78:81], v[50:53], v[208:211]
	v_mfma_f32_16x16x32_bf16 v[50:53], v[82:85], v[102:105], v[34:37]
	v_mfma_f32_16x16x32_bf16 v[34:37], v[228:231], v[98:101], v[42:45]
	v_mfma_f32_16x16x32_bf16 v[58:61], v[82:85], v[54:57], v[58:61]
	v_mfma_f32_16x16x32_bf16 v[54:57], v[232:235], v[102:105], v[34:37]
	v_mfma_f32_16x16x32_bf16 v[34:37], v[78:81], v[110:113], v[46:49]
	v_mfma_f32_16x16x32_bf16 v[42:45], v[82:85], v[192:195], v[34:37]
	v_mfma_f32_16x16x32_bf16 v[34:37], v[228:231], v[110:113], v[136:139]
	v_mfma_f32_16x16x32_bf16 v[46:49], v[232:235], v[192:195], v[34:37]
	v_mfma_f32_16x16x32_bf16 v[34:37], v[78:81], v[196:199], v[140:143]
	v_mfma_f32_16x16x32_bf16 v[38:41], v[228:231], v[196:199], v[144:147]
	v_mfma_f32_16x16x32_bf16 v[34:37], v[82:85], v[200:203], v[34:37]
	v_mfma_f32_16x16x32_bf16 v[38:41], v[232:235], v[200:203], v[38:41]
	s_setprio 0
	s_mov_b32 m0, s45
	v_lshl_add_u64 v[70:71], v[240:241], 0, s[86:87]
	s_barrier
	ds_read_b128 v[136:139], v174 offset:49152
	ds_read_b128 v[140:143], v174 offset:50176
	ds_read_b128 v[144:147], v174 offset:51200
	ds_read_b128 v[192:195], v174 offset:52224
	ds_read_b128 v[196:199], v174 offset:53248
	ds_read_b128 v[200:203], v174 offset:54272
	ds_read_b128 v[208:211], v174 offset:55296
	ds_read_b128 v[236:239], v174 offset:56320
	global_load_lds_dwordx4 v[70:71], off
	v_lshl_add_u64 v[70:71], v[242:243], 0, s[86:87]
	s_mov_b32 m0, s46
	s_nop 0
	global_load_lds_dwordx4 v[70:71], off
	s_barrier
	s_waitcnt lgkmcnt(0)
	s_setprio 1
	s_waitcnt lgkmcnt(0)
	v_mfma_f32_16x16x32_bf16 v[70:73], v[26:29], v[136:139], v[152:155]
	v_mfma_f32_16x16x32_bf16 v[110:113], v[30:33], v[140:143], v[70:73]
	v_mfma_f32_16x16x32_bf16 v[70:73], v[148:151], v[136:139], v[156:159]
	v_mfma_f32_16x16x32_bf16 v[102:105], v[184:187], v[140:143], v[70:73]
	v_mfma_f32_16x16x32_bf16 v[70:73], v[26:29], v[144:147], v[160:163]
	v_mfma_f32_16x16x32_bf16 v[98:101], v[30:33], v[192:195], v[70:73]
	v_mfma_f32_16x16x32_bf16 v[70:73], v[148:151], v[144:147], v[164:167]
	v_mfma_f32_16x16x32_bf16 v[94:97], v[184:187], v[192:195], v[70:73]
	v_mfma_f32_16x16x32_bf16 v[70:73], v[26:29], v[196:199], v[176:179]
	v_mfma_f32_16x16x32_bf16 v[10:13], v[26:29], v[208:211], v[10:13]
	v_mfma_f32_16x16x32_bf16 v[90:93], v[30:33], v[200:203], v[70:73]
	v_mfma_f32_16x16x32_bf16 v[70:73], v[148:151], v[196:199], v[180:183]
	v_mfma_f32_16x16x32_bf16 v[74:77], v[30:33], v[236:239], v[10:13]
	v_mfma_f32_16x16x32_bf16 v[10:13], v[148:151], v[208:211], v[14:17]
	v_mfma_f32_16x16x32_bf16 v[86:89], v[184:187], v[200:203], v[70:73]
	v_mfma_f32_16x16x32_bf16 v[70:73], v[184:187], v[236:239], v[10:13]
	s_setprio 0
	s_barrier
	s_add_u32 s26, s30, 0x10080
	s_addc_u32 s27, s31, 0
	s_mov_b32 m0, s29
	s_nop 0
	v_lshl_add_u64 v[10:11], s[26:27], 0, v[0:1]
	global_load_lds_dwordx4 v[10:11], off
	v_lshl_add_u64 v[10:11], s[26:27], 0, v[134:135]
	s_mov_b32 m0, s28
	s_nop 0
	global_load_lds_dwordx4 v[10:11], off
	s_waitcnt vmcnt(6)
	s_barrier
; #define LAS __attribute__((address_space(3)))
; __device__ __forceinline__ unsigned cvt_pk_bf16(float lo, float hi) { unsigned r; asm volatile("v_cvt_pk_bf16_f32 %0, %1, %2" : "=v"(r) : "v"(lo), "v"(hi)); return r; }
; __device__ __forceinline__ int ltid(int sw) { unsigned z = 0u; asm volatile("" : "+s"(sw), "+s"(z)); int t = sw * 64 + (int)__builtin_amdgcn_mbcnt_hi(~0u, __builtin_amdgcn_mbcnt_lo(~0u, z)); asm volatile("" : "+v"(t)); return t; }
; #define PG8_WAIT_V(n) asm volatile("s_waitcnt vmcnt(" #n ")" ::: "memory")
; #define PG8_BAR __builtin_amdgcn_s_barrier()
; template <class Epi>
; __device__ __forceinline__ void gemm_phase(LAS unsigned char* lds, const Gemm g, const StaticOrder& S_in, const Epi& E, int sw) {
;     ...
;             PG8_WAIT_V(6); PG8_BAR; PG8_MMA(1, 1, At, B1); PG8_BAR;
;     __device__ __forceinline__ void operator()(AccMut acc, const Unit& u, int sw) const {
;         const int tid_ = ltid(sw), lane_ = tid_ & 63, wr = sw >> 2, wc = sw & 3, fr = lane_ & 15, fq = lane_ >> 4;
;         const int row0 = u.pm * BM + wr * 64 + fr, c0 = u.pn * 128 + wc * 32 + 8 * fq;
;         u32x4 xnext = *(const u32x4*)(XC + (size_t)row0 * E + c0);
;         { f32x4 ns[2];
; #pragma unroll
;           for (int n = 0; n < 2; ++n) ns[n] = *(const LAS f32x4*)(nsp + c0 + 4 * n);
; #pragma unroll
;           for (int ai = 0; ai < 2; ++ai)
; #pragma unroll
;             for (int m = 0; m < 4; ++m) {
; #pragma unroll
;                 for (int n = 0; n < 2; ++n)
; #pragma unroll
;                     for (int jp = 0; jp < 2; ++jp) {
;                         const f32x2 z = (f32x2){acc[ai][0][m][n][2 * jp], acc[ai][0][m][n][2 * jp + 1]} * (-1.44269504f);
;                         f32x2 e; e.x = __builtin_amdgcn_exp2f(z.x); e.y = __builtin_amdgcn_exp2f(z.y); e = e + 1.0f;
;                         f32x2 r; r.x = __builtin_amdgcn_rcpf(e.x); r.y = __builtin_amdgcn_rcpf(e.y);
;                         r = r * (f32x2){ns[n][2 * jp], ns[n][2 * jp + 1]};
;                         acc[ai][0][m][n][2 * jp] = r.x; acc[ai][0][m][n][2 * jp + 1] = r.y; }
;                 const f32x4 l0 = acc[ai][0][m][0], l1 = acc[ai][0][m][1];
;                 u32x4 w; w.x = cvt_pk_bf16(l0[0], l0[1]); w.y = cvt_pk_bf16(l0[2], l0[3]); w.z = cvt_pk_bf16(l1[0], l1[1]); w.w = cvt_pk_bf16(l1[2], l1[3]);
;                 *(u32x4*)(LA + (size_t)(row0 + ai * HALF + m * 16) * E + c0) = w; } }
	s_setprio 1
	v_mfma_f32_16x16x32_bf16 v[10:13], v[78:81], v[136:139], v[18:21]
	v_mfma_f32_16x16x32_bf16 v[26:29], v[82:85], v[140:143], v[10:13]
	v_mfma_f32_16x16x32_bf16 v[10:13], v[228:231], v[136:139], v[22:25]
	v_mfma_f32_16x16x32_bf16 v[30:33], v[232:235], v[140:143], v[10:13]
	v_mfma_f32_16x16x32_bf16 v[10:13], v[78:81], v[144:147], v[188:191]
	v_mfma_f32_16x16x32_bf16 v[18:21], v[82:85], v[192:195], v[10:13]
	v_mfma_f32_16x16x32_bf16 v[10:13], v[228:231], v[144:147], v[212:215]
	v_mfma_f32_16x16x32_bf16 v[22:25], v[232:235], v[192:195], v[10:13]
	v_mfma_f32_16x16x32_bf16 v[10:13], v[78:81], v[196:199], v[62:65]
	v_mfma_f32_16x16x32_bf16 v[14:17], v[228:231], v[196:199], v[216:219]
	v_mfma_f32_16x16x32_bf16 v[2:5], v[78:81], v[208:211], v[2:5]
	v_mfma_f32_16x16x32_bf16 v[6:9], v[228:231], v[208:211], v[6:9]
	v_mfma_f32_16x16x32_bf16 v[10:13], v[82:85], v[200:203], v[10:13]
	v_mfma_f32_16x16x32_bf16 v[14:17], v[232:235], v[200:203], v[14:17]
	v_mfma_f32_16x16x32_bf16 v[2:5], v[82:85], v[236:239], v[2:5]
	v_mfma_f32_16x16x32_bf16 v[6:9], v[232:235], v[236:239], v[6:9]
	s_setprio 0
	s_barrier
	s_load_dwordx2 s[26:27], s[92:93], 0xa8
	v_mbcnt_lo_u32_b32 v216, -1, 0
	v_mbcnt_hi_u32_b32 v216, -1, v216
	v_mov_b32_e32 v237, 0x20000
	ds_read_b32 v239, v237 offset:48
	ds_read_b32 v237, v237 offset:40
	s_lshl_b32 s13, s24, 8
	s_add_i32 s13, s13, s3
	s_lshl_b32 s17, s22, 7
	s_or_b32 s17, s17, s85
	v_and_b32_e32 v217, 15, v216
	v_lshrrev_b32_e32 v218, 1, v216
	v_and_b32_e32 v218, 24, v218
	v_lshl_or_b32 v217, v217, 2, s13
	v_or_b32_e32 v219, s17, v218
	v_lshlrev_b32_e32 v168, 12, v217
	v_lshlrev_b32_e32 v240, 2, v219
	v_lshl_add_u32 v168, v219, 1, v168
	v_add_u32_e32 v240, 0x24400, v240
	global_load_dwordx4 v[136:139], v168, s[6:7]
	ds_read_b128 v[228:231], v240
	ds_read_b128 v[232:235], v240 offset:16
	v_add_u32_e32 v169, 0x1000, v168
	global_load_dwordx4 v[140:143], v169, s[6:7]
	v_add_u32_e32 v172, 0x2000, v168
	global_load_dwordx4 v[144:147], v172, s[6:7]
	v_add_u32_e32 v173, 0x3000, v168
	global_load_dwordx4 v[148:151], v173, s[6:7]
	v_add_u32_e32 v176, 0x80000, v168
	global_load_dwordx4 v[152:155], v176, s[6:7]
	v_add_u32_e32 v177, 0x81000, v168
	global_load_dwordx4 v[156:159], v177, s[6:7]
	v_add_u32_e32 v178, 0x82000, v168
	global_load_dwordx4 v[160:163], v178, s[6:7]
	v_add_u32_e32 v179, 0x83000, v168
	global_load_dwordx4 v[164:167], v179, s[6:7]
	s_lshl_b32 s17, s24, 2
	s_lshr_b32 s13, s3, 6
	s_add_i32 s17, s17, s13
	s_mov_b32 s24, 0xbe888889
	s_mov_b32 s22, 0xbfaaaaab
	s_mov_b32 s13, 0xbe000000
	v_mov_b32_e32 v236, 0xbf2aaaab
	v_mov_b32_e32 v238, 0
	s_waitcnt lgkmcnt(0)
	v_cmp_ne_u32_e32 vcc, 0, v239
	v_lshlrev_b32_e32 v237, 6, v237
	s_nop 0
	v_cndmask_b32_e32 v237, 0, v237, vcc
	v_add_u32_e32 v237, s17, v237
	v_lshl_add_u32 v237, v237, 11, v219
	v_lshlrev_b32_e32 v237, 2, v237
	v_add_u32_e32 v239, 0x800000, v237
	v_pk_mul_f32 v[180:181], v[204:205], s[74:75] op_sel_hi:[1,0]
	v_pk_mul_f32 v[182:183], v[206:207], s[74:75] op_sel_hi:[1,0]
	v_pk_mul_f32 v[184:185], v[220:221], s[74:75] op_sel_hi:[1,0]
	v_pk_mul_f32 v[186:187], v[222:223], s[74:75] op_sel_hi:[1,0]
	v_exp_f32_e32 v180, v180
	v_exp_f32_e32 v181, v181
	v_exp_f32_e32 v182, v182
	v_exp_f32_e32 v183, v183
	v_exp_f32_e32 v184, v184
	v_exp_f32_e32 v185, v185
	v_exp_f32_e32 v186, v186
	v_exp_f32_e32 v187, v187
	v_pk_add_f32 v[180:181], v[180:181], 1.0 op_sel_hi:[1,0]
	v_pk_add_f32 v[182:183], v[182:183], 1.0 op_sel_hi:[1,0]
	v_pk_add_f32 v[184:185], v[184:185], 1.0 op_sel_hi:[1,0]
	v_pk_add_f32 v[186:187], v[186:187], 1.0 op_sel_hi:[1,0]
	v_rcp_f32_e32 v180, v180
	v_rcp_f32_e32 v181, v181
	v_rcp_f32_e32 v182, v182
	v_rcp_f32_e32 v183, v183
	v_rcp_f32_e32 v184, v184
	v_rcp_f32_e32 v185, v185
	v_rcp_f32_e32 v186, v186
	v_rcp_f32_e32 v187, v187
	v_pk_mul_f32 v[204:205], v[180:181], v[228:229]
	v_pk_mul_f32 v[206:207], v[182:183], v[230:231]
	v_pk_mul_f32 v[220:221], v[184:185], v[232:233]
	v_pk_mul_f32 v[222:223], v[186:187], v[234:235]
	v_min3_f32 v238, v238, v204, v205
	v_min3_f32 v238, v238, v206, v207
	v_min3_f32 v238, v238, v220, v221
	v_min3_f32 v238, v238, v222, v223
	v_cvt_pk_bf16_f32 v208, v204, v205
	v_cvt_pk_bf16_f32 v209, v206, v207
	v_cvt_pk_bf16_f32 v210, v220, v221
	v_cvt_pk_bf16_f32 v211, v222, v223
	global_store_dwordx4 v168, v[208:211], s[8:9] nt
	v_pk_mul_f32 v[180:181], v[224:225], s[74:75] op_sel_hi:[1,0]
	v_pk_mul_f32 v[182:183], v[226:227], s[74:75] op_sel_hi:[1,0]
	v_pk_mul_f32 v[184:185], v[126:127], s[74:75] op_sel_hi:[1,0]
	v_pk_mul_f32 v[186:187], v[128:129], s[74:75] op_sel_hi:[1,0]
	v_exp_f32_e32 v180, v180
	v_exp_f32_e32 v181, v181
	v_exp_f32_e32 v182, v182
	v_exp_f32_e32 v183, v183
	v_exp_f32_e32 v184, v184
	v_exp_f32_e32 v185, v185
	v_exp_f32_e32 v186, v186
	v_exp_f32_e32 v187, v187
	v_pk_add_f32 v[180:181], v[180:181], 1.0 op_sel_hi:[1,0]
	v_pk_add_f32 v[182:183], v[182:183], 1.0 op_sel_hi:[1,0]
	v_pk_add_f32 v[184:185], v[184:185], 1.0 op_sel_hi:[1,0]
	v_pk_add_f32 v[186:187], v[186:187], 1.0 op_sel_hi:[1,0]
	v_rcp_f32_e32 v180, v180
	v_rcp_f32_e32 v181, v181
	v_rcp_f32_e32 v182, v182
	v_rcp_f32_e32 v183, v183
	v_rcp_f32_e32 v184, v184
	v_rcp_f32_e32 v185, v185
	v_rcp_f32_e32 v186, v186
	v_rcp_f32_e32 v187, v187
	v_pk_mul_f32 v[224:225], v[180:181], v[228:229]
	v_pk_mul_f32 v[226:227], v[182:183], v[230:231]
	v_pk_mul_f32 v[126:127], v[184:185], v[232:233]
	v_pk_mul_f32 v[128:129], v[186:187], v[234:235]
	v_min3_f32 v238, v238, v224, v225
	v_min3_f32 v238, v238, v226, v227
	v_min3_f32 v238, v238, v126, v127
	v_min3_f32 v238, v238, v128, v129
	v_cvt_pk_bf16_f32 v212, v224, v225
	v_cvt_pk_bf16_f32 v213, v226, v227
	v_cvt_pk_bf16_f32 v214, v126, v127
; __device__ __forceinline__ unsigned cvt_pk_bf16(float lo, float hi) { unsigned r; asm volatile("v_cvt_pk_bf16_f32 %0, %1, %2" : "=v"(r) : "v"(lo), "v"(hi)); return r; }
;     __device__ __forceinline__ void operator()(AccMut acc, const Unit& u, int sw) const {
;     ...
;           for (int ai = 0; ai < 2; ++ai)
; #pragma unroll
;             for (int m = 0; m < 4; ++m) {
; #pragma unroll
;                 for (int n = 0; n < 2; ++n)
; #pragma unroll
;                     for (int jp = 0; jp < 2; ++jp) {
;                         const f32x2 z = (f32x2){acc[ai][0][m][n][2 * jp], acc[ai][0][m][n][2 * jp + 1]} * (-1.44269504f);
;                         f32x2 e; e.x = __builtin_amdgcn_exp2f(z.x); e.y = __builtin_amdgcn_exp2f(z.y); e = e + 1.0f;
;                         f32x2 r; r.x = __builtin_amdgcn_rcpf(e.x); r.y = __builtin_amdgcn_rcpf(e.y);
;                         r = r * (f32x2){ns[n][2 * jp], ns[n][2 * jp + 1]};
;                         acc[ai][0][m][n][2 * jp] = r.x; acc[ai][0][m][n][2 * jp + 1] = r.y; }
;                 const f32x4 l0 = acc[ai][0][m][0], l1 = acc[ai][0][m][1];
;                 u32x4 w; w.x = cvt_pk_bf16(l0[0], l0[1]); w.y = cvt_pk_bf16(l0[2], l0[3]); w.z = cvt_pk_bf16(l1[0], l1[1]); w.w = cvt_pk_bf16(l1[2], l1[3]);
;                 *(u32x4*)(LA + (size_t)(row0 + ai * HALF + m * 16) * E + c0) = w; } }
	v_cvt_pk_bf16_f32 v215, v128, v129
	global_store_dwordx4 v169, v[212:215], s[8:9] nt
	v_pk_mul_f32 v[180:181], v[122:123], s[74:75] op_sel_hi:[1,0]
	v_pk_mul_f32 v[182:183], v[124:125], s[74:75] op_sel_hi:[1,0]
	v_pk_mul_f32 v[184:185], v[118:119], s[74:75] op_sel_hi:[1,0]
	v_pk_mul_f32 v[186:187], v[120:121], s[74:75] op_sel_hi:[1,0]
	v_exp_f32_e32 v180, v180
	v_exp_f32_e32 v181, v181
	v_exp_f32_e32 v182, v182
	v_exp_f32_e32 v183, v183
	v_exp_f32_e32 v184, v184
	v_exp_f32_e32 v185, v185
	v_exp_f32_e32 v186, v186
	v_exp_f32_e32 v187, v187
	v_pk_add_f32 v[180:181], v[180:181], 1.0 op_sel_hi:[1,0]
	v_pk_add_f32 v[182:183], v[182:183], 1.0 op_sel_hi:[1,0]
	v_pk_add_f32 v[184:185], v[184:185], 1.0 op_sel_hi:[1,0]
	v_pk_add_f32 v[186:187], v[186:187], 1.0 op_sel_hi:[1,0]
	v_rcp_f32_e32 v180, v180
	v_rcp_f32_e32 v181, v181
	v_rcp_f32_e32 v182, v182
	v_rcp_f32_e32 v183, v183
	v_rcp_f32_e32 v184, v184
	v_rcp_f32_e32 v185, v185
	v_rcp_f32_e32 v186, v186
	v_rcp_f32_e32 v187, v187
	v_pk_mul_f32 v[122:123], v[180:181], v[228:229]
	v_pk_mul_f32 v[124:125], v[182:183], v[230:231]
	v_pk_mul_f32 v[118:119], v[184:185], v[232:233]
	v_pk_mul_f32 v[120:121], v[186:187], v[234:235]
	v_min3_f32 v238, v238, v122, v123
	v_min3_f32 v238, v238, v124, v125
	v_min3_f32 v238, v238, v118, v119
	v_min3_f32 v238, v238, v120, v121
	v_cvt_pk_bf16_f32 v208, v122, v123
	v_cvt_pk_bf16_f32 v209, v124, v125
	v_cvt_pk_bf16_f32 v210, v118, v119
	v_cvt_pk_bf16_f32 v211, v120, v121
	global_store_dwordx4 v172, v[208:211], s[8:9] nt
	v_pk_mul_f32 v[180:181], v[114:115], s[74:75] op_sel_hi:[1,0]
	v_pk_mul_f32 v[182:183], v[116:117], s[74:75] op_sel_hi:[1,0]
	v_pk_mul_f32 v[184:185], v[106:107], s[74:75] op_sel_hi:[1,0]
	v_pk_mul_f32 v[186:187], v[108:109], s[74:75] op_sel_hi:[1,0]
	v_exp_f32_e32 v180, v180
	v_exp_f32_e32 v181, v181
	v_exp_f32_e32 v182, v182
	v_exp_f32_e32 v183, v183
	v_exp_f32_e32 v184, v184
	v_exp_f32_e32 v185, v185
	v_exp_f32_e32 v186, v186
	v_exp_f32_e32 v187, v187
	v_pk_add_f32 v[180:181], v[180:181], 1.0 op_sel_hi:[1,0]
	v_pk_add_f32 v[182:183], v[182:183], 1.0 op_sel_hi:[1,0]
	v_pk_add_f32 v[184:185], v[184:185], 1.0 op_sel_hi:[1,0]
	v_pk_add_f32 v[186:187], v[186:187], 1.0 op_sel_hi:[1,0]
	v_rcp_f32_e32 v180, v180
	v_rcp_f32_e32 v181, v181
	v_rcp_f32_e32 v182, v182
	v_rcp_f32_e32 v183, v183
	v_rcp_f32_e32 v184, v184
	v_rcp_f32_e32 v185, v185
	v_rcp_f32_e32 v186, v186
	v_rcp_f32_e32 v187, v187
	v_pk_mul_f32 v[114:115], v[180:181], v[228:229]
	v_pk_mul_f32 v[116:117], v[182:183], v[230:231]
	v_pk_mul_f32 v[106:107], v[184:185], v[232:233]
	v_pk_mul_f32 v[108:109], v[186:187], v[234:235]
	v_min3_f32 v238, v238, v114, v115
	v_min3_f32 v238, v238, v116, v117
	v_min3_f32 v238, v238, v106, v107
	v_min3_f32 v238, v238, v108, v109
	v_cvt_pk_bf16_f32 v212, v114, v115
	v_cvt_pk_bf16_f32 v213, v116, v117
	v_cvt_pk_bf16_f32 v214, v106, v107
	v_cvt_pk_bf16_f32 v215, v108, v109
	global_store_dwordx4 v173, v[212:215], s[8:9] nt
	v_pk_mul_f32 v[180:181], v[110:111], s[74:75] op_sel_hi:[1,0]
	v_pk_mul_f32 v[182:183], v[112:113], s[74:75] op_sel_hi:[1,0]
	v_pk_mul_f32 v[184:185], v[102:103], s[74:75] op_sel_hi:[1,0]
	v_pk_mul_f32 v[186:187], v[104:105], s[74:75] op_sel_hi:[1,0]
	v_exp_f32_e32 v180, v180
	v_exp_f32_e32 v181, v181
	v_exp_f32_e32 v182, v182
	v_exp_f32_e32 v183, v183
	v_exp_f32_e32 v184, v184
	v_exp_f32_e32 v185, v185
	v_exp_f32_e32 v186, v186
	v_exp_f32_e32 v187, v187
	v_pk_add_f32 v[180:181], v[180:181], 1.0 op_sel_hi:[1,0]
	v_pk_add_f32 v[182:183], v[182:183], 1.0 op_sel_hi:[1,0]
	v_pk_add_f32 v[184:185], v[184:185], 1.0 op_sel_hi:[1,0]
	v_pk_add_f32 v[186:187], v[186:187], 1.0 op_sel_hi:[1,0]
	v_rcp_f32_e32 v180, v180
	v_rcp_f32_e32 v181, v181
	v_rcp_f32_e32 v182, v182
	v_rcp_f32_e32 v183, v183
	v_rcp_f32_e32 v184, v184
	v_rcp_f32_e32 v185, v185
	v_rcp_f32_e32 v186, v186
	v_rcp_f32_e32 v187, v187
	v_pk_mul_f32 v[110:111], v[180:181], v[228:229]
	v_pk_mul_f32 v[112:113], v[182:183], v[230:231]
	v_pk_mul_f32 v[102:103], v[184:185], v[232:233]
	v_pk_mul_f32 v[104:105], v[186:187], v[234:235]
	v_min3_f32 v238, v238, v110, v111
	v_min3_f32 v238, v238, v112, v113
	v_min3_f32 v238, v238, v102, v103
	v_min3_f32 v238, v238, v104, v105
	v_cvt_pk_bf16_f32 v208, v110, v111
	v_cvt_pk_bf16_f32 v209, v112, v113
	v_cvt_pk_bf16_f32 v210, v102, v103
	v_cvt_pk_bf16_f32 v211, v104, v105
	global_store_dwordx4 v176, v[208:211], s[8:9] nt
	v_pk_mul_f32 v[180:181], v[98:99], s[74:75] op_sel_hi:[1,0]
	v_pk_mul_f32 v[182:183], v[100:101], s[74:75] op_sel_hi:[1,0]
	v_pk_mul_f32 v[184:185], v[94:95], s[74:75] op_sel_hi:[1,0]
	v_pk_mul_f32 v[186:187], v[96:97], s[74:75] op_sel_hi:[1,0]
	v_exp_f32_e32 v180, v180
	v_exp_f32_e32 v181, v181
	v_exp_f32_e32 v182, v182
	v_exp_f32_e32 v183, v183
	v_exp_f32_e32 v184, v184
	v_exp_f32_e32 v185, v185
	v_exp_f32_e32 v186, v186
	v_exp_f32_e32 v187, v187
	v_pk_add_f32 v[180:181], v[180:181], 1.0 op_sel_hi:[1,0]
	v_pk_add_f32 v[182:183], v[182:183], 1.0 op_sel_hi:[1,0]
	v_pk_add_f32 v[184:185], v[184:185], 1.0 op_sel_hi:[1,0]
	v_pk_add_f32 v[186:187], v[186:187], 1.0 op_sel_hi:[1,0]
	v_rcp_f32_e32 v180, v180
	v_rcp_f32_e32 v181, v181
	v_rcp_f32_e32 v182, v182
	v_rcp_f32_e32 v183, v183
	v_rcp_f32_e32 v184, v184
	v_rcp_f32_e32 v185, v185
	v_rcp_f32_e32 v186, v186
	v_rcp_f32_e32 v187, v187
	v_pk_mul_f32 v[98:99], v[180:181], v[228:229]
	v_pk_mul_f32 v[100:101], v[182:183], v[230:231]
	v_pk_mul_f32 v[94:95], v[184:185], v[232:233]
	v_pk_mul_f32 v[96:97], v[186:187], v[234:235]
	v_min3_f32 v238, v238, v98, v99
	v_min3_f32 v238, v238, v100, v101
	v_min3_f32 v238, v238, v94, v95
	v_min3_f32 v238, v238, v96, v97
	v_cvt_pk_bf16_f32 v212, v98, v99
; __device__ __forceinline__ unsigned cvt_pk_bf16(float lo, float hi) { unsigned r; asm volatile("v_cvt_pk_bf16_f32 %0, %1, %2" : "=v"(r) : "v"(lo), "v"(hi)); return r; }
;     __device__ __forceinline__ void operator()(AccMut acc, const Unit& u, int sw) const {
;     ...
;                         const f32x2 z = (f32x2){acc[ai][0][m][n][2 * jp], acc[ai][0][m][n][2 * jp + 1]} * (-1.44269504f);
;                         f32x2 e; e.x = __builtin_amdgcn_exp2f(z.x); e.y = __builtin_amdgcn_exp2f(z.y); e = e + 1.0f;
;                         f32x2 r; r.x = __builtin_amdgcn_rcpf(e.x); r.y = __builtin_amdgcn_rcpf(e.y);
;                         r = r * (f32x2){ns[n][2 * jp], ns[n][2 * jp + 1]};
;                         acc[ai][0][m][n][2 * jp] = r.x; acc[ai][0][m][n][2 * jp + 1] = r.y; }
;                 const f32x4 l0 = acc[ai][0][m][0], l1 = acc[ai][0][m][1];
;                 u32x4 w; w.x = cvt_pk_bf16(l0[0], l0[1]); w.y = cvt_pk_bf16(l0[2], l0[3]); w.z = cvt_pk_bf16(l1[0], l1[1]); w.w = cvt_pk_bf16(l1[2], l1[3]);
;                 *(u32x4*)(LA + (size_t)(row0 + ai * HALF + m * 16) * E + c0) = w; } }
;     ...
;                         const f32x2 z = (f32x2){acc[ai][1][m][n][2 * jp], acc[ai][1][m][n][2 * jp + 1]} * (-1.44269504f);
;                         f32x2 e; e.x = __builtin_amdgcn_exp2f(z.x); e.y = __builtin_amdgcn_exp2f(z.y); e = e + 1.0f;
;                         f32x2 ig; ig.x = __builtin_amdgcn_rcpf(e.x); ig.y = __builtin_amdgcn_rcpf(e.y);
;                         const f32x2 x2 = (f32x2){acc[ai][0][m][n][2 * jp], acc[ai][0][m][n][2 * jp + 1]} * 2.0f;
;                         f32x2 ser = x2 * (1.0f / 120.0f) + (1.0f / 24.0f); ser = ser * x2 + (1.0f / 6.0f); ser = ser * x2 + 0.5f; ser = ser * x2 + 1.0f; ser = ser * (-x2);
;                         f32x2 em = ser;
;                         if (__builtin_expect(__builtin_amdgcn_ballot_w64(x2.x <= -0.25f || x2.y <= -0.25f) != 0ull, 0)) {
;                             em.x = (x2.x > -0.25f) ? ser.x : (1.0f - fexp(x2.x)); em.y = (x2.y > -0.25f) ? ser.y : (1.0f - fexp(x2.y)); }
;                         const unsigned wv = xw[2 * n + jp];
;                         f32x2 sq; sq.x = __builtin_amdgcn_sqrtf(em.x); sq.y = __builtin_amdgcn_sqrtf(em.y);
;                         const f32x2 b2 = sq * ig * (f32x2){bf_lo(wv), bf_hi(wv)};
;                         bt[4 * n + 2 * jp] = b2.x; bt[4 * n + 2 * jp + 1] = b2.y; }
	v_cvt_pk_bf16_f32 v213, v100, v101
	v_cvt_pk_bf16_f32 v214, v94, v95
	v_cvt_pk_bf16_f32 v215, v96, v97
	global_store_dwordx4 v177, v[212:215], s[8:9] nt
	v_pk_mul_f32 v[180:181], v[90:91], s[74:75] op_sel_hi:[1,0]
	v_pk_mul_f32 v[182:183], v[92:93], s[74:75] op_sel_hi:[1,0]
	v_pk_mul_f32 v[184:185], v[86:87], s[74:75] op_sel_hi:[1,0]
	v_pk_mul_f32 v[186:187], v[88:89], s[74:75] op_sel_hi:[1,0]
	v_exp_f32_e32 v180, v180
	v_exp_f32_e32 v181, v181
	v_exp_f32_e32 v182, v182
	v_exp_f32_e32 v183, v183
	v_exp_f32_e32 v184, v184
	v_exp_f32_e32 v185, v185
	v_exp_f32_e32 v186, v186
	v_exp_f32_e32 v187, v187
	v_pk_add_f32 v[180:181], v[180:181], 1.0 op_sel_hi:[1,0]
	v_pk_add_f32 v[182:183], v[182:183], 1.0 op_sel_hi:[1,0]
	v_pk_add_f32 v[184:185], v[184:185], 1.0 op_sel_hi:[1,0]
	v_pk_add_f32 v[186:187], v[186:187], 1.0 op_sel_hi:[1,0]
	v_rcp_f32_e32 v180, v180
	v_rcp_f32_e32 v181, v181
	v_rcp_f32_e32 v182, v182
	v_rcp_f32_e32 v183, v183
	v_rcp_f32_e32 v184, v184
	v_rcp_f32_e32 v185, v185
	v_rcp_f32_e32 v186, v186
	v_rcp_f32_e32 v187, v187
	v_pk_mul_f32 v[90:91], v[180:181], v[228:229]
	v_pk_mul_f32 v[92:93], v[182:183], v[230:231]
	v_pk_mul_f32 v[86:87], v[184:185], v[232:233]
	v_pk_mul_f32 v[88:89], v[186:187], v[234:235]
	v_min3_f32 v238, v238, v90, v91
	v_min3_f32 v238, v238, v92, v93
	v_min3_f32 v238, v238, v86, v87
	v_min3_f32 v238, v238, v88, v89
	v_cvt_pk_bf16_f32 v208, v90, v91
	v_cvt_pk_bf16_f32 v209, v92, v93
	v_cvt_pk_bf16_f32 v210, v86, v87
	v_cvt_pk_bf16_f32 v211, v88, v89
	global_store_dwordx4 v178, v[208:211], s[8:9] nt
	v_pk_mul_f32 v[180:181], v[74:75], s[74:75] op_sel_hi:[1,0]
	v_pk_mul_f32 v[182:183], v[76:77], s[74:75] op_sel_hi:[1,0]
	v_pk_mul_f32 v[184:185], v[70:71], s[74:75] op_sel_hi:[1,0]
	v_pk_mul_f32 v[186:187], v[72:73], s[74:75] op_sel_hi:[1,0]
	v_exp_f32_e32 v180, v180
	v_exp_f32_e32 v181, v181
	v_exp_f32_e32 v182, v182
	v_exp_f32_e32 v183, v183
	v_exp_f32_e32 v184, v184
	v_exp_f32_e32 v185, v185
	v_exp_f32_e32 v186, v186
	v_exp_f32_e32 v187, v187
	v_pk_add_f32 v[180:181], v[180:181], 1.0 op_sel_hi:[1,0]
	v_pk_add_f32 v[182:183], v[182:183], 1.0 op_sel_hi:[1,0]
	v_pk_add_f32 v[184:185], v[184:185], 1.0 op_sel_hi:[1,0]
	v_pk_add_f32 v[186:187], v[186:187], 1.0 op_sel_hi:[1,0]
	v_rcp_f32_e32 v180, v180
	v_rcp_f32_e32 v181, v181
	v_rcp_f32_e32 v182, v182
	v_rcp_f32_e32 v183, v183
	v_rcp_f32_e32 v184, v184
	v_rcp_f32_e32 v185, v185
	v_rcp_f32_e32 v186, v186
	v_rcp_f32_e32 v187, v187
	v_pk_mul_f32 v[74:75], v[180:181], v[228:229]
	v_pk_mul_f32 v[76:77], v[182:183], v[230:231]
	v_pk_mul_f32 v[70:71], v[184:185], v[232:233]
	v_pk_mul_f32 v[72:73], v[186:187], v[234:235]
	v_min3_f32 v238, v238, v74, v75
	v_min3_f32 v238, v238, v76, v77
	v_min3_f32 v238, v238, v70, v71
	v_min3_f32 v238, v238, v72, v73
	v_cvt_pk_bf16_f32 v212, v74, v75
	v_cvt_pk_bf16_f32 v213, v76, v77
	v_cvt_pk_bf16_f32 v214, v70, v71
	v_cvt_pk_bf16_f32 v215, v72, v73
	global_store_dwordx4 v179, v[212:215], s[8:9] nt
	v_cmp_ge_f32_e32 vcc, s13, v238
	s_nop 4
	s_cbranch_vccnz .Lgate_epi_general
	v_pk_mul_f32 v[180:181], v[58:59], s[74:75] op_sel_hi:[1,0]
	v_pk_mul_f32 v[182:183], v[60:61], s[74:75] op_sel_hi:[1,0]
	v_pk_mul_f32 v[184:185], v[66:67], s[74:75] op_sel_hi:[1,0]
	v_pk_mul_f32 v[186:187], v[68:69], s[74:75] op_sel_hi:[1,0]
	v_exp_f32_e32 v180, v180
	v_exp_f32_e32 v181, v181
	v_exp_f32_e32 v182, v182
	v_exp_f32_e32 v183, v183
	v_exp_f32_e32 v184, v184
	v_exp_f32_e32 v185, v185
	v_exp_f32_e32 v186, v186
	v_exp_f32_e32 v187, v187
	v_pk_fma_f32 v[188:189], v[204:205], s[24:25], v[236:237] op_sel_hi:[1,0,0]
	v_pk_fma_f32 v[190:191], v[206:207], s[24:25], v[236:237] op_sel_hi:[1,0,0]
	v_pk_fma_f32 v[192:193], v[220:221], s[24:25], v[236:237] op_sel_hi:[1,0,0]
	v_pk_fma_f32 v[194:195], v[222:223], s[24:25], v[236:237] op_sel_hi:[1,0,0]
	v_pk_add_f32 v[180:181], v[180:181], 1.0 op_sel_hi:[1,0]
	v_pk_add_f32 v[182:183], v[182:183], 1.0 op_sel_hi:[1,0]
	v_pk_add_f32 v[184:185], v[184:185], 1.0 op_sel_hi:[1,0]
	v_pk_add_f32 v[186:187], v[186:187], 1.0 op_sel_hi:[1,0]
	v_rcp_f32_e32 v180, v180
	v_rcp_f32_e32 v181, v181
	v_rcp_f32_e32 v182, v182
	v_rcp_f32_e32 v183, v183
	v_rcp_f32_e32 v184, v184
	v_rcp_f32_e32 v185, v185
	v_rcp_f32_e32 v186, v186
	v_rcp_f32_e32 v187, v187
	v_pk_fma_f32 v[188:189], v[204:205], v[188:189], s[22:23] op_sel_hi:[1,1,0]
	v_pk_fma_f32 v[190:191], v[206:207], v[190:191], s[22:23] op_sel_hi:[1,1,0]
	v_pk_fma_f32 v[192:193], v[220:221], v[192:193], s[22:23] op_sel_hi:[1,1,0]
	v_pk_fma_f32 v[194:195], v[222:223], v[194:195], s[22:23] op_sel_hi:[1,1,0]
	v_pk_fma_f32 v[188:189], v[204:205], v[188:189], -2.0 op_sel_hi:[1,1,0]
	v_pk_fma_f32 v[190:191], v[206:207], v[190:191], -2.0 op_sel_hi:[1,1,0]
	v_pk_fma_f32 v[192:193], v[220:221], v[192:193], -2.0 op_sel_hi:[1,1,0]
	v_pk_fma_f32 v[194:195], v[222:223], v[194:195], -2.0 op_sel_hi:[1,1,0]
	v_pk_fma_f32 v[188:189], v[204:205], v[188:189], -2.0 op_sel_hi:[1,1,0]
	v_pk_fma_f32 v[190:191], v[206:207], v[190:191], -2.0 op_sel_hi:[1,1,0]
	v_pk_fma_f32 v[192:193], v[220:221], v[192:193], -2.0 op_sel_hi:[1,1,0]
	v_pk_fma_f32 v[194:195], v[222:223], v[194:195], -2.0 op_sel_hi:[1,1,0]
	v_pk_mul_f32 v[188:189], v[204:205], v[188:189]
	v_pk_mul_f32 v[190:191], v[206:207], v[190:191]
	v_pk_mul_f32 v[192:193], v[220:221], v[192:193]
	v_pk_mul_f32 v[194:195], v[222:223], v[194:195]
	v_pk_mul_f32 v[228:229], v[204:205], s[74:75] op_sel_hi:[1,0] neg_lo:[0,1] neg_hi:[0,1]
	v_pk_mul_f32 v[230:231], v[206:207], s[74:75] op_sel_hi:[1,0] neg_lo:[0,1] neg_hi:[0,1]
	v_pk_mul_f32 v[232:233], v[220:221], s[74:75] op_sel_hi:[1,0] neg_lo:[0,1] neg_hi:[0,1]
	v_pk_mul_f32 v[234:235], v[222:223], s[74:75] op_sel_hi:[1,0] neg_lo:[0,1] neg_hi:[0,1]
	v_sqrt_f32_e32 v188, v188
	v_sqrt_f32_e32 v189, v189
	v_sqrt_f32_e32 v190, v190
	v_sqrt_f32_e32 v191, v191
	v_sqrt_f32_e32 v192, v192
	v_sqrt_f32_e32 v193, v193
	v_sqrt_f32_e32 v194, v194
	v_sqrt_f32_e32 v195, v195
	v_exp_f32_e32 v58, v228
	v_exp_f32_e32 v59, v229
	v_exp_f32_e32 v60, v230
	v_exp_f32_e32 v61, v231
	v_exp_f32_e32 v66, v232
	v_exp_f32_e32 v67, v233
	v_exp_f32_e32 v68, v234
	v_exp_f32_e32 v69, v235
	s_waitcnt vmcnt(15)
; __device__ __forceinline__ unsigned cvt_pk_bf16(float lo, float hi) { unsigned r; asm volatile("v_cvt_pk_bf16_f32 %0, %1, %2" : "=v"(r) : "v"(lo), "v"(hi)); return r; }
; __device__ __forceinline__ float bf_lo(unsigned w) { return __uint_as_float(w << 16); }
;     __device__ __forceinline__ void operator()(AccMut acc, const Unit& u, int sw) const {
;     ...
;             for (int m = 0; m < 4; ++m) { const size_t off = (size_t)(row0 + ai * HALF + m * 16) * E + c0;
;                 const u32x4 xw = xnext;
;                 if (ai * 4 + m < 7) { const int ai2 = (ai * 4 + m + 1) >> 2, m2 = (ai * 4 + m + 1) & 3; xnext = *(const u32x4*)(XC + (size_t)(row0 + ai2 * HALF + m2 * 16) * E + c0); }
;                 float bt[8];
; #pragma unroll
;                 for (int n = 0; n < 2; ++n)
; #pragma unroll
;                     for (int jp = 0; jp < 2; ++jp) {
;                         const f32x2 z = (f32x2){acc[ai][1][m][n][2 * jp], acc[ai][1][m][n][2 * jp + 1]} * (-1.44269504f);
;                         f32x2 e; e.x = __builtin_amdgcn_exp2f(z.x); e.y = __builtin_amdgcn_exp2f(z.y); e = e + 1.0f;
;                         f32x2 ig; ig.x = __builtin_amdgcn_rcpf(e.x); ig.y = __builtin_amdgcn_rcpf(e.y);
;                         const f32x2 x2 = (f32x2){acc[ai][0][m][n][2 * jp], acc[ai][0][m][n][2 * jp + 1]} * 2.0f;
;                         f32x2 ser = x2 * (1.0f / 120.0f) + (1.0f / 24.0f); ser = ser * x2 + (1.0f / 6.0f); ser = ser * x2 + 0.5f; ser = ser * x2 + 1.0f; ser = ser * (-x2);
;                         f32x2 em = ser;
;                         if (__builtin_expect(__builtin_amdgcn_ballot_w64(x2.x <= -0.25f || x2.y <= -0.25f) != 0ull, 0)) {
;                             em.x = (x2.x > -0.25f) ? ser.x : (1.0f - fexp(x2.x)); em.y = (x2.y > -0.25f) ? ser.y : (1.0f - fexp(x2.y)); }
;                         const unsigned wv = xw[2 * n + jp];
;                         f32x2 sq; sq.x = __builtin_amdgcn_sqrtf(em.x); sq.y = __builtin_amdgcn_sqrtf(em.y);
;                         const f32x2 b2 = sq * ig * (f32x2){bf_lo(wv), bf_hi(wv)};
;                         bt[4 * n + 2 * jp] = b2.x; bt[4 * n + 2 * jp + 1] = b2.y; }
;                 u32x4 w; w.x = cvt_pk_bf16(bt[0], bt[1]); w.y = cvt_pk_bf16(bt[2], bt[3]); w.z = cvt_pk_bf16(bt[4], bt[5]); w.w = cvt_pk_bf16(bt[6], bt[7]);
;                 *(u32x4*)(BT + off) = w; }
	v_lshlrev_b32_e32 v196, 16, v136
	v_and_b32_e32 v197, 0xffff0000, v136
	v_lshlrev_b32_e32 v198, 16, v137
	v_and_b32_e32 v199, 0xffff0000, v137
	v_lshlrev_b32_e32 v200, 16, v138
	v_and_b32_e32 v201, 0xffff0000, v138
	v_lshlrev_b32_e32 v202, 16, v139
	v_and_b32_e32 v203, 0xffff0000, v139
	v_pk_mul_f32 v[188:189], v[188:189], v[180:181]
	v_pk_mul_f32 v[190:191], v[190:191], v[182:183]
	v_pk_mul_f32 v[192:193], v[192:193], v[184:185]
	v_pk_mul_f32 v[194:195], v[194:195], v[186:187]
	v_pk_mul_f32 v[216:217], v[188:189], v[196:197]
	v_pk_mul_f32 v[218:219], v[190:191], v[198:199]
	v_pk_mul_f32 v[240:241], v[192:193], v[200:201]
	v_pk_mul_f32 v[242:243], v[194:195], v[202:203]
	v_cvt_pk_bf16_f32 v208, v216, v217
	v_cvt_pk_bf16_f32 v209, v218, v219
	v_cvt_pk_bf16_f32 v210, v240, v241
	v_cvt_pk_bf16_f32 v211, v242, v243
	global_store_dwordx4 v168, v[208:211], s[10:11] nt
	v_pk_mul_f32 v[180:181], v[50:51], s[74:75] op_sel_hi:[1,0]
	v_pk_mul_f32 v[182:183], v[52:53], s[74:75] op_sel_hi:[1,0]
	v_pk_mul_f32 v[184:185], v[54:55], s[74:75] op_sel_hi:[1,0]
	v_pk_mul_f32 v[186:187], v[56:57], s[74:75] op_sel_hi:[1,0]
	v_exp_f32_e32 v180, v180
	v_exp_f32_e32 v181, v181
	v_exp_f32_e32 v182, v182
	v_exp_f32_e32 v183, v183
	v_exp_f32_e32 v184, v184
	v_exp_f32_e32 v185, v185
	v_exp_f32_e32 v186, v186
	v_exp_f32_e32 v187, v187
	v_pk_fma_f32 v[188:189], v[224:225], s[24:25], v[236:237] op_sel_hi:[1,0,0]
	v_pk_fma_f32 v[190:191], v[226:227], s[24:25], v[236:237] op_sel_hi:[1,0,0]
	v_pk_fma_f32 v[192:193], v[126:127], s[24:25], v[236:237] op_sel_hi:[1,0,0]
	v_pk_fma_f32 v[194:195], v[128:129], s[24:25], v[236:237] op_sel_hi:[1,0,0]
	v_pk_add_f32 v[180:181], v[180:181], 1.0 op_sel_hi:[1,0]
	v_pk_add_f32 v[182:183], v[182:183], 1.0 op_sel_hi:[1,0]
	v_pk_add_f32 v[184:185], v[184:185], 1.0 op_sel_hi:[1,0]
	v_pk_add_f32 v[186:187], v[186:187], 1.0 op_sel_hi:[1,0]
	v_rcp_f32_e32 v180, v180
	v_rcp_f32_e32 v181, v181
	v_rcp_f32_e32 v182, v182
	v_rcp_f32_e32 v183, v183
	v_rcp_f32_e32 v184, v184
	v_rcp_f32_e32 v185, v185
	v_rcp_f32_e32 v186, v186
	v_rcp_f32_e32 v187, v187
	v_pk_fma_f32 v[188:189], v[224:225], v[188:189], s[22:23] op_sel_hi:[1,1,0]
	v_pk_fma_f32 v[190:191], v[226:227], v[190:191], s[22:23] op_sel_hi:[1,1,0]
	v_pk_fma_f32 v[192:193], v[126:127], v[192:193], s[22:23] op_sel_hi:[1,1,0]
	v_pk_fma_f32 v[194:195], v[128:129], v[194:195], s[22:23] op_sel_hi:[1,1,0]
	v_pk_fma_f32 v[188:189], v[224:225], v[188:189], -2.0 op_sel_hi:[1,1,0]
	v_pk_fma_f32 v[190:191], v[226:227], v[190:191], -2.0 op_sel_hi:[1,1,0]
	v_pk_fma_f32 v[192:193], v[126:127], v[192:193], -2.0 op_sel_hi:[1,1,0]
	v_pk_fma_f32 v[194:195], v[128:129], v[194:195], -2.0 op_sel_hi:[1,1,0]
	v_pk_fma_f32 v[188:189], v[224:225], v[188:189], -2.0 op_sel_hi:[1,1,0]
	v_pk_fma_f32 v[190:191], v[226:227], v[190:191], -2.0 op_sel_hi:[1,1,0]
	v_pk_fma_f32 v[192:193], v[126:127], v[192:193], -2.0 op_sel_hi:[1,1,0]
	v_pk_fma_f32 v[194:195], v[128:129], v[194:195], -2.0 op_sel_hi:[1,1,0]
	v_pk_mul_f32 v[188:189], v[224:225], v[188:189]
	v_pk_mul_f32 v[190:191], v[226:227], v[190:191]
	v_pk_mul_f32 v[192:193], v[126:127], v[192:193]
	v_pk_mul_f32 v[194:195], v[128:129], v[194:195]
	v_pk_mul_f32 v[228:229], v[224:225], s[74:75] op_sel_hi:[1,0] neg_lo:[0,1] neg_hi:[0,1]
	v_pk_mul_f32 v[230:231], v[226:227], s[74:75] op_sel_hi:[1,0] neg_lo:[0,1] neg_hi:[0,1]
	v_pk_mul_f32 v[232:233], v[126:127], s[74:75] op_sel_hi:[1,0] neg_lo:[0,1] neg_hi:[0,1]
	v_pk_mul_f32 v[234:235], v[128:129], s[74:75] op_sel_hi:[1,0] neg_lo:[0,1] neg_hi:[0,1]
	v_sqrt_f32_e32 v188, v188
	v_sqrt_f32_e32 v189, v189
	v_sqrt_f32_e32 v190, v190
	v_sqrt_f32_e32 v191, v191
	v_sqrt_f32_e32 v192, v192
	v_sqrt_f32_e32 v193, v193
	v_sqrt_f32_e32 v194, v194
	v_sqrt_f32_e32 v195, v195
	v_exp_f32_e32 v228, v228
	v_exp_f32_e32 v229, v229
	v_exp_f32_e32 v230, v230
	v_exp_f32_e32 v231, v231
	v_exp_f32_e32 v232, v232
	v_exp_f32_e32 v233, v233
	v_exp_f32_e32 v234, v234
	v_exp_f32_e32 v235, v235
	s_waitcnt vmcnt(15)
	v_lshlrev_b32_e32 v196, 16, v140
	v_and_b32_e32 v197, 0xffff0000, v140
	v_lshlrev_b32_e32 v198, 16, v141
	v_and_b32_e32 v199, 0xffff0000, v141
	v_lshlrev_b32_e32 v200, 16, v142
	v_and_b32_e32 v201, 0xffff0000, v142
	v_lshlrev_b32_e32 v202, 16, v143
	v_and_b32_e32 v203, 0xffff0000, v143
	v_pk_mul_f32 v[188:189], v[188:189], v[180:181]
	v_pk_mul_f32 v[190:191], v[190:191], v[182:183]
	v_pk_mul_f32 v[192:193], v[192:193], v[184:185]
	v_pk_mul_f32 v[194:195], v[194:195], v[186:187]
	v_pk_mul_f32 v[188:189], v[188:189], v[196:197]
	v_pk_mul_f32 v[190:191], v[190:191], v[198:199]
	v_pk_mul_f32 v[192:193], v[192:193], v[200:201]
	v_pk_mul_f32 v[194:195], v[194:195], v[202:203]
	v_cvt_pk_bf16_f32 v212, v188, v189
	v_cvt_pk_bf16_f32 v213, v190, v191
	v_cvt_pk_bf16_f32 v214, v192, v193
	v_cvt_pk_bf16_f32 v215, v194, v195
	global_store_dwordx4 v169, v[212:215], s[10:11] nt
	v_pk_fma_f32 v[216:217], v[228:229], v[216:217], v[188:189]
	v_pk_fma_f32 v[218:219], v[230:231], v[218:219], v[190:191]
	v_pk_fma_f32 v[240:241], v[232:233], v[240:241], v[192:193]
	v_pk_fma_f32 v[242:243], v[234:235], v[242:243], v[194:195]
	v_pk_mul_f32 v[58:59], v[58:59], v[228:229]
	v_pk_mul_f32 v[60:61], v[60:61], v[230:231]
	v_pk_mul_f32 v[66:67], v[66:67], v[232:233]
	v_pk_mul_f32 v[68:69], v[68:69], v[234:235]
	v_pk_add_f32 v[204:205], v[204:205], v[224:225]
	v_pk_add_f32 v[206:207], v[206:207], v[226:227]
	v_pk_add_f32 v[220:221], v[220:221], v[126:127]
	v_pk_add_f32 v[222:223], v[222:223], v[128:129]
	v_pk_mul_f32 v[180:181], v[42:43], s[74:75] op_sel_hi:[1,0]
	v_pk_mul_f32 v[182:183], v[44:45], s[74:75] op_sel_hi:[1,0]
	v_pk_mul_f32 v[184:185], v[46:47], s[74:75] op_sel_hi:[1,0]
; __device__ __forceinline__ unsigned cvt_pk_bf16(float lo, float hi) { unsigned r; asm volatile("v_cvt_pk_bf16_f32 %0, %1, %2" : "=v"(r) : "v"(lo), "v"(hi)); return r; }
; __device__ __forceinline__ float bf_lo(unsigned w) { return __uint_as_float(w << 16); }
;     __device__ __forceinline__ void operator()(AccMut acc, const Unit& u, int sw) const {
;     ...
;             for (int m = 0; m < 4; ++m) { const size_t off = (size_t)(row0 + ai * HALF + m * 16) * E + c0;
;                 const u32x4 xw = xnext;
;                 if (ai * 4 + m < 7) { const int ai2 = (ai * 4 + m + 1) >> 2, m2 = (ai * 4 + m + 1) & 3; xnext = *(const u32x4*)(XC + (size_t)(row0 + ai2 * HALF + m2 * 16) * E + c0); }
;                 float bt[8];
; #pragma unroll
;                 for (int n = 0; n < 2; ++n)
; #pragma unroll
;                     for (int jp = 0; jp < 2; ++jp) {
;                         const f32x2 z = (f32x2){acc[ai][1][m][n][2 * jp], acc[ai][1][m][n][2 * jp + 1]} * (-1.44269504f);
;                         f32x2 e; e.x = __builtin_amdgcn_exp2f(z.x); e.y = __builtin_amdgcn_exp2f(z.y); e = e + 1.0f;
;                         f32x2 ig; ig.x = __builtin_amdgcn_rcpf(e.x); ig.y = __builtin_amdgcn_rcpf(e.y);
;                         const f32x2 x2 = (f32x2){acc[ai][0][m][n][2 * jp], acc[ai][0][m][n][2 * jp + 1]} * 2.0f;
;                         f32x2 ser = x2 * (1.0f / 120.0f) + (1.0f / 24.0f); ser = ser * x2 + (1.0f / 6.0f); ser = ser * x2 + 0.5f; ser = ser * x2 + 1.0f; ser = ser * (-x2);
;                         f32x2 em = ser;
;                         if (__builtin_expect(__builtin_amdgcn_ballot_w64(x2.x <= -0.25f || x2.y <= -0.25f) != 0ull, 0)) {
;                             em.x = (x2.x > -0.25f) ? ser.x : (1.0f - fexp(x2.x)); em.y = (x2.y > -0.25f) ? ser.y : (1.0f - fexp(x2.y)); }
;                         const unsigned wv = xw[2 * n + jp];
;                         f32x2 sq; sq.x = __builtin_amdgcn_sqrtf(em.x); sq.y = __builtin_amdgcn_sqrtf(em.y);
;                         const f32x2 b2 = sq * ig * (f32x2){bf_lo(wv), bf_hi(wv)};
;                         bt[4 * n + 2 * jp] = b2.x; bt[4 * n + 2 * jp + 1] = b2.y; }
;                 u32x4 w; w.x = cvt_pk_bf16(bt[0], bt[1]); w.y = cvt_pk_bf16(bt[2], bt[3]); w.z = cvt_pk_bf16(bt[4], bt[5]); w.w = cvt_pk_bf16(bt[6], bt[7]);
;                 *(u32x4*)(BT + off) = w; }
	v_pk_mul_f32 v[186:187], v[48:49], s[74:75] op_sel_hi:[1,0]
	v_exp_f32_e32 v180, v180
	v_exp_f32_e32 v181, v181
	v_exp_f32_e32 v182, v182
	v_exp_f32_e32 v183, v183
	v_exp_f32_e32 v184, v184
	v_exp_f32_e32 v185, v185
	v_exp_f32_e32 v186, v186
	v_exp_f32_e32 v187, v187
	v_pk_fma_f32 v[188:189], v[122:123], s[24:25], v[236:237] op_sel_hi:[1,0,0]
	v_pk_fma_f32 v[190:191], v[124:125], s[24:25], v[236:237] op_sel_hi:[1,0,0]
	v_pk_fma_f32 v[192:193], v[118:119], s[24:25], v[236:237] op_sel_hi:[1,0,0]
	v_pk_fma_f32 v[194:195], v[120:121], s[24:25], v[236:237] op_sel_hi:[1,0,0]
	v_pk_add_f32 v[180:181], v[180:181], 1.0 op_sel_hi:[1,0]
	v_pk_add_f32 v[182:183], v[182:183], 1.0 op_sel_hi:[1,0]
	v_pk_add_f32 v[184:185], v[184:185], 1.0 op_sel_hi:[1,0]
	v_pk_add_f32 v[186:187], v[186:187], 1.0 op_sel_hi:[1,0]
	v_rcp_f32_e32 v180, v180
	v_rcp_f32_e32 v181, v181
	v_rcp_f32_e32 v182, v182
	v_rcp_f32_e32 v183, v183
	v_rcp_f32_e32 v184, v184
	v_rcp_f32_e32 v185, v185
	v_rcp_f32_e32 v186, v186
	v_rcp_f32_e32 v187, v187
	v_pk_fma_f32 v[188:189], v[122:123], v[188:189], s[22:23] op_sel_hi:[1,1,0]
	v_pk_fma_f32 v[190:191], v[124:125], v[190:191], s[22:23] op_sel_hi:[1,1,0]
	v_pk_fma_f32 v[192:193], v[118:119], v[192:193], s[22:23] op_sel_hi:[1,1,0]
	v_pk_fma_f32 v[194:195], v[120:121], v[194:195], s[22:23] op_sel_hi:[1,1,0]
	v_pk_fma_f32 v[188:189], v[122:123], v[188:189], -2.0 op_sel_hi:[1,1,0]
	v_pk_fma_f32 v[190:191], v[124:125], v[190:191], -2.0 op_sel_hi:[1,1,0]
	v_pk_fma_f32 v[192:193], v[118:119], v[192:193], -2.0 op_sel_hi:[1,1,0]
	v_pk_fma_f32 v[194:195], v[120:121], v[194:195], -2.0 op_sel_hi:[1,1,0]
	v_pk_fma_f32 v[188:189], v[122:123], v[188:189], -2.0 op_sel_hi:[1,1,0]
	v_pk_fma_f32 v[190:191], v[124:125], v[190:191], -2.0 op_sel_hi:[1,1,0]
	v_pk_fma_f32 v[192:193], v[118:119], v[192:193], -2.0 op_sel_hi:[1,1,0]
	v_pk_fma_f32 v[194:195], v[120:121], v[194:195], -2.0 op_sel_hi:[1,1,0]
	v_pk_mul_f32 v[188:189], v[122:123], v[188:189]
	v_pk_mul_f32 v[190:191], v[124:125], v[190:191]
	v_pk_mul_f32 v[192:193], v[118:119], v[192:193]
	v_pk_mul_f32 v[194:195], v[120:121], v[194:195]
	v_pk_mul_f32 v[228:229], v[122:123], s[74:75] op_sel_hi:[1,0] neg_lo:[0,1] neg_hi:[0,1]
	v_pk_mul_f32 v[230:231], v[124:125], s[74:75] op_sel_hi:[1,0] neg_lo:[0,1] neg_hi:[0,1]
	v_pk_mul_f32 v[232:233], v[118:119], s[74:75] op_sel_hi:[1,0] neg_lo:[0,1] neg_hi:[0,1]
	v_pk_mul_f32 v[234:235], v[120:121], s[74:75] op_sel_hi:[1,0] neg_lo:[0,1] neg_hi:[0,1]
	v_sqrt_f32_e32 v188, v188
	v_sqrt_f32_e32 v189, v189
	v_sqrt_f32_e32 v190, v190
	v_sqrt_f32_e32 v191, v191
	v_sqrt_f32_e32 v192, v192
	v_sqrt_f32_e32 v193, v193
	v_sqrt_f32_e32 v194, v194
	v_sqrt_f32_e32 v195, v195
	v_exp_f32_e32 v228, v228
	v_exp_f32_e32 v229, v229
	v_exp_f32_e32 v230, v230
	v_exp_f32_e32 v231, v231
	v_exp_f32_e32 v232, v232
	v_exp_f32_e32 v233, v233
	v_exp_f32_e32 v234, v234
	v_exp_f32_e32 v235, v235
	s_waitcnt vmcnt(15)
	v_lshlrev_b32_e32 v196, 16, v144
	v_and_b32_e32 v197, 0xffff0000, v144
	v_lshlrev_b32_e32 v198, 16, v145
	v_and_b32_e32 v199, 0xffff0000, v145
	v_lshlrev_b32_e32 v200, 16, v146
	v_and_b32_e32 v201, 0xffff0000, v146
	v_lshlrev_b32_e32 v202, 16, v147
	v_and_b32_e32 v203, 0xffff0000, v147
	v_pk_mul_f32 v[188:189], v[188:189], v[180:181]
	v_pk_mul_f32 v[190:191], v[190:191], v[182:183]
	v_pk_mul_f32 v[192:193], v[192:193], v[184:185]
	v_pk_mul_f32 v[194:195], v[194:195], v[186:187]
	v_pk_mul_f32 v[188:189], v[188:189], v[196:197]
	v_pk_mul_f32 v[190:191], v[190:191], v[198:199]
	v_pk_mul_f32 v[192:193], v[192:193], v[200:201]
	v_pk_mul_f32 v[194:195], v[194:195], v[202:203]
	v_cvt_pk_bf16_f32 v208, v188, v189
	v_cvt_pk_bf16_f32 v209, v190, v191
	v_cvt_pk_bf16_f32 v210, v192, v193
	v_cvt_pk_bf16_f32 v211, v194, v195
	global_store_dwordx4 v172, v[208:211], s[10:11] nt
	v_pk_fma_f32 v[216:217], v[228:229], v[216:217], v[188:189]
	v_pk_fma_f32 v[218:219], v[230:231], v[218:219], v[190:191]
	v_pk_fma_f32 v[240:241], v[232:233], v[240:241], v[192:193]
	v_pk_fma_f32 v[242:243], v[234:235], v[242:243], v[194:195]
	v_pk_mul_f32 v[58:59], v[58:59], v[228:229]
	v_pk_mul_f32 v[60:61], v[60:61], v[230:231]
	v_pk_mul_f32 v[66:67], v[66:67], v[232:233]
	v_pk_mul_f32 v[68:69], v[68:69], v[234:235]
	v_pk_add_f32 v[204:205], v[204:205], v[122:123]
	v_pk_add_f32 v[206:207], v[206:207], v[124:125]
	v_pk_add_f32 v[220:221], v[220:221], v[118:119]
	v_pk_add_f32 v[222:223], v[222:223], v[120:121]
	v_pk_mul_f32 v[180:181], v[34:35], s[74:75] op_sel_hi:[1,0]
	v_pk_mul_f32 v[182:183], v[36:37], s[74:75] op_sel_hi:[1,0]
	v_pk_mul_f32 v[184:185], v[38:39], s[74:75] op_sel_hi:[1,0]
	v_pk_mul_f32 v[186:187], v[40:41], s[74:75] op_sel_hi:[1,0]
	v_exp_f32_e32 v180, v180
	v_exp_f32_e32 v181, v181
	v_exp_f32_e32 v182, v182
	v_exp_f32_e32 v183, v183
	v_exp_f32_e32 v184, v184
	v_exp_f32_e32 v185, v185
	v_exp_f32_e32 v186, v186
	v_exp_f32_e32 v187, v187
	v_pk_fma_f32 v[188:189], v[114:115], s[24:25], v[236:237] op_sel_hi:[1,0,0]
	v_pk_fma_f32 v[190:191], v[116:117], s[24:25], v[236:237] op_sel_hi:[1,0,0]
	v_pk_fma_f32 v[192:193], v[106:107], s[24:25], v[236:237] op_sel_hi:[1,0,0]
	v_pk_fma_f32 v[194:195], v[108:109], s[24:25], v[236:237] op_sel_hi:[1,0,0]
	v_pk_add_f32 v[180:181], v[180:181], 1.0 op_sel_hi:[1,0]
	v_pk_add_f32 v[182:183], v[182:183], 1.0 op_sel_hi:[1,0]
	v_pk_add_f32 v[184:185], v[184:185], 1.0 op_sel_hi:[1,0]
	v_pk_add_f32 v[186:187], v[186:187], 1.0 op_sel_hi:[1,0]
	v_rcp_f32_e32 v180, v180
	v_rcp_f32_e32 v181, v181
	v_rcp_f32_e32 v182, v182
	v_rcp_f32_e32 v183, v183
	v_rcp_f32_e32 v184, v184
	v_rcp_f32_e32 v185, v185
	v_rcp_f32_e32 v186, v186
	v_rcp_f32_e32 v187, v187
; __device__ __forceinline__ float bf_lo(unsigned w) { return __uint_as_float(w << 16); }
;     __device__ __forceinline__ void operator()(AccMut acc, const Unit& u, int sw) const {
;     ...
;                         const f32x2 z = (f32x2){acc[ai][1][m][n][2 * jp], acc[ai][1][m][n][2 * jp + 1]} * (-1.44269504f);
;                         f32x2 e; e.x = __builtin_amdgcn_exp2f(z.x); e.y = __builtin_amdgcn_exp2f(z.y); e = e + 1.0f;
;                         f32x2 ig; ig.x = __builtin_amdgcn_rcpf(e.x); ig.y = __builtin_amdgcn_rcpf(e.y);
;                         const f32x2 x2 = (f32x2){acc[ai][0][m][n][2 * jp], acc[ai][0][m][n][2 * jp + 1]} * 2.0f;
;                         f32x2 ser = x2 * (1.0f / 120.0f) + (1.0f / 24.0f); ser = ser * x2 + (1.0f / 6.0f); ser = ser * x2 + 0.5f; ser = ser * x2 + 1.0f; ser = ser * (-x2);
;                         f32x2 em = ser;
;                         if (__builtin_expect(__builtin_amdgcn_ballot_w64(x2.x <= -0.25f || x2.y <= -0.25f) != 0ull, 0)) {
;                             em.x = (x2.x > -0.25f) ? ser.x : (1.0f - fexp(x2.x)); em.y = (x2.y > -0.25f) ? ser.y : (1.0f - fexp(x2.y)); }
;                         const unsigned wv = xw[2 * n + jp];
;                         f32x2 sq; sq.x = __builtin_amdgcn_sqrtf(em.x); sq.y = __builtin_amdgcn_sqrtf(em.y);
;                         const f32x2 b2 = sq * ig * (f32x2){bf_lo(wv), bf_hi(wv)};
;                         bt[4 * n + 2 * jp] = b2.x; bt[4 * n + 2 * jp + 1] = b2.y; }
;                 u32x4 w; w.x = cvt_pk_bf16(bt[0], bt[1]); w.y = cvt_pk_bf16(bt[2], bt[3]); w.z = cvt_pk_bf16(bt[4], bt[5]); w.w = cvt_pk_bf16(bt[6], bt[7]);
;                 *(u32x4*)(BT + off) = w; }
; __device__ __forceinline__ void scan1_phase(const bf16_t* LA, const bf16_t* BT, int sw, View vw) {
;     ...
;             for (int i = 0; i < 8; ++i) {
;                 const float l0 = bf_lo(lw[i].x), l1 = bf_hi(lw[i].x), l2 = bf_lo(lw[i].y), l3 = bf_hi(lw[i].y);
;                 S[0] += l0; S[1] += l1; S[2] += l2; S[3] += l3;
;                 Hc[0] = fexp(l0) * Hc[0] + bf_lo(bw[i].x); Hc[1] = fexp(l1) * Hc[1] + bf_hi(bw[i].x); Hc[2] = fexp(l2) * Hc[2] + bf_lo(bw[i].y); Hc[3] = fexp(l3) * Hc[3] + bf_hi(bw[i].y); }
;         }
;         *(f32x4*)(CP + (size_t)bq * E + 4 * quad) = (f32x4){S[0], S[1], S[2], S[3]};
;         *(f32x4*)(CH + (size_t)bq * E + 4 * quad) = (f32x4){Hc[0], Hc[1], Hc[2], Hc[3]};
	v_pk_fma_f32 v[188:189], v[114:115], v[188:189], s[22:23] op_sel_hi:[1,1,0]
	v_pk_fma_f32 v[190:191], v[116:117], v[190:191], s[22:23] op_sel_hi:[1,1,0]
	v_pk_fma_f32 v[192:193], v[106:107], v[192:193], s[22:23] op_sel_hi:[1,1,0]
	v_pk_fma_f32 v[194:195], v[108:109], v[194:195], s[22:23] op_sel_hi:[1,1,0]
	v_pk_fma_f32 v[188:189], v[114:115], v[188:189], -2.0 op_sel_hi:[1,1,0]
	v_pk_fma_f32 v[190:191], v[116:117], v[190:191], -2.0 op_sel_hi:[1,1,0]
	v_pk_fma_f32 v[192:193], v[106:107], v[192:193], -2.0 op_sel_hi:[1,1,0]
	v_pk_fma_f32 v[194:195], v[108:109], v[194:195], -2.0 op_sel_hi:[1,1,0]
	v_pk_fma_f32 v[188:189], v[114:115], v[188:189], -2.0 op_sel_hi:[1,1,0]
	v_pk_fma_f32 v[190:191], v[116:117], v[190:191], -2.0 op_sel_hi:[1,1,0]
	v_pk_fma_f32 v[192:193], v[106:107], v[192:193], -2.0 op_sel_hi:[1,1,0]
	v_pk_fma_f32 v[194:195], v[108:109], v[194:195], -2.0 op_sel_hi:[1,1,0]
	v_pk_mul_f32 v[188:189], v[114:115], v[188:189]
	v_pk_mul_f32 v[190:191], v[116:117], v[190:191]
	v_pk_mul_f32 v[192:193], v[106:107], v[192:193]
	v_pk_mul_f32 v[194:195], v[108:109], v[194:195]
	v_pk_mul_f32 v[228:229], v[114:115], s[74:75] op_sel_hi:[1,0] neg_lo:[0,1] neg_hi:[0,1]
	v_pk_mul_f32 v[230:231], v[116:117], s[74:75] op_sel_hi:[1,0] neg_lo:[0,1] neg_hi:[0,1]
	v_pk_mul_f32 v[232:233], v[106:107], s[74:75] op_sel_hi:[1,0] neg_lo:[0,1] neg_hi:[0,1]
	v_pk_mul_f32 v[234:235], v[108:109], s[74:75] op_sel_hi:[1,0] neg_lo:[0,1] neg_hi:[0,1]
	v_sqrt_f32_e32 v188, v188
	v_sqrt_f32_e32 v189, v189
	v_sqrt_f32_e32 v190, v190
	v_sqrt_f32_e32 v191, v191
	v_sqrt_f32_e32 v192, v192
	v_sqrt_f32_e32 v193, v193
	v_sqrt_f32_e32 v194, v194
	v_sqrt_f32_e32 v195, v195
	v_exp_f32_e32 v228, v228
	v_exp_f32_e32 v229, v229
	v_exp_f32_e32 v230, v230
	v_exp_f32_e32 v231, v231
	v_exp_f32_e32 v232, v232
	v_exp_f32_e32 v233, v233
	v_exp_f32_e32 v234, v234
	v_exp_f32_e32 v235, v235
	s_waitcnt vmcnt(15)
	v_lshlrev_b32_e32 v196, 16, v148
	v_and_b32_e32 v197, 0xffff0000, v148
	v_lshlrev_b32_e32 v198, 16, v149
	v_and_b32_e32 v199, 0xffff0000, v149
	v_lshlrev_b32_e32 v200, 16, v150
	v_and_b32_e32 v201, 0xffff0000, v150
	v_lshlrev_b32_e32 v202, 16, v151
	v_and_b32_e32 v203, 0xffff0000, v151
	v_pk_mul_f32 v[188:189], v[188:189], v[180:181]
	v_pk_mul_f32 v[190:191], v[190:191], v[182:183]
	v_pk_mul_f32 v[192:193], v[192:193], v[184:185]
	v_pk_mul_f32 v[194:195], v[194:195], v[186:187]
	v_pk_mul_f32 v[188:189], v[188:189], v[196:197]
	v_pk_mul_f32 v[190:191], v[190:191], v[198:199]
	v_pk_mul_f32 v[192:193], v[192:193], v[200:201]
	v_pk_mul_f32 v[194:195], v[194:195], v[202:203]
	v_cvt_pk_bf16_f32 v212, v188, v189
	v_cvt_pk_bf16_f32 v213, v190, v191
	v_cvt_pk_bf16_f32 v214, v192, v193
	v_cvt_pk_bf16_f32 v215, v194, v195
	global_store_dwordx4 v173, v[212:215], s[10:11] nt
	v_pk_fma_f32 v[216:217], v[228:229], v[216:217], v[188:189]
	v_pk_fma_f32 v[218:219], v[230:231], v[218:219], v[190:191]
	v_pk_fma_f32 v[240:241], v[232:233], v[240:241], v[192:193]
	v_pk_fma_f32 v[242:243], v[234:235], v[242:243], v[194:195]
	v_pk_mul_f32 v[58:59], v[58:59], v[228:229]
	v_pk_mul_f32 v[60:61], v[60:61], v[230:231]
	v_pk_mul_f32 v[66:67], v[66:67], v[232:233]
	v_pk_mul_f32 v[68:69], v[68:69], v[234:235]
	v_pk_add_f32 v[204:205], v[204:205], v[114:115]
	v_pk_add_f32 v[206:207], v[206:207], v[116:117]
	v_pk_add_f32 v[220:221], v[220:221], v[106:107]
	v_pk_add_f32 v[222:223], v[222:223], v[108:109]
	v_fmac_f32_dpp v216, v216, v58 row_shr:1 row_mask:0xf bank_mask:0xf
	v_fmac_f32_dpp v217, v217, v59 row_shr:1 row_mask:0xf bank_mask:0xf
	v_fmac_f32_dpp v218, v218, v60 row_shr:1 row_mask:0xf bank_mask:0xf
	v_fmac_f32_dpp v219, v219, v61 row_shr:1 row_mask:0xf bank_mask:0xf
	v_fmac_f32_dpp v240, v240, v66 row_shr:1 row_mask:0xf bank_mask:0xf
	v_fmac_f32_dpp v241, v241, v67 row_shr:1 row_mask:0xf bank_mask:0xf
	v_fmac_f32_dpp v242, v242, v68 row_shr:1 row_mask:0xf bank_mask:0xf
	v_fmac_f32_dpp v243, v243, v69 row_shr:1 row_mask:0xf bank_mask:0xf
	v_mul_f32_dpp v58, v58, v58 row_shr:1 row_mask:0xf bank_mask:0xf
	v_mul_f32_dpp v59, v59, v59 row_shr:1 row_mask:0xf bank_mask:0xf
	v_mul_f32_dpp v60, v60, v60 row_shr:1 row_mask:0xf bank_mask:0xf
	v_mul_f32_dpp v61, v61, v61 row_shr:1 row_mask:0xf bank_mask:0xf
	v_mul_f32_dpp v66, v66, v66 row_shr:1 row_mask:0xf bank_mask:0xf
	v_mul_f32_dpp v67, v67, v67 row_shr:1 row_mask:0xf bank_mask:0xf
	v_mul_f32_dpp v68, v68, v68 row_shr:1 row_mask:0xf bank_mask:0xf
	v_mul_f32_dpp v69, v69, v69 row_shr:1 row_mask:0xf bank_mask:0xf
	v_add_f32_dpp v204, v204, v204 row_shr:1 row_mask:0xf bank_mask:0xf
	v_add_f32_dpp v205, v205, v205 row_shr:1 row_mask:0xf bank_mask:0xf
	v_add_f32_dpp v206, v206, v206 row_shr:1 row_mask:0xf bank_mask:0xf
	v_add_f32_dpp v207, v207, v207 row_shr:1 row_mask:0xf bank_mask:0xf
	v_add_f32_dpp v220, v220, v220 row_shr:1 row_mask:0xf bank_mask:0xf
	v_add_f32_dpp v221, v221, v221 row_shr:1 row_mask:0xf bank_mask:0xf
	v_add_f32_dpp v222, v222, v222 row_shr:1 row_mask:0xf bank_mask:0xf
	v_add_f32_dpp v223, v223, v223 row_shr:1 row_mask:0xf bank_mask:0xf
	v_fmac_f32_dpp v216, v216, v58 row_shr:2 row_mask:0xf bank_mask:0xf
	v_fmac_f32_dpp v217, v217, v59 row_shr:2 row_mask:0xf bank_mask:0xf
	v_fmac_f32_dpp v218, v218, v60 row_shr:2 row_mask:0xf bank_mask:0xf
	v_fmac_f32_dpp v219, v219, v61 row_shr:2 row_mask:0xf bank_mask:0xf
	v_fmac_f32_dpp v240, v240, v66 row_shr:2 row_mask:0xf bank_mask:0xf
	v_fmac_f32_dpp v241, v241, v67 row_shr:2 row_mask:0xf bank_mask:0xf
	v_fmac_f32_dpp v242, v242, v68 row_shr:2 row_mask:0xf bank_mask:0xf
	v_fmac_f32_dpp v243, v243, v69 row_shr:2 row_mask:0xf bank_mask:0xf
	v_mul_f32_dpp v58, v58, v58 row_shr:2 row_mask:0xf bank_mask:0xf
; __device__ __forceinline__ float bf_lo(unsigned w) { return __uint_as_float(w << 16); }
; __device__ __forceinline__ float bf_hi(unsigned w) { return __uint_as_float(w & 0xffff0000u); }
; __device__ __forceinline__ float fexp(float x) { return __builtin_amdgcn_exp2f(1.44269504f * x); }
;     __device__ __forceinline__ void operator()(AccMut acc, const Unit& u, int sw) const {
;     ...
;                         const f32x2 z = (f32x2){acc[ai][1][m][n][2 * jp], acc[ai][1][m][n][2 * jp + 1]} * (-1.44269504f);
;                         f32x2 e; e.x = __builtin_amdgcn_exp2f(z.x); e.y = __builtin_amdgcn_exp2f(z.y); e = e + 1.0f;
;                         f32x2 ig; ig.x = __builtin_amdgcn_rcpf(e.x); ig.y = __builtin_amdgcn_rcpf(e.y);
;                         const f32x2 x2 = (f32x2){acc[ai][0][m][n][2 * jp], acc[ai][0][m][n][2 * jp + 1]} * 2.0f;
;                         f32x2 ser = x2 * (1.0f / 120.0f) + (1.0f / 24.0f); ser = ser * x2 + (1.0f / 6.0f); ser = ser * x2 + 0.5f; ser = ser * x2 + 1.0f; ser = ser * (-x2);
;                         f32x2 em = ser;
;                         if (__builtin_expect(__builtin_amdgcn_ballot_w64(x2.x <= -0.25f || x2.y <= -0.25f) != 0ull, 0)) {
;                             em.x = (x2.x > -0.25f) ? ser.x : (1.0f - fexp(x2.x)); em.y = (x2.y > -0.25f) ? ser.y : (1.0f - fexp(x2.y)); }
;                         const unsigned wv = xw[2 * n + jp];
;                         f32x2 sq; sq.x = __builtin_amdgcn_sqrtf(em.x); sq.y = __builtin_amdgcn_sqrtf(em.y);
; __device__ __forceinline__ void scan1_phase(const bf16_t* LA, const bf16_t* BT, int sw, View vw) {
;     ...
;             for (int i = 0; i < 8; ++i) {
;                 const float l0 = bf_lo(lw[i].x), l1 = bf_hi(lw[i].x), l2 = bf_lo(lw[i].y), l3 = bf_hi(lw[i].y);
;                 S[0] += l0; S[1] += l1; S[2] += l2; S[3] += l3;
;                 Hc[0] = fexp(l0) * Hc[0] + bf_lo(bw[i].x); Hc[1] = fexp(l1) * Hc[1] + bf_hi(bw[i].x); Hc[2] = fexp(l2) * Hc[2] + bf_lo(bw[i].y); Hc[3] = fexp(l3) * Hc[3] + bf_hi(bw[i].y); }
;         }
;         *(f32x4*)(CP + (size_t)bq * E + 4 * quad) = (f32x4){S[0], S[1], S[2], S[3]};
;         *(f32x4*)(CH + (size_t)bq * E + 4 * quad) = (f32x4){Hc[0], Hc[1], Hc[2], Hc[3]};
	v_mul_f32_dpp v59, v59, v59 row_shr:2 row_mask:0xf bank_mask:0xf
	v_mul_f32_dpp v60, v60, v60 row_shr:2 row_mask:0xf bank_mask:0xf
	v_mul_f32_dpp v61, v61, v61 row_shr:2 row_mask:0xf bank_mask:0xf
	v_mul_f32_dpp v66, v66, v66 row_shr:2 row_mask:0xf bank_mask:0xf
	v_mul_f32_dpp v67, v67, v67 row_shr:2 row_mask:0xf bank_mask:0xf
	v_mul_f32_dpp v68, v68, v68 row_shr:2 row_mask:0xf bank_mask:0xf
	v_mul_f32_dpp v69, v69, v69 row_shr:2 row_mask:0xf bank_mask:0xf
	v_add_f32_dpp v204, v204, v204 row_shr:2 row_mask:0xf bank_mask:0xf
	v_add_f32_dpp v205, v205, v205 row_shr:2 row_mask:0xf bank_mask:0xf
	v_add_f32_dpp v206, v206, v206 row_shr:2 row_mask:0xf bank_mask:0xf
	v_add_f32_dpp v207, v207, v207 row_shr:2 row_mask:0xf bank_mask:0xf
	v_add_f32_dpp v220, v220, v220 row_shr:2 row_mask:0xf bank_mask:0xf
	v_add_f32_dpp v221, v221, v221 row_shr:2 row_mask:0xf bank_mask:0xf
	v_add_f32_dpp v222, v222, v222 row_shr:2 row_mask:0xf bank_mask:0xf
	v_add_f32_dpp v223, v223, v223 row_shr:2 row_mask:0xf bank_mask:0xf
	v_fmac_f32_dpp v216, v216, v58 row_shr:4 row_mask:0xf bank_mask:0xf
	v_fmac_f32_dpp v217, v217, v59 row_shr:4 row_mask:0xf bank_mask:0xf
	v_fmac_f32_dpp v218, v218, v60 row_shr:4 row_mask:0xf bank_mask:0xf
	v_fmac_f32_dpp v219, v219, v61 row_shr:4 row_mask:0xf bank_mask:0xf
	v_fmac_f32_dpp v240, v240, v66 row_shr:4 row_mask:0xf bank_mask:0xf
	v_fmac_f32_dpp v241, v241, v67 row_shr:4 row_mask:0xf bank_mask:0xf
	v_fmac_f32_dpp v242, v242, v68 row_shr:4 row_mask:0xf bank_mask:0xf
	v_fmac_f32_dpp v243, v243, v69 row_shr:4 row_mask:0xf bank_mask:0xf
	v_mul_f32_dpp v58, v58, v58 row_shr:4 row_mask:0xf bank_mask:0xf
	v_mul_f32_dpp v59, v59, v59 row_shr:4 row_mask:0xf bank_mask:0xf
	v_mul_f32_dpp v60, v60, v60 row_shr:4 row_mask:0xf bank_mask:0xf
	v_mul_f32_dpp v61, v61, v61 row_shr:4 row_mask:0xf bank_mask:0xf
	v_mul_f32_dpp v66, v66, v66 row_shr:4 row_mask:0xf bank_mask:0xf
	v_mul_f32_dpp v67, v67, v67 row_shr:4 row_mask:0xf bank_mask:0xf
	v_mul_f32_dpp v68, v68, v68 row_shr:4 row_mask:0xf bank_mask:0xf
	v_mul_f32_dpp v69, v69, v69 row_shr:4 row_mask:0xf bank_mask:0xf
	v_add_f32_dpp v204, v204, v204 row_shr:4 row_mask:0xf bank_mask:0xf
	v_add_f32_dpp v205, v205, v205 row_shr:4 row_mask:0xf bank_mask:0xf
	v_add_f32_dpp v206, v206, v206 row_shr:4 row_mask:0xf bank_mask:0xf
	v_add_f32_dpp v207, v207, v207 row_shr:4 row_mask:0xf bank_mask:0xf
	v_add_f32_dpp v220, v220, v220 row_shr:4 row_mask:0xf bank_mask:0xf
	v_add_f32_dpp v221, v221, v221 row_shr:4 row_mask:0xf bank_mask:0xf
	v_add_f32_dpp v222, v222, v222 row_shr:4 row_mask:0xf bank_mask:0xf
	v_add_f32_dpp v223, v223, v223 row_shr:4 row_mask:0xf bank_mask:0xf
	v_fmac_f32_dpp v216, v216, v58 row_shr:8 row_mask:0xf bank_mask:0xf
	v_fmac_f32_dpp v217, v217, v59 row_shr:8 row_mask:0xf bank_mask:0xf
	v_fmac_f32_dpp v218, v218, v60 row_shr:8 row_mask:0xf bank_mask:0xf
	v_fmac_f32_dpp v219, v219, v61 row_shr:8 row_mask:0xf bank_mask:0xf
	v_fmac_f32_dpp v240, v240, v66 row_shr:8 row_mask:0xf bank_mask:0xf
	v_fmac_f32_dpp v241, v241, v67 row_shr:8 row_mask:0xf bank_mask:0xf
	v_fmac_f32_dpp v242, v242, v68 row_shr:8 row_mask:0xf bank_mask:0xf
	v_fmac_f32_dpp v243, v243, v69 row_shr:8 row_mask:0xf bank_mask:0xf
	v_add_f32_dpp v204, v204, v204 row_shr:8 row_mask:0xf bank_mask:0xf
	v_add_f32_dpp v205, v205, v205 row_shr:8 row_mask:0xf bank_mask:0xf
	v_add_f32_dpp v206, v206, v206 row_shr:8 row_mask:0xf bank_mask:0xf
	v_add_f32_dpp v207, v207, v207 row_shr:8 row_mask:0xf bank_mask:0xf
	v_add_f32_dpp v220, v220, v220 row_shr:8 row_mask:0xf bank_mask:0xf
	v_add_f32_dpp v221, v221, v221 row_shr:8 row_mask:0xf bank_mask:0xf
	v_add_f32_dpp v222, v222, v222 row_shr:8 row_mask:0xf bank_mask:0xf
	v_add_f32_dpp v223, v223, v223 row_shr:8 row_mask:0xf bank_mask:0xf
	v_mbcnt_lo_u32_b32 v180, -1, 0
	v_mbcnt_hi_u32_b32 v180, -1, v180
	v_and_b32_e32 v180, 15, v180
	v_cmp_eq_u32_e32 vcc, 15, v180
	v_add_u32_e32 v181, 0x0, v239
	v_add_u32_e32 v182, 0x400000, v239
	s_mov_b64 exec, vcc
	global_store_dwordx4 v181, v[204:207], s[26:27]
	global_store_dwordx4 v181, v[220:223], s[26:27] offset:16
	global_store_dwordx4 v182, v[216:219], s[26:27]
	global_store_dwordx4 v182, v[240:243], s[26:27] offset:16
	s_mov_b64 exec, -1
	v_pk_mul_f32 v[180:181], v[26:27], s[74:75] op_sel_hi:[1,0]
	v_pk_mul_f32 v[182:183], v[28:29], s[74:75] op_sel_hi:[1,0]
	v_pk_mul_f32 v[184:185], v[30:31], s[74:75] op_sel_hi:[1,0]
	v_pk_mul_f32 v[186:187], v[32:33], s[74:75] op_sel_hi:[1,0]
	v_exp_f32_e32 v180, v180
	v_exp_f32_e32 v181, v181
	v_exp_f32_e32 v182, v182
	v_exp_f32_e32 v183, v183
	v_exp_f32_e32 v184, v184
	v_exp_f32_e32 v185, v185
	v_exp_f32_e32 v186, v186
	v_exp_f32_e32 v187, v187
	v_pk_fma_f32 v[188:189], v[110:111], s[24:25], v[236:237] op_sel_hi:[1,0,0]
	v_pk_fma_f32 v[190:191], v[112:113], s[24:25], v[236:237] op_sel_hi:[1,0,0]
	v_pk_fma_f32 v[192:193], v[102:103], s[24:25], v[236:237] op_sel_hi:[1,0,0]
	v_pk_fma_f32 v[194:195], v[104:105], s[24:25], v[236:237] op_sel_hi:[1,0,0]
	v_pk_add_f32 v[180:181], v[180:181], 1.0 op_sel_hi:[1,0]
	v_pk_add_f32 v[182:183], v[182:183], 1.0 op_sel_hi:[1,0]
	v_pk_add_f32 v[184:185], v[184:185], 1.0 op_sel_hi:[1,0]
	v_pk_add_f32 v[186:187], v[186:187], 1.0 op_sel_hi:[1,0]
	v_rcp_f32_e32 v180, v180
	v_rcp_f32_e32 v181, v181
	v_rcp_f32_e32 v182, v182
	v_rcp_f32_e32 v183, v183
	v_rcp_f32_e32 v184, v184
	v_rcp_f32_e32 v185, v185
	v_rcp_f32_e32 v186, v186
	v_rcp_f32_e32 v187, v187
	v_pk_fma_f32 v[188:189], v[110:111], v[188:189], s[22:23] op_sel_hi:[1,1,0]
	v_pk_fma_f32 v[190:191], v[112:113], v[190:191], s[22:23] op_sel_hi:[1,1,0]
	v_pk_fma_f32 v[192:193], v[102:103], v[192:193], s[22:23] op_sel_hi:[1,1,0]
; __device__ __forceinline__ unsigned cvt_pk_bf16(float lo, float hi) { unsigned r; asm volatile("v_cvt_pk_bf16_f32 %0, %1, %2" : "=v"(r) : "v"(lo), "v"(hi)); return r; }
; __device__ __forceinline__ float bf_lo(unsigned w) { return __uint_as_float(w << 16); }
;     __device__ __forceinline__ void operator()(AccMut acc, const Unit& u, int sw) const {
;     ...
;             for (int m = 0; m < 4; ++m) { const size_t off = (size_t)(row0 + ai * HALF + m * 16) * E + c0;
;                 const u32x4 xw = xnext;
;                 if (ai * 4 + m < 7) { const int ai2 = (ai * 4 + m + 1) >> 2, m2 = (ai * 4 + m + 1) & 3; xnext = *(const u32x4*)(XC + (size_t)(row0 + ai2 * HALF + m2 * 16) * E + c0); }
;                 float bt[8];
; #pragma unroll
;                 for (int n = 0; n < 2; ++n)
; #pragma unroll
;                     for (int jp = 0; jp < 2; ++jp) {
;                         const f32x2 z = (f32x2){acc[ai][1][m][n][2 * jp], acc[ai][1][m][n][2 * jp + 1]} * (-1.44269504f);
;                         f32x2 e; e.x = __builtin_amdgcn_exp2f(z.x); e.y = __builtin_amdgcn_exp2f(z.y); e = e + 1.0f;
;                         f32x2 ig; ig.x = __builtin_amdgcn_rcpf(e.x); ig.y = __builtin_amdgcn_rcpf(e.y);
;                         const f32x2 x2 = (f32x2){acc[ai][0][m][n][2 * jp], acc[ai][0][m][n][2 * jp + 1]} * 2.0f;
;                         f32x2 ser = x2 * (1.0f / 120.0f) + (1.0f / 24.0f); ser = ser * x2 + (1.0f / 6.0f); ser = ser * x2 + 0.5f; ser = ser * x2 + 1.0f; ser = ser * (-x2);
;                         f32x2 em = ser;
;                         if (__builtin_expect(__builtin_amdgcn_ballot_w64(x2.x <= -0.25f || x2.y <= -0.25f) != 0ull, 0)) {
;                             em.x = (x2.x > -0.25f) ? ser.x : (1.0f - fexp(x2.x)); em.y = (x2.y > -0.25f) ? ser.y : (1.0f - fexp(x2.y)); }
;                         const unsigned wv = xw[2 * n + jp];
;                         f32x2 sq; sq.x = __builtin_amdgcn_sqrtf(em.x); sq.y = __builtin_amdgcn_sqrtf(em.y);
;                         const f32x2 b2 = sq * ig * (f32x2){bf_lo(wv), bf_hi(wv)};
;                         bt[4 * n + 2 * jp] = b2.x; bt[4 * n + 2 * jp + 1] = b2.y; }
;                 u32x4 w; w.x = cvt_pk_bf16(bt[0], bt[1]); w.y = cvt_pk_bf16(bt[2], bt[3]); w.z = cvt_pk_bf16(bt[4], bt[5]); w.w = cvt_pk_bf16(bt[6], bt[7]);
;                 *(u32x4*)(BT + off) = w; }
	v_pk_fma_f32 v[194:195], v[104:105], v[194:195], s[22:23] op_sel_hi:[1,1,0]
	v_pk_fma_f32 v[188:189], v[110:111], v[188:189], -2.0 op_sel_hi:[1,1,0]
	v_pk_fma_f32 v[190:191], v[112:113], v[190:191], -2.0 op_sel_hi:[1,1,0]
	v_pk_fma_f32 v[192:193], v[102:103], v[192:193], -2.0 op_sel_hi:[1,1,0]
	v_pk_fma_f32 v[194:195], v[104:105], v[194:195], -2.0 op_sel_hi:[1,1,0]
	v_pk_fma_f32 v[188:189], v[110:111], v[188:189], -2.0 op_sel_hi:[1,1,0]
	v_pk_fma_f32 v[190:191], v[112:113], v[190:191], -2.0 op_sel_hi:[1,1,0]
	v_pk_fma_f32 v[192:193], v[102:103], v[192:193], -2.0 op_sel_hi:[1,1,0]
	v_pk_fma_f32 v[194:195], v[104:105], v[194:195], -2.0 op_sel_hi:[1,1,0]
	v_pk_mul_f32 v[188:189], v[110:111], v[188:189]
	v_pk_mul_f32 v[190:191], v[112:113], v[190:191]
	v_pk_mul_f32 v[192:193], v[102:103], v[192:193]
	v_pk_mul_f32 v[194:195], v[104:105], v[194:195]
	v_pk_mul_f32 v[228:229], v[110:111], s[74:75] op_sel_hi:[1,0] neg_lo:[0,1] neg_hi:[0,1]
	v_pk_mul_f32 v[230:231], v[112:113], s[74:75] op_sel_hi:[1,0] neg_lo:[0,1] neg_hi:[0,1]
	v_pk_mul_f32 v[232:233], v[102:103], s[74:75] op_sel_hi:[1,0] neg_lo:[0,1] neg_hi:[0,1]
	v_pk_mul_f32 v[234:235], v[104:105], s[74:75] op_sel_hi:[1,0] neg_lo:[0,1] neg_hi:[0,1]
	v_sqrt_f32_e32 v188, v188
	v_sqrt_f32_e32 v189, v189
	v_sqrt_f32_e32 v190, v190
	v_sqrt_f32_e32 v191, v191
	v_sqrt_f32_e32 v192, v192
	v_sqrt_f32_e32 v193, v193
	v_sqrt_f32_e32 v194, v194
	v_sqrt_f32_e32 v195, v195
	v_exp_f32_e32 v26, v228
	v_exp_f32_e32 v27, v229
	v_exp_f32_e32 v28, v230
	v_exp_f32_e32 v29, v231
	v_exp_f32_e32 v30, v232
	v_exp_f32_e32 v31, v233
	v_exp_f32_e32 v32, v234
	v_exp_f32_e32 v33, v235
	s_waitcnt vmcnt(19)
	v_lshlrev_b32_e32 v196, 16, v152
	v_and_b32_e32 v197, 0xffff0000, v152
	v_lshlrev_b32_e32 v198, 16, v153
	v_and_b32_e32 v199, 0xffff0000, v153
	v_lshlrev_b32_e32 v200, 16, v154
	v_and_b32_e32 v201, 0xffff0000, v154
	v_lshlrev_b32_e32 v202, 16, v155
	v_and_b32_e32 v203, 0xffff0000, v155
	v_pk_mul_f32 v[188:189], v[188:189], v[180:181]
	v_pk_mul_f32 v[190:191], v[190:191], v[182:183]
	v_pk_mul_f32 v[192:193], v[192:193], v[184:185]
	v_pk_mul_f32 v[194:195], v[194:195], v[186:187]
	v_pk_mul_f32 v[216:217], v[188:189], v[196:197]
	v_pk_mul_f32 v[218:219], v[190:191], v[198:199]
	v_pk_mul_f32 v[240:241], v[192:193], v[200:201]
	v_pk_mul_f32 v[242:243], v[194:195], v[202:203]
	v_cvt_pk_bf16_f32 v208, v216, v217
	v_cvt_pk_bf16_f32 v209, v218, v219
	v_cvt_pk_bf16_f32 v210, v240, v241
	v_cvt_pk_bf16_f32 v211, v242, v243
	global_store_dwordx4 v176, v[208:211], s[10:11] nt
	v_pk_mul_f32 v[180:181], v[18:19], s[74:75] op_sel_hi:[1,0]
	v_pk_mul_f32 v[182:183], v[20:21], s[74:75] op_sel_hi:[1,0]
	v_pk_mul_f32 v[184:185], v[22:23], s[74:75] op_sel_hi:[1,0]
	v_pk_mul_f32 v[186:187], v[24:25], s[74:75] op_sel_hi:[1,0]
	v_exp_f32_e32 v180, v180
	v_exp_f32_e32 v181, v181
	v_exp_f32_e32 v182, v182
	v_exp_f32_e32 v183, v183
	v_exp_f32_e32 v184, v184
	v_exp_f32_e32 v185, v185
	v_exp_f32_e32 v186, v186
	v_exp_f32_e32 v187, v187
	v_pk_fma_f32 v[188:189], v[98:99], s[24:25], v[236:237] op_sel_hi:[1,0,0]
	v_pk_fma_f32 v[190:191], v[100:101], s[24:25], v[236:237] op_sel_hi:[1,0,0]
	v_pk_fma_f32 v[192:193], v[94:95], s[24:25], v[236:237] op_sel_hi:[1,0,0]
	v_pk_fma_f32 v[194:195], v[96:97], s[24:25], v[236:237] op_sel_hi:[1,0,0]
	v_pk_add_f32 v[180:181], v[180:181], 1.0 op_sel_hi:[1,0]
	v_pk_add_f32 v[182:183], v[182:183], 1.0 op_sel_hi:[1,0]
	v_pk_add_f32 v[184:185], v[184:185], 1.0 op_sel_hi:[1,0]
	v_pk_add_f32 v[186:187], v[186:187], 1.0 op_sel_hi:[1,0]
	v_rcp_f32_e32 v180, v180
	v_rcp_f32_e32 v181, v181
	v_rcp_f32_e32 v182, v182
	v_rcp_f32_e32 v183, v183
	v_rcp_f32_e32 v184, v184
	v_rcp_f32_e32 v185, v185
	v_rcp_f32_e32 v186, v186
	v_rcp_f32_e32 v187, v187
	v_pk_fma_f32 v[188:189], v[98:99], v[188:189], s[22:23] op_sel_hi:[1,1,0]
	v_pk_fma_f32 v[190:191], v[100:101], v[190:191], s[22:23] op_sel_hi:[1,1,0]
	v_pk_fma_f32 v[192:193], v[94:95], v[192:193], s[22:23] op_sel_hi:[1,1,0]
	v_pk_fma_f32 v[194:195], v[96:97], v[194:195], s[22:23] op_sel_hi:[1,1,0]
	v_pk_fma_f32 v[188:189], v[98:99], v[188:189], -2.0 op_sel_hi:[1,1,0]
	v_pk_fma_f32 v[190:191], v[100:101], v[190:191], -2.0 op_sel_hi:[1,1,0]
	v_pk_fma_f32 v[192:193], v[94:95], v[192:193], -2.0 op_sel_hi:[1,1,0]
	v_pk_fma_f32 v[194:195], v[96:97], v[194:195], -2.0 op_sel_hi:[1,1,0]
	v_pk_fma_f32 v[188:189], v[98:99], v[188:189], -2.0 op_sel_hi:[1,1,0]
	v_pk_fma_f32 v[190:191], v[100:101], v[190:191], -2.0 op_sel_hi:[1,1,0]
	v_pk_fma_f32 v[192:193], v[94:95], v[192:193], -2.0 op_sel_hi:[1,1,0]
	v_pk_fma_f32 v[194:195], v[96:97], v[194:195], -2.0 op_sel_hi:[1,1,0]
	v_pk_mul_f32 v[188:189], v[98:99], v[188:189]
	v_pk_mul_f32 v[190:191], v[100:101], v[190:191]
	v_pk_mul_f32 v[192:193], v[94:95], v[192:193]
	v_pk_mul_f32 v[194:195], v[96:97], v[194:195]
	v_pk_mul_f32 v[228:229], v[98:99], s[74:75] op_sel_hi:[1,0] neg_lo:[0,1] neg_hi:[0,1]
	v_pk_mul_f32 v[230:231], v[100:101], s[74:75] op_sel_hi:[1,0] neg_lo:[0,1] neg_hi:[0,1]
	v_pk_mul_f32 v[232:233], v[94:95], s[74:75] op_sel_hi:[1,0] neg_lo:[0,1] neg_hi:[0,1]
	v_pk_mul_f32 v[234:235], v[96:97], s[74:75] op_sel_hi:[1,0] neg_lo:[0,1] neg_hi:[0,1]
	v_sqrt_f32_e32 v188, v188
	v_sqrt_f32_e32 v189, v189
	v_sqrt_f32_e32 v190, v190
	v_sqrt_f32_e32 v191, v191
	v_sqrt_f32_e32 v192, v192
	v_sqrt_f32_e32 v193, v193
	v_sqrt_f32_e32 v194, v194
	v_sqrt_f32_e32 v195, v195
	v_exp_f32_e32 v228, v228
	v_exp_f32_e32 v229, v229
	v_exp_f32_e32 v230, v230
	v_exp_f32_e32 v231, v231
	v_exp_f32_e32 v232, v232
	v_exp_f32_e32 v233, v233
	v_exp_f32_e32 v234, v234
	v_exp_f32_e32 v235, v235
	s_waitcnt vmcnt(19)
; __device__ __forceinline__ unsigned cvt_pk_bf16(float lo, float hi) { unsigned r; asm volatile("v_cvt_pk_bf16_f32 %0, %1, %2" : "=v"(r) : "v"(lo), "v"(hi)); return r; }
; __device__ __forceinline__ float bf_lo(unsigned w) { return __uint_as_float(w << 16); }
;     __device__ __forceinline__ void operator()(AccMut acc, const Unit& u, int sw) const {
;     ...
;             for (int m = 0; m < 4; ++m) { const size_t off = (size_t)(row0 + ai * HALF + m * 16) * E + c0;
;                 const u32x4 xw = xnext;
;                 if (ai * 4 + m < 7) { const int ai2 = (ai * 4 + m + 1) >> 2, m2 = (ai * 4 + m + 1) & 3; xnext = *(const u32x4*)(XC + (size_t)(row0 + ai2 * HALF + m2 * 16) * E + c0); }
;                 float bt[8];
; #pragma unroll
;                 for (int n = 0; n < 2; ++n)
; #pragma unroll
;                     for (int jp = 0; jp < 2; ++jp) {
;                         const f32x2 z = (f32x2){acc[ai][1][m][n][2 * jp], acc[ai][1][m][n][2 * jp + 1]} * (-1.44269504f);
;                         f32x2 e; e.x = __builtin_amdgcn_exp2f(z.x); e.y = __builtin_amdgcn_exp2f(z.y); e = e + 1.0f;
;                         f32x2 ig; ig.x = __builtin_amdgcn_rcpf(e.x); ig.y = __builtin_amdgcn_rcpf(e.y);
;                         const f32x2 x2 = (f32x2){acc[ai][0][m][n][2 * jp], acc[ai][0][m][n][2 * jp + 1]} * 2.0f;
;                         f32x2 ser = x2 * (1.0f / 120.0f) + (1.0f / 24.0f); ser = ser * x2 + (1.0f / 6.0f); ser = ser * x2 + 0.5f; ser = ser * x2 + 1.0f; ser = ser * (-x2);
;                         f32x2 em = ser;
;                         if (__builtin_expect(__builtin_amdgcn_ballot_w64(x2.x <= -0.25f || x2.y <= -0.25f) != 0ull, 0)) {
;                             em.x = (x2.x > -0.25f) ? ser.x : (1.0f - fexp(x2.x)); em.y = (x2.y > -0.25f) ? ser.y : (1.0f - fexp(x2.y)); }
;                         const unsigned wv = xw[2 * n + jp];
;                         f32x2 sq; sq.x = __builtin_amdgcn_sqrtf(em.x); sq.y = __builtin_amdgcn_sqrtf(em.y);
;                         const f32x2 b2 = sq * ig * (f32x2){bf_lo(wv), bf_hi(wv)};
;                         bt[4 * n + 2 * jp] = b2.x; bt[4 * n + 2 * jp + 1] = b2.y; }
;                 u32x4 w; w.x = cvt_pk_bf16(bt[0], bt[1]); w.y = cvt_pk_bf16(bt[2], bt[3]); w.z = cvt_pk_bf16(bt[4], bt[5]); w.w = cvt_pk_bf16(bt[6], bt[7]);
;                 *(u32x4*)(BT + off) = w; }
	v_lshlrev_b32_e32 v196, 16, v156
	v_and_b32_e32 v197, 0xffff0000, v156
	v_lshlrev_b32_e32 v198, 16, v157
	v_and_b32_e32 v199, 0xffff0000, v157
	v_lshlrev_b32_e32 v200, 16, v158
	v_and_b32_e32 v201, 0xffff0000, v158
	v_lshlrev_b32_e32 v202, 16, v159
	v_and_b32_e32 v203, 0xffff0000, v159
	v_pk_mul_f32 v[188:189], v[188:189], v[180:181]
	v_pk_mul_f32 v[190:191], v[190:191], v[182:183]
	v_pk_mul_f32 v[192:193], v[192:193], v[184:185]
	v_pk_mul_f32 v[194:195], v[194:195], v[186:187]
	v_pk_mul_f32 v[188:189], v[188:189], v[196:197]
	v_pk_mul_f32 v[190:191], v[190:191], v[198:199]
	v_pk_mul_f32 v[192:193], v[192:193], v[200:201]
	v_pk_mul_f32 v[194:195], v[194:195], v[202:203]
	v_cvt_pk_bf16_f32 v212, v188, v189
	v_cvt_pk_bf16_f32 v213, v190, v191
	v_cvt_pk_bf16_f32 v214, v192, v193
	v_cvt_pk_bf16_f32 v215, v194, v195
	global_store_dwordx4 v177, v[212:215], s[10:11] nt
	v_pk_fma_f32 v[216:217], v[228:229], v[216:217], v[188:189]
	v_pk_fma_f32 v[218:219], v[230:231], v[218:219], v[190:191]
	v_pk_fma_f32 v[240:241], v[232:233], v[240:241], v[192:193]
	v_pk_fma_f32 v[242:243], v[234:235], v[242:243], v[194:195]
	v_pk_mul_f32 v[26:27], v[26:27], v[228:229]
	v_pk_mul_f32 v[28:29], v[28:29], v[230:231]
	v_pk_mul_f32 v[30:31], v[30:31], v[232:233]
	v_pk_mul_f32 v[32:33], v[32:33], v[234:235]
	v_pk_add_f32 v[110:111], v[110:111], v[98:99]
	v_pk_add_f32 v[112:113], v[112:113], v[100:101]
	v_pk_add_f32 v[102:103], v[102:103], v[94:95]
	v_pk_add_f32 v[104:105], v[104:105], v[96:97]
	v_pk_mul_f32 v[180:181], v[10:11], s[74:75] op_sel_hi:[1,0]
	v_pk_mul_f32 v[182:183], v[12:13], s[74:75] op_sel_hi:[1,0]
	v_pk_mul_f32 v[184:185], v[14:15], s[74:75] op_sel_hi:[1,0]
	v_pk_mul_f32 v[186:187], v[16:17], s[74:75] op_sel_hi:[1,0]
	v_exp_f32_e32 v180, v180
	v_exp_f32_e32 v181, v181
	v_exp_f32_e32 v182, v182
	v_exp_f32_e32 v183, v183
	v_exp_f32_e32 v184, v184
	v_exp_f32_e32 v185, v185
	v_exp_f32_e32 v186, v186
	v_exp_f32_e32 v187, v187
	v_pk_fma_f32 v[188:189], v[90:91], s[24:25], v[236:237] op_sel_hi:[1,0,0]
	v_pk_fma_f32 v[190:191], v[92:93], s[24:25], v[236:237] op_sel_hi:[1,0,0]
	v_pk_fma_f32 v[192:193], v[86:87], s[24:25], v[236:237] op_sel_hi:[1,0,0]
	v_pk_fma_f32 v[194:195], v[88:89], s[24:25], v[236:237] op_sel_hi:[1,0,0]
	v_pk_add_f32 v[180:181], v[180:181], 1.0 op_sel_hi:[1,0]
	v_pk_add_f32 v[182:183], v[182:183], 1.0 op_sel_hi:[1,0]
	v_pk_add_f32 v[184:185], v[184:185], 1.0 op_sel_hi:[1,0]
	v_pk_add_f32 v[186:187], v[186:187], 1.0 op_sel_hi:[1,0]
	v_rcp_f32_e32 v180, v180
	v_rcp_f32_e32 v181, v181
	v_rcp_f32_e32 v182, v182
	v_rcp_f32_e32 v183, v183
	v_rcp_f32_e32 v184, v184
	v_rcp_f32_e32 v185, v185
	v_rcp_f32_e32 v186, v186
	v_rcp_f32_e32 v187, v187
	v_pk_fma_f32 v[188:189], v[90:91], v[188:189], s[22:23] op_sel_hi:[1,1,0]
	v_pk_fma_f32 v[190:191], v[92:93], v[190:191], s[22:23] op_sel_hi:[1,1,0]
	v_pk_fma_f32 v[192:193], v[86:87], v[192:193], s[22:23] op_sel_hi:[1,1,0]
	v_pk_fma_f32 v[194:195], v[88:89], v[194:195], s[22:23] op_sel_hi:[1,1,0]
	v_pk_fma_f32 v[188:189], v[90:91], v[188:189], -2.0 op_sel_hi:[1,1,0]
	v_pk_fma_f32 v[190:191], v[92:93], v[190:191], -2.0 op_sel_hi:[1,1,0]
	v_pk_fma_f32 v[192:193], v[86:87], v[192:193], -2.0 op_sel_hi:[1,1,0]
	v_pk_fma_f32 v[194:195], v[88:89], v[194:195], -2.0 op_sel_hi:[1,1,0]
	v_pk_fma_f32 v[188:189], v[90:91], v[188:189], -2.0 op_sel_hi:[1,1,0]
	v_pk_fma_f32 v[190:191], v[92:93], v[190:191], -2.0 op_sel_hi:[1,1,0]
	v_pk_fma_f32 v[192:193], v[86:87], v[192:193], -2.0 op_sel_hi:[1,1,0]
	v_pk_fma_f32 v[194:195], v[88:89], v[194:195], -2.0 op_sel_hi:[1,1,0]
	v_pk_mul_f32 v[188:189], v[90:91], v[188:189]
	v_pk_mul_f32 v[190:191], v[92:93], v[190:191]
	v_pk_mul_f32 v[192:193], v[86:87], v[192:193]
	v_pk_mul_f32 v[194:195], v[88:89], v[194:195]
	v_pk_mul_f32 v[228:229], v[90:91], s[74:75] op_sel_hi:[1,0] neg_lo:[0,1] neg_hi:[0,1]
	v_pk_mul_f32 v[230:231], v[92:93], s[74:75] op_sel_hi:[1,0] neg_lo:[0,1] neg_hi:[0,1]
	v_pk_mul_f32 v[232:233], v[86:87], s[74:75] op_sel_hi:[1,0] neg_lo:[0,1] neg_hi:[0,1]
	v_pk_mul_f32 v[234:235], v[88:89], s[74:75] op_sel_hi:[1,0] neg_lo:[0,1] neg_hi:[0,1]
	v_sqrt_f32_e32 v188, v188
	v_sqrt_f32_e32 v189, v189
	v_sqrt_f32_e32 v190, v190
	v_sqrt_f32_e32 v191, v191
	v_sqrt_f32_e32 v192, v192
	v_sqrt_f32_e32 v193, v193
	v_sqrt_f32_e32 v194, v194
	v_sqrt_f32_e32 v195, v195
	v_exp_f32_e32 v228, v228
	v_exp_f32_e32 v229, v229
	v_exp_f32_e32 v230, v230
	v_exp_f32_e32 v231, v231
	v_exp_f32_e32 v232, v232
	v_exp_f32_e32 v233, v233
	v_exp_f32_e32 v234, v234
	v_exp_f32_e32 v235, v235
	s_waitcnt vmcnt(19)
; __device__ __forceinline__ unsigned cvt_pk_bf16(float lo, float hi) { unsigned r; asm volatile("v_cvt_pk_bf16_f32 %0, %1, %2" : "=v"(r) : "v"(lo), "v"(hi)); return r; }
; __device__ __forceinline__ float bf_lo(unsigned w) { return __uint_as_float(w << 16); }
;     __device__ __forceinline__ void operator()(AccMut acc, const Unit& u, int sw) const {
;     ...
;             for (int m = 0; m < 4; ++m) { const size_t off = (size_t)(row0 + ai * HALF + m * 16) * E + c0;
;                 const u32x4 xw = xnext;
;                 if (ai * 4 + m < 7) { const int ai2 = (ai * 4 + m + 1) >> 2, m2 = (ai * 4 + m + 1) & 3; xnext = *(const u32x4*)(XC + (size_t)(row0 + ai2 * HALF + m2 * 16) * E + c0); }
;                 float bt[8];
; #pragma unroll
;                 for (int n = 0; n < 2; ++n)
; #pragma unroll
;                     for (int jp = 0; jp < 2; ++jp) {
;                         const f32x2 z = (f32x2){acc[ai][1][m][n][2 * jp], acc[ai][1][m][n][2 * jp + 1]} * (-1.44269504f);
;                         f32x2 e; e.x = __builtin_amdgcn_exp2f(z.x); e.y = __builtin_amdgcn_exp2f(z.y); e = e + 1.0f;
;                         f32x2 ig; ig.x = __builtin_amdgcn_rcpf(e.x); ig.y = __builtin_amdgcn_rcpf(e.y);
;                         const f32x2 x2 = (f32x2){acc[ai][0][m][n][2 * jp], acc[ai][0][m][n][2 * jp + 1]} * 2.0f;
;                         f32x2 ser = x2 * (1.0f / 120.0f) + (1.0f / 24.0f); ser = ser * x2 + (1.0f / 6.0f); ser = ser * x2 + 0.5f; ser = ser * x2 + 1.0f; ser = ser * (-x2);
;                         f32x2 em = ser;
;                         if (__builtin_expect(__builtin_amdgcn_ballot_w64(x2.x <= -0.25f || x2.y <= -0.25f) != 0ull, 0)) {
;                             em.x = (x2.x > -0.25f) ? ser.x : (1.0f - fexp(x2.x)); em.y = (x2.y > -0.25f) ? ser.y : (1.0f - fexp(x2.y)); }
;                         const unsigned wv = xw[2 * n + jp];
;                         f32x2 sq; sq.x = __builtin_amdgcn_sqrtf(em.x); sq.y = __builtin_amdgcn_sqrtf(em.y);
;                         const f32x2 b2 = sq * ig * (f32x2){bf_lo(wv), bf_hi(wv)};
;                         bt[4 * n + 2 * jp] = b2.x; bt[4 * n + 2 * jp + 1] = b2.y; }
;                 u32x4 w; w.x = cvt_pk_bf16(bt[0], bt[1]); w.y = cvt_pk_bf16(bt[2], bt[3]); w.z = cvt_pk_bf16(bt[4], bt[5]); w.w = cvt_pk_bf16(bt[6], bt[7]);
;                 *(u32x4*)(BT + off) = w; }
	v_lshlrev_b32_e32 v196, 16, v160
	v_and_b32_e32 v197, 0xffff0000, v160
	v_lshlrev_b32_e32 v198, 16, v161
	v_and_b32_e32 v199, 0xffff0000, v161
	v_lshlrev_b32_e32 v200, 16, v162
	v_and_b32_e32 v201, 0xffff0000, v162
	v_lshlrev_b32_e32 v202, 16, v163
	v_and_b32_e32 v203, 0xffff0000, v163
	v_pk_mul_f32 v[188:189], v[188:189], v[180:181]
	v_pk_mul_f32 v[190:191], v[190:191], v[182:183]
	v_pk_mul_f32 v[192:193], v[192:193], v[184:185]
	v_pk_mul_f32 v[194:195], v[194:195], v[186:187]
	v_pk_mul_f32 v[188:189], v[188:189], v[196:197]
	v_pk_mul_f32 v[190:191], v[190:191], v[198:199]
	v_pk_mul_f32 v[192:193], v[192:193], v[200:201]
	v_pk_mul_f32 v[194:195], v[194:195], v[202:203]
	v_cvt_pk_bf16_f32 v208, v188, v189
	v_cvt_pk_bf16_f32 v209, v190, v191
	v_cvt_pk_bf16_f32 v210, v192, v193
	v_cvt_pk_bf16_f32 v211, v194, v195
	global_store_dwordx4 v178, v[208:211], s[10:11] nt
	v_pk_fma_f32 v[216:217], v[228:229], v[216:217], v[188:189]
	v_pk_fma_f32 v[218:219], v[230:231], v[218:219], v[190:191]
	v_pk_fma_f32 v[240:241], v[232:233], v[240:241], v[192:193]
	v_pk_fma_f32 v[242:243], v[234:235], v[242:243], v[194:195]
	v_pk_mul_f32 v[26:27], v[26:27], v[228:229]
	v_pk_mul_f32 v[28:29], v[28:29], v[230:231]
	v_pk_mul_f32 v[30:31], v[30:31], v[232:233]
	v_pk_mul_f32 v[32:33], v[32:33], v[234:235]
	v_pk_add_f32 v[110:111], v[110:111], v[90:91]
	v_pk_add_f32 v[112:113], v[112:113], v[92:93]
	v_pk_add_f32 v[102:103], v[102:103], v[86:87]
	v_pk_add_f32 v[104:105], v[104:105], v[88:89]
	v_pk_mul_f32 v[180:181], v[2:3], s[74:75] op_sel_hi:[1,0]
	v_pk_mul_f32 v[182:183], v[4:5], s[74:75] op_sel_hi:[1,0]
	v_pk_mul_f32 v[184:185], v[6:7], s[74:75] op_sel_hi:[1,0]
	v_pk_mul_f32 v[186:187], v[8:9], s[74:75] op_sel_hi:[1,0]
	v_exp_f32_e32 v180, v180
	v_exp_f32_e32 v181, v181
	v_exp_f32_e32 v182, v182
	v_exp_f32_e32 v183, v183
	v_exp_f32_e32 v184, v184
	v_exp_f32_e32 v185, v185
	v_exp_f32_e32 v186, v186
	v_exp_f32_e32 v187, v187
	v_pk_fma_f32 v[188:189], v[74:75], s[24:25], v[236:237] op_sel_hi:[1,0,0]
	v_pk_fma_f32 v[190:191], v[76:77], s[24:25], v[236:237] op_sel_hi:[1,0,0]
	v_pk_fma_f32 v[192:193], v[70:71], s[24:25], v[236:237] op_sel_hi:[1,0,0]
	v_pk_fma_f32 v[194:195], v[72:73], s[24:25], v[236:237] op_sel_hi:[1,0,0]
	v_pk_add_f32 v[180:181], v[180:181], 1.0 op_sel_hi:[1,0]
	v_pk_add_f32 v[182:183], v[182:183], 1.0 op_sel_hi:[1,0]
	v_pk_add_f32 v[184:185], v[184:185], 1.0 op_sel_hi:[1,0]
	v_pk_add_f32 v[186:187], v[186:187], 1.0 op_sel_hi:[1,0]
	v_rcp_f32_e32 v180, v180
	v_rcp_f32_e32 v181, v181
	v_rcp_f32_e32 v182, v182
	v_rcp_f32_e32 v183, v183
	v_rcp_f32_e32 v184, v184
	v_rcp_f32_e32 v185, v185
	v_rcp_f32_e32 v186, v186
	v_rcp_f32_e32 v187, v187
	v_pk_fma_f32 v[188:189], v[74:75], v[188:189], s[22:23] op_sel_hi:[1,1,0]
	v_pk_fma_f32 v[190:191], v[76:77], v[190:191], s[22:23] op_sel_hi:[1,1,0]
	v_pk_fma_f32 v[192:193], v[70:71], v[192:193], s[22:23] op_sel_hi:[1,1,0]
	v_pk_fma_f32 v[194:195], v[72:73], v[194:195], s[22:23] op_sel_hi:[1,1,0]
	v_pk_fma_f32 v[188:189], v[74:75], v[188:189], -2.0 op_sel_hi:[1,1,0]
	v_pk_fma_f32 v[190:191], v[76:77], v[190:191], -2.0 op_sel_hi:[1,1,0]
	v_pk_fma_f32 v[192:193], v[70:71], v[192:193], -2.0 op_sel_hi:[1,1,0]
	v_pk_fma_f32 v[194:195], v[72:73], v[194:195], -2.0 op_sel_hi:[1,1,0]
	v_pk_fma_f32 v[188:189], v[74:75], v[188:189], -2.0 op_sel_hi:[1,1,0]
	v_pk_fma_f32 v[190:191], v[76:77], v[190:191], -2.0 op_sel_hi:[1,1,0]
	v_pk_fma_f32 v[192:193], v[70:71], v[192:193], -2.0 op_sel_hi:[1,1,0]
	v_pk_fma_f32 v[194:195], v[72:73], v[194:195], -2.0 op_sel_hi:[1,1,0]
	v_pk_mul_f32 v[188:189], v[74:75], v[188:189]
	v_pk_mul_f32 v[190:191], v[76:77], v[190:191]
	v_pk_mul_f32 v[192:193], v[70:71], v[192:193]
	v_pk_mul_f32 v[194:195], v[72:73], v[194:195]
	v_pk_mul_f32 v[228:229], v[74:75], s[74:75] op_sel_hi:[1,0] neg_lo:[0,1] neg_hi:[0,1]
	v_pk_mul_f32 v[230:231], v[76:77], s[74:75] op_sel_hi:[1,0] neg_lo:[0,1] neg_hi:[0,1]
	v_pk_mul_f32 v[232:233], v[70:71], s[74:75] op_sel_hi:[1,0] neg_lo:[0,1] neg_hi:[0,1]
	v_pk_mul_f32 v[234:235], v[72:73], s[74:75] op_sel_hi:[1,0] neg_lo:[0,1] neg_hi:[0,1]
	v_sqrt_f32_e32 v188, v188
	v_sqrt_f32_e32 v189, v189
	v_sqrt_f32_e32 v190, v190
	v_sqrt_f32_e32 v191, v191
	v_sqrt_f32_e32 v192, v192
	v_sqrt_f32_e32 v193, v193
	v_sqrt_f32_e32 v194, v194
	v_sqrt_f32_e32 v195, v195
	v_exp_f32_e32 v228, v228
	v_exp_f32_e32 v229, v229
	v_exp_f32_e32 v230, v230
	v_exp_f32_e32 v231, v231
	v_exp_f32_e32 v232, v232
	v_exp_f32_e32 v233, v233
	v_exp_f32_e32 v234, v234
	v_exp_f32_e32 v235, v235
	s_waitcnt vmcnt(19)
; __device__ __forceinline__ unsigned cvt_pk_bf16(float lo, float hi) { unsigned r; asm volatile("v_cvt_pk_bf16_f32 %0, %1, %2" : "=v"(r) : "v"(lo), "v"(hi)); return r; }
; __device__ __forceinline__ float bf_lo(unsigned w) { return __uint_as_float(w << 16); }
;     __device__ __forceinline__ void operator()(AccMut acc, const Unit& u, int sw) const {
;     ...
;                         const f32x2 z = (f32x2){acc[ai][1][m][n][2 * jp], acc[ai][1][m][n][2 * jp + 1]} * (-1.44269504f);
;                         f32x2 e; e.x = __builtin_amdgcn_exp2f(z.x); e.y = __builtin_amdgcn_exp2f(z.y); e = e + 1.0f;
;                         f32x2 ig; ig.x = __builtin_amdgcn_rcpf(e.x); ig.y = __builtin_amdgcn_rcpf(e.y);
;                         const f32x2 x2 = (f32x2){acc[ai][0][m][n][2 * jp], acc[ai][0][m][n][2 * jp + 1]} * 2.0f;
;                         f32x2 ser = x2 * (1.0f / 120.0f) + (1.0f / 24.0f); ser = ser * x2 + (1.0f / 6.0f); ser = ser * x2 + 0.5f; ser = ser * x2 + 1.0f; ser = ser * (-x2);
;                         f32x2 em = ser;
;                         if (__builtin_expect(__builtin_amdgcn_ballot_w64(x2.x <= -0.25f || x2.y <= -0.25f) != 0ull, 0)) {
;                             em.x = (x2.x > -0.25f) ? ser.x : (1.0f - fexp(x2.x)); em.y = (x2.y > -0.25f) ? ser.y : (1.0f - fexp(x2.y)); }
;                         const unsigned wv = xw[2 * n + jp];
;                         f32x2 sq; sq.x = __builtin_amdgcn_sqrtf(em.x); sq.y = __builtin_amdgcn_sqrtf(em.y);
;                         const f32x2 b2 = sq * ig * (f32x2){bf_lo(wv), bf_hi(wv)};
;                         bt[4 * n + 2 * jp] = b2.x; bt[4 * n + 2 * jp + 1] = b2.y; }
;                 u32x4 w; w.x = cvt_pk_bf16(bt[0], bt[1]); w.y = cvt_pk_bf16(bt[2], bt[3]); w.z = cvt_pk_bf16(bt[4], bt[5]); w.w = cvt_pk_bf16(bt[6], bt[7]);
;                 *(u32x4*)(BT + off) = w; }
; __device__ __forceinline__ void scan1_phase(const bf16_t* LA, const bf16_t* BT, int sw, View vw) {
;     ...
;             for (int i = 0; i < 8; ++i) {
;                 const float l0 = bf_lo(lw[i].x), l1 = bf_hi(lw[i].x), l2 = bf_lo(lw[i].y), l3 = bf_hi(lw[i].y);
;                 S[0] += l0; S[1] += l1; S[2] += l2; S[3] += l3;
;                 Hc[0] = fexp(l0) * Hc[0] + bf_lo(bw[i].x); Hc[1] = fexp(l1) * Hc[1] + bf_hi(bw[i].x); Hc[2] = fexp(l2) * Hc[2] + bf_lo(bw[i].y); Hc[3] = fexp(l3) * Hc[3] + bf_hi(bw[i].y); }
	v_lshlrev_b32_e32 v196, 16, v164
	v_and_b32_e32 v197, 0xffff0000, v164
	v_lshlrev_b32_e32 v198, 16, v165
	v_and_b32_e32 v199, 0xffff0000, v165
	v_lshlrev_b32_e32 v200, 16, v166
	v_and_b32_e32 v201, 0xffff0000, v166
	v_lshlrev_b32_e32 v202, 16, v167
	v_and_b32_e32 v203, 0xffff0000, v167
	v_pk_mul_f32 v[188:189], v[188:189], v[180:181]
	v_pk_mul_f32 v[190:191], v[190:191], v[182:183]
	v_pk_mul_f32 v[192:193], v[192:193], v[184:185]
	v_pk_mul_f32 v[194:195], v[194:195], v[186:187]
	v_pk_mul_f32 v[188:189], v[188:189], v[196:197]
	v_pk_mul_f32 v[190:191], v[190:191], v[198:199]
	v_pk_mul_f32 v[192:193], v[192:193], v[200:201]
	v_pk_mul_f32 v[194:195], v[194:195], v[202:203]
	v_cvt_pk_bf16_f32 v212, v188, v189
	v_cvt_pk_bf16_f32 v213, v190, v191
	v_cvt_pk_bf16_f32 v214, v192, v193
	v_cvt_pk_bf16_f32 v215, v194, v195
	global_store_dwordx4 v179, v[212:215], s[10:11] nt
	v_pk_fma_f32 v[216:217], v[228:229], v[216:217], v[188:189]
	v_pk_fma_f32 v[218:219], v[230:231], v[218:219], v[190:191]
	v_pk_fma_f32 v[240:241], v[232:233], v[240:241], v[192:193]
	v_pk_fma_f32 v[242:243], v[234:235], v[242:243], v[194:195]
	v_pk_mul_f32 v[26:27], v[26:27], v[228:229]
	v_pk_mul_f32 v[28:29], v[28:29], v[230:231]
	v_pk_mul_f32 v[30:31], v[30:31], v[232:233]
	v_pk_mul_f32 v[32:33], v[32:33], v[234:235]
	v_pk_add_f32 v[110:111], v[110:111], v[74:75]
	v_pk_add_f32 v[112:113], v[112:113], v[76:77]
	v_pk_add_f32 v[102:103], v[102:103], v[70:71]
	v_pk_add_f32 v[104:105], v[104:105], v[72:73]
	v_fmac_f32_dpp v216, v216, v26 row_shr:1 row_mask:0xf bank_mask:0xf
	v_fmac_f32_dpp v217, v217, v27 row_shr:1 row_mask:0xf bank_mask:0xf
	v_fmac_f32_dpp v218, v218, v28 row_shr:1 row_mask:0xf bank_mask:0xf
	v_fmac_f32_dpp v219, v219, v29 row_shr:1 row_mask:0xf bank_mask:0xf
	v_fmac_f32_dpp v240, v240, v30 row_shr:1 row_mask:0xf bank_mask:0xf
	v_fmac_f32_dpp v241, v241, v31 row_shr:1 row_mask:0xf bank_mask:0xf
	v_fmac_f32_dpp v242, v242, v32 row_shr:1 row_mask:0xf bank_mask:0xf
	v_fmac_f32_dpp v243, v243, v33 row_shr:1 row_mask:0xf bank_mask:0xf
	v_mul_f32_dpp v26, v26, v26 row_shr:1 row_mask:0xf bank_mask:0xf
	v_mul_f32_dpp v27, v27, v27 row_shr:1 row_mask:0xf bank_mask:0xf
	v_mul_f32_dpp v28, v28, v28 row_shr:1 row_mask:0xf bank_mask:0xf
	v_mul_f32_dpp v29, v29, v29 row_shr:1 row_mask:0xf bank_mask:0xf
	v_mul_f32_dpp v30, v30, v30 row_shr:1 row_mask:0xf bank_mask:0xf
	v_mul_f32_dpp v31, v31, v31 row_shr:1 row_mask:0xf bank_mask:0xf
	v_mul_f32_dpp v32, v32, v32 row_shr:1 row_mask:0xf bank_mask:0xf
	v_mul_f32_dpp v33, v33, v33 row_shr:1 row_mask:0xf bank_mask:0xf
	v_add_f32_dpp v110, v110, v110 row_shr:1 row_mask:0xf bank_mask:0xf
	v_add_f32_dpp v111, v111, v111 row_shr:1 row_mask:0xf bank_mask:0xf
	v_add_f32_dpp v112, v112, v112 row_shr:1 row_mask:0xf bank_mask:0xf
	v_add_f32_dpp v113, v113, v113 row_shr:1 row_mask:0xf bank_mask:0xf
	v_add_f32_dpp v102, v102, v102 row_shr:1 row_mask:0xf bank_mask:0xf
	v_add_f32_dpp v103, v103, v103 row_shr:1 row_mask:0xf bank_mask:0xf
	v_add_f32_dpp v104, v104, v104 row_shr:1 row_mask:0xf bank_mask:0xf
	v_add_f32_dpp v105, v105, v105 row_shr:1 row_mask:0xf bank_mask:0xf
	v_fmac_f32_dpp v216, v216, v26 row_shr:2 row_mask:0xf bank_mask:0xf
	v_fmac_f32_dpp v217, v217, v27 row_shr:2 row_mask:0xf bank_mask:0xf
	v_fmac_f32_dpp v218, v218, v28 row_shr:2 row_mask:0xf bank_mask:0xf
	v_fmac_f32_dpp v219, v219, v29 row_shr:2 row_mask:0xf bank_mask:0xf
	v_fmac_f32_dpp v240, v240, v30 row_shr:2 row_mask:0xf bank_mask:0xf
	v_fmac_f32_dpp v241, v241, v31 row_shr:2 row_mask:0xf bank_mask:0xf
	v_fmac_f32_dpp v242, v242, v32 row_shr:2 row_mask:0xf bank_mask:0xf
	v_fmac_f32_dpp v243, v243, v33 row_shr:2 row_mask:0xf bank_mask:0xf
	v_mul_f32_dpp v26, v26, v26 row_shr:2 row_mask:0xf bank_mask:0xf
	v_mul_f32_dpp v27, v27, v27 row_shr:2 row_mask:0xf bank_mask:0xf
	v_mul_f32_dpp v28, v28, v28 row_shr:2 row_mask:0xf bank_mask:0xf
	v_mul_f32_dpp v29, v29, v29 row_shr:2 row_mask:0xf bank_mask:0xf
	v_mul_f32_dpp v30, v30, v30 row_shr:2 row_mask:0xf bank_mask:0xf
; __device__ __forceinline__ float bf_lo(unsigned w) { return __uint_as_float(w << 16); }
; __device__ __forceinline__ float bf_hi(unsigned w) { return __uint_as_float(w & 0xffff0000u); }
; __device__ __forceinline__ float fexp(float x) { return __builtin_amdgcn_exp2f(1.44269504f * x); }
; __device__ __forceinline__ void scan1_phase(const bf16_t* LA, const bf16_t* BT, int sw, View vw) {
;     ...
;             for (int i = 0; i < 8; ++i) {
;                 const float l0 = bf_lo(lw[i].x), l1 = bf_hi(lw[i].x), l2 = bf_lo(lw[i].y), l3 = bf_hi(lw[i].y);
;                 S[0] += l0; S[1] += l1; S[2] += l2; S[3] += l3;
;                 Hc[0] = fexp(l0) * Hc[0] + bf_lo(bw[i].x); Hc[1] = fexp(l1) * Hc[1] + bf_hi(bw[i].x); Hc[2] = fexp(l2) * Hc[2] + bf_lo(bw[i].y); Hc[3] = fexp(l3) * Hc[3] + bf_hi(bw[i].y); }
;         }
;         *(f32x4*)(CP + (size_t)bq * E + 4 * quad) = (f32x4){S[0], S[1], S[2], S[3]};
;         *(f32x4*)(CH + (size_t)bq * E + 4 * quad) = (f32x4){Hc[0], Hc[1], Hc[2], Hc[3]};
	v_mul_f32_dpp v31, v31, v31 row_shr:2 row_mask:0xf bank_mask:0xf
	v_mul_f32_dpp v32, v32, v32 row_shr:2 row_mask:0xf bank_mask:0xf
	v_mul_f32_dpp v33, v33, v33 row_shr:2 row_mask:0xf bank_mask:0xf
	v_add_f32_dpp v110, v110, v110 row_shr:2 row_mask:0xf bank_mask:0xf
	v_add_f32_dpp v111, v111, v111 row_shr:2 row_mask:0xf bank_mask:0xf
	v_add_f32_dpp v112, v112, v112 row_shr:2 row_mask:0xf bank_mask:0xf
	v_add_f32_dpp v113, v113, v113 row_shr:2 row_mask:0xf bank_mask:0xf
	v_add_f32_dpp v102, v102, v102 row_shr:2 row_mask:0xf bank_mask:0xf
	v_add_f32_dpp v103, v103, v103 row_shr:2 row_mask:0xf bank_mask:0xf
	v_add_f32_dpp v104, v104, v104 row_shr:2 row_mask:0xf bank_mask:0xf
	v_add_f32_dpp v105, v105, v105 row_shr:2 row_mask:0xf bank_mask:0xf
	v_fmac_f32_dpp v216, v216, v26 row_shr:4 row_mask:0xf bank_mask:0xf
	v_fmac_f32_dpp v217, v217, v27 row_shr:4 row_mask:0xf bank_mask:0xf
	v_fmac_f32_dpp v218, v218, v28 row_shr:4 row_mask:0xf bank_mask:0xf
	v_fmac_f32_dpp v219, v219, v29 row_shr:4 row_mask:0xf bank_mask:0xf
	v_fmac_f32_dpp v240, v240, v30 row_shr:4 row_mask:0xf bank_mask:0xf
	v_fmac_f32_dpp v241, v241, v31 row_shr:4 row_mask:0xf bank_mask:0xf
	v_fmac_f32_dpp v242, v242, v32 row_shr:4 row_mask:0xf bank_mask:0xf
	v_fmac_f32_dpp v243, v243, v33 row_shr:4 row_mask:0xf bank_mask:0xf
	v_mul_f32_dpp v26, v26, v26 row_shr:4 row_mask:0xf bank_mask:0xf
	v_mul_f32_dpp v27, v27, v27 row_shr:4 row_mask:0xf bank_mask:0xf
	v_mul_f32_dpp v28, v28, v28 row_shr:4 row_mask:0xf bank_mask:0xf
	v_mul_f32_dpp v29, v29, v29 row_shr:4 row_mask:0xf bank_mask:0xf
	v_mul_f32_dpp v30, v30, v30 row_shr:4 row_mask:0xf bank_mask:0xf
	v_mul_f32_dpp v31, v31, v31 row_shr:4 row_mask:0xf bank_mask:0xf
	v_mul_f32_dpp v32, v32, v32 row_shr:4 row_mask:0xf bank_mask:0xf
	v_mul_f32_dpp v33, v33, v33 row_shr:4 row_mask:0xf bank_mask:0xf
	v_add_f32_dpp v110, v110, v110 row_shr:4 row_mask:0xf bank_mask:0xf
	v_add_f32_dpp v111, v111, v111 row_shr:4 row_mask:0xf bank_mask:0xf
	v_add_f32_dpp v112, v112, v112 row_shr:4 row_mask:0xf bank_mask:0xf
	v_add_f32_dpp v113, v113, v113 row_shr:4 row_mask:0xf bank_mask:0xf
	v_add_f32_dpp v102, v102, v102 row_shr:4 row_mask:0xf bank_mask:0xf
	v_add_f32_dpp v103, v103, v103 row_shr:4 row_mask:0xf bank_mask:0xf
	v_add_f32_dpp v104, v104, v104 row_shr:4 row_mask:0xf bank_mask:0xf
	v_add_f32_dpp v105, v105, v105 row_shr:4 row_mask:0xf bank_mask:0xf
	v_fmac_f32_dpp v216, v216, v26 row_shr:8 row_mask:0xf bank_mask:0xf
	v_fmac_f32_dpp v217, v217, v27 row_shr:8 row_mask:0xf bank_mask:0xf
	v_fmac_f32_dpp v218, v218, v28 row_shr:8 row_mask:0xf bank_mask:0xf
	v_fmac_f32_dpp v219, v219, v29 row_shr:8 row_mask:0xf bank_mask:0xf
	v_fmac_f32_dpp v240, v240, v30 row_shr:8 row_mask:0xf bank_mask:0xf
	v_fmac_f32_dpp v241, v241, v31 row_shr:8 row_mask:0xf bank_mask:0xf
	v_fmac_f32_dpp v242, v242, v32 row_shr:8 row_mask:0xf bank_mask:0xf
	v_fmac_f32_dpp v243, v243, v33 row_shr:8 row_mask:0xf bank_mask:0xf
	v_add_f32_dpp v110, v110, v110 row_shr:8 row_mask:0xf bank_mask:0xf
	v_add_f32_dpp v111, v111, v111 row_shr:8 row_mask:0xf bank_mask:0xf
	v_add_f32_dpp v112, v112, v112 row_shr:8 row_mask:0xf bank_mask:0xf
	v_add_f32_dpp v113, v113, v113 row_shr:8 row_mask:0xf bank_mask:0xf
	v_add_f32_dpp v102, v102, v102 row_shr:8 row_mask:0xf bank_mask:0xf
	v_add_f32_dpp v103, v103, v103 row_shr:8 row_mask:0xf bank_mask:0xf
	v_add_f32_dpp v104, v104, v104 row_shr:8 row_mask:0xf bank_mask:0xf
	v_add_f32_dpp v105, v105, v105 row_shr:8 row_mask:0xf bank_mask:0xf
	v_mbcnt_lo_u32_b32 v180, -1, 0
	v_mbcnt_hi_u32_b32 v180, -1, v180
	v_and_b32_e32 v180, 15, v180
	v_cmp_eq_u32_e32 vcc, 15, v180
	v_add_u32_e32 v181, 0x4000, v239
	v_add_u32_e32 v182, 0x404000, v239
	s_mov_b64 exec, vcc
	global_store_dwordx4 v181, v[110:113], s[26:27]
	global_store_dwordx4 v181, v[102:105], s[26:27] offset:16
	global_store_dwordx4 v182, v[216:219], s[26:27]
	global_store_dwordx4 v182, v[240:243], s[26:27] offset:16
	s_mov_b64 exec, -1

; __device__ __forceinline__ float bf_lo(unsigned w) { return __uint_as_float(w << 16); }
; __device__ __forceinline__ float bf_hi(unsigned w) { return __uint_as_float(w & 0xffff0000u); }
; __device__ __forceinline__ float fexp(float x) { return __builtin_amdgcn_exp2f(1.44269504f * x); }
;     __device__ __forceinline__ void operator()(AccMut acc, const Unit& u, int sw) const {
;     ...
;                         const f32x2 z = (f32x2){acc[ai][1][m][n][2 * jp], acc[ai][1][m][n][2 * jp + 1]} * (-1.44269504f);
;                         f32x2 e; e.x = __builtin_amdgcn_exp2f(z.x); e.y = __builtin_amdgcn_exp2f(z.y); e = e + 1.0f;
;                         f32x2 ig; ig.x = __builtin_amdgcn_rcpf(e.x); ig.y = __builtin_amdgcn_rcpf(e.y);
;                         const f32x2 x2 = (f32x2){acc[ai][0][m][n][2 * jp], acc[ai][0][m][n][2 * jp + 1]} * 2.0f;
;                         f32x2 ser = x2 * (1.0f / 120.0f) + (1.0f / 24.0f); ser = ser * x2 + (1.0f / 6.0f); ser = ser * x2 + 0.5f; ser = ser * x2 + 1.0f; ser = ser * (-x2);
;                         f32x2 em = ser;
;                         if (__builtin_expect(__builtin_amdgcn_ballot_w64(x2.x <= -0.25f || x2.y <= -0.25f) != 0ull, 0)) {
;                             em.x = (x2.x > -0.25f) ? ser.x : (1.0f - fexp(x2.x)); em.y = (x2.y > -0.25f) ? ser.y : (1.0f - fexp(x2.y)); }
;                         const unsigned wv = xw[2 * n + jp];
;                         f32x2 sq; sq.x = __builtin_amdgcn_sqrtf(em.x); sq.y = __builtin_amdgcn_sqrtf(em.y);
;                         const f32x2 b2 = sq * ig * (f32x2){bf_lo(wv), bf_hi(wv)};
.Lgate_epi_general:
	s_mov_b32 s17, 0x4038aa3b
	v_pk_mul_f32 v[180:181], v[58:59], s[74:75] op_sel_hi:[1,0]
	v_pk_mul_f32 v[182:183], v[60:61], s[74:75] op_sel_hi:[1,0]
	v_pk_mul_f32 v[184:185], v[66:67], s[74:75] op_sel_hi:[1,0]
	v_pk_mul_f32 v[186:187], v[68:69], s[74:75] op_sel_hi:[1,0]
	v_exp_f32_e32 v180, v180
	v_exp_f32_e32 v181, v181
	v_exp_f32_e32 v182, v182
	v_exp_f32_e32 v183, v183
	v_exp_f32_e32 v184, v184
	v_exp_f32_e32 v185, v185
	v_exp_f32_e32 v186, v186
	v_exp_f32_e32 v187, v187
	v_pk_fma_f32 v[188:189], v[204:205], s[24:25], v[236:237] op_sel_hi:[1,0,0]
	v_pk_fma_f32 v[190:191], v[206:207], s[24:25], v[236:237] op_sel_hi:[1,0,0]
	v_pk_fma_f32 v[192:193], v[220:221], s[24:25], v[236:237] op_sel_hi:[1,0,0]
	v_pk_fma_f32 v[194:195], v[222:223], s[24:25], v[236:237] op_sel_hi:[1,0,0]
	v_pk_add_f32 v[180:181], v[180:181], 1.0 op_sel_hi:[1,0]
	v_pk_add_f32 v[182:183], v[182:183], 1.0 op_sel_hi:[1,0]
	v_pk_add_f32 v[184:185], v[184:185], 1.0 op_sel_hi:[1,0]
	v_pk_add_f32 v[186:187], v[186:187], 1.0 op_sel_hi:[1,0]
	v_rcp_f32_e32 v180, v180
	v_rcp_f32_e32 v181, v181
	v_rcp_f32_e32 v182, v182
	v_rcp_f32_e32 v183, v183
	v_rcp_f32_e32 v184, v184
	v_rcp_f32_e32 v185, v185
	v_rcp_f32_e32 v186, v186
	v_rcp_f32_e32 v187, v187
	v_pk_fma_f32 v[188:189], v[204:205], v[188:189], s[22:23] op_sel_hi:[1,1,0]
	v_pk_fma_f32 v[190:191], v[206:207], v[190:191], s[22:23] op_sel_hi:[1,1,0]
	v_pk_fma_f32 v[192:193], v[220:221], v[192:193], s[22:23] op_sel_hi:[1,1,0]
	v_pk_fma_f32 v[194:195], v[222:223], v[194:195], s[22:23] op_sel_hi:[1,1,0]
	v_pk_fma_f32 v[188:189], v[204:205], v[188:189], -2.0 op_sel_hi:[1,1,0]
	v_pk_fma_f32 v[190:191], v[206:207], v[190:191], -2.0 op_sel_hi:[1,1,0]
	v_pk_fma_f32 v[192:193], v[220:221], v[192:193], -2.0 op_sel_hi:[1,1,0]
	v_pk_fma_f32 v[194:195], v[222:223], v[194:195], -2.0 op_sel_hi:[1,1,0]
	v_pk_fma_f32 v[188:189], v[204:205], v[188:189], -2.0 op_sel_hi:[1,1,0]
	v_pk_fma_f32 v[190:191], v[206:207], v[190:191], -2.0 op_sel_hi:[1,1,0]
	v_pk_fma_f32 v[192:193], v[220:221], v[192:193], -2.0 op_sel_hi:[1,1,0]
	v_pk_fma_f32 v[194:195], v[222:223], v[194:195], -2.0 op_sel_hi:[1,1,0]
	v_pk_mul_f32 v[188:189], v[204:205], v[188:189]
	v_pk_mul_f32 v[190:191], v[206:207], v[190:191]
	v_pk_mul_f32 v[192:193], v[220:221], v[192:193]
	v_pk_mul_f32 v[194:195], v[222:223], v[194:195]
	v_mul_f32_e32 v196, s17, v204
	v_mul_f32_e32 v197, s17, v205
	v_mul_f32_e32 v198, s17, v206
	v_mul_f32_e32 v199, s17, v207
	v_mul_f32_e32 v200, s17, v220
	v_mul_f32_e32 v201, s17, v221
	v_mul_f32_e32 v202, s17, v222
	v_mul_f32_e32 v203, s17, v223
	v_exp_f32_e32 v196, v196
	v_exp_f32_e32 v197, v197
	v_exp_f32_e32 v198, v198
	v_exp_f32_e32 v199, v199
	v_exp_f32_e32 v200, v200
	v_exp_f32_e32 v201, v201
	v_exp_f32_e32 v202, v202
	v_exp_f32_e32 v203, v203
	v_pk_add_f32 v[196:197], v[196:197], 1.0 op_sel_hi:[1,0] neg_lo:[1,0] neg_hi:[1,0]
	v_pk_add_f32 v[198:199], v[198:199], 1.0 op_sel_hi:[1,0] neg_lo:[1,0] neg_hi:[1,0]
	v_pk_add_f32 v[200:201], v[200:201], 1.0 op_sel_hi:[1,0] neg_lo:[1,0] neg_hi:[1,0]
	v_pk_add_f32 v[202:203], v[202:203], 1.0 op_sel_hi:[1,0] neg_lo:[1,0] neg_hi:[1,0]
	v_cmp_lt_f32_e32 vcc, s13, v204
	s_nop 1
	v_cndmask_b32_e32 v188, v196, v188, vcc
	v_cmp_lt_f32_e32 vcc, s13, v205
	s_nop 1
	v_cndmask_b32_e32 v189, v197, v189, vcc
	v_cmp_lt_f32_e32 vcc, s13, v206
	s_nop 1
	v_cndmask_b32_e32 v190, v198, v190, vcc
	v_cmp_lt_f32_e32 vcc, s13, v207
	s_nop 1
	v_cndmask_b32_e32 v191, v199, v191, vcc
	v_cmp_lt_f32_e32 vcc, s13, v220
	s_nop 1
	v_cndmask_b32_e32 v192, v200, v192, vcc
	v_cmp_lt_f32_e32 vcc, s13, v221
	s_nop 1
	v_cndmask_b32_e32 v193, v201, v193, vcc
	v_cmp_lt_f32_e32 vcc, s13, v222
	s_nop 1
	v_cndmask_b32_e32 v194, v202, v194, vcc
	v_cmp_lt_f32_e32 vcc, s13, v223
	s_nop 1
	v_cndmask_b32_e32 v195, v203, v195, vcc
	v_pk_mul_f32 v[228:229], v[204:205], s[74:75] op_sel_hi:[1,0] neg_lo:[0,1] neg_hi:[0,1]
	v_pk_mul_f32 v[230:231], v[206:207], s[74:75] op_sel_hi:[1,0] neg_lo:[0,1] neg_hi:[0,1]
	v_pk_mul_f32 v[232:233], v[220:221], s[74:75] op_sel_hi:[1,0] neg_lo:[0,1] neg_hi:[0,1]
	v_pk_mul_f32 v[234:235], v[222:223], s[74:75] op_sel_hi:[1,0] neg_lo:[0,1] neg_hi:[0,1]
	v_sqrt_f32_e32 v188, v188
	v_sqrt_f32_e32 v189, v189
	v_sqrt_f32_e32 v190, v190
	v_sqrt_f32_e32 v191, v191
	v_sqrt_f32_e32 v192, v192
	v_sqrt_f32_e32 v193, v193
	v_sqrt_f32_e32 v194, v194
	v_sqrt_f32_e32 v195, v195
	v_exp_f32_e32 v58, v228
	v_exp_f32_e32 v59, v229
	v_exp_f32_e32 v60, v230
	v_exp_f32_e32 v61, v231
	v_exp_f32_e32 v66, v232
	v_exp_f32_e32 v67, v233
	v_exp_f32_e32 v68, v234
	v_exp_f32_e32 v69, v235
	s_waitcnt vmcnt(15)
; __device__ __forceinline__ unsigned cvt_pk_bf16(float lo, float hi) { unsigned r; asm volatile("v_cvt_pk_bf16_f32 %0, %1, %2" : "=v"(r) : "v"(lo), "v"(hi)); return r; }
; __device__ __forceinline__ float bf_lo(unsigned w) { return __uint_as_float(w << 16); }
; __device__ __forceinline__ float bf_hi(unsigned w) { return __uint_as_float(w & 0xffff0000u); }
; __device__ __forceinline__ float fexp(float x) { return __builtin_amdgcn_exp2f(1.44269504f * x); }
;     __device__ __forceinline__ void operator()(AccMut acc, const Unit& u, int sw) const {
;     ...
;                         const f32x2 z = (f32x2){acc[ai][1][m][n][2 * jp], acc[ai][1][m][n][2 * jp + 1]} * (-1.44269504f);
;                         f32x2 e; e.x = __builtin_amdgcn_exp2f(z.x); e.y = __builtin_amdgcn_exp2f(z.y); e = e + 1.0f;
;                         f32x2 ig; ig.x = __builtin_amdgcn_rcpf(e.x); ig.y = __builtin_amdgcn_rcpf(e.y);
;                         const f32x2 x2 = (f32x2){acc[ai][0][m][n][2 * jp], acc[ai][0][m][n][2 * jp + 1]} * 2.0f;
;                         f32x2 ser = x2 * (1.0f / 120.0f) + (1.0f / 24.0f); ser = ser * x2 + (1.0f / 6.0f); ser = ser * x2 + 0.5f; ser = ser * x2 + 1.0f; ser = ser * (-x2);
;                         f32x2 em = ser;
;                         if (__builtin_expect(__builtin_amdgcn_ballot_w64(x2.x <= -0.25f || x2.y <= -0.25f) != 0ull, 0)) {
;                             em.x = (x2.x > -0.25f) ? ser.x : (1.0f - fexp(x2.x)); em.y = (x2.y > -0.25f) ? ser.y : (1.0f - fexp(x2.y)); }
;                         const unsigned wv = xw[2 * n + jp];
;                         f32x2 sq; sq.x = __builtin_amdgcn_sqrtf(em.x); sq.y = __builtin_amdgcn_sqrtf(em.y);
;                         const f32x2 b2 = sq * ig * (f32x2){bf_lo(wv), bf_hi(wv)};
;                         bt[4 * n + 2 * jp] = b2.x; bt[4 * n + 2 * jp + 1] = b2.y; }
;                 u32x4 w; w.x = cvt_pk_bf16(bt[0], bt[1]); w.y = cvt_pk_bf16(bt[2], bt[3]); w.z = cvt_pk_bf16(bt[4], bt[5]); w.w = cvt_pk_bf16(bt[6], bt[7]);
;                 *(u32x4*)(BT + off) = w; }
	v_lshlrev_b32_e32 v196, 16, v136
	v_and_b32_e32 v197, 0xffff0000, v136
	v_lshlrev_b32_e32 v198, 16, v137
	v_and_b32_e32 v199, 0xffff0000, v137
	v_lshlrev_b32_e32 v200, 16, v138
	v_and_b32_e32 v201, 0xffff0000, v138
	v_lshlrev_b32_e32 v202, 16, v139
	v_and_b32_e32 v203, 0xffff0000, v139
	v_pk_mul_f32 v[188:189], v[188:189], v[180:181]
	v_pk_mul_f32 v[190:191], v[190:191], v[182:183]
	v_pk_mul_f32 v[192:193], v[192:193], v[184:185]
	v_pk_mul_f32 v[194:195], v[194:195], v[186:187]
	v_pk_mul_f32 v[216:217], v[188:189], v[196:197]
	v_pk_mul_f32 v[218:219], v[190:191], v[198:199]
	v_pk_mul_f32 v[240:241], v[192:193], v[200:201]
	v_pk_mul_f32 v[242:243], v[194:195], v[202:203]
	v_cvt_pk_bf16_f32 v208, v216, v217
	v_cvt_pk_bf16_f32 v209, v218, v219
	v_cvt_pk_bf16_f32 v210, v240, v241
	v_cvt_pk_bf16_f32 v211, v242, v243
	global_store_dwordx4 v168, v[208:211], s[10:11] nt
	v_pk_mul_f32 v[180:181], v[50:51], s[74:75] op_sel_hi:[1,0]
	v_pk_mul_f32 v[182:183], v[52:53], s[74:75] op_sel_hi:[1,0]
	v_pk_mul_f32 v[184:185], v[54:55], s[74:75] op_sel_hi:[1,0]
	v_pk_mul_f32 v[186:187], v[56:57], s[74:75] op_sel_hi:[1,0]
	v_exp_f32_e32 v180, v180
	v_exp_f32_e32 v181, v181
	v_exp_f32_e32 v182, v182
	v_exp_f32_e32 v183, v183
	v_exp_f32_e32 v184, v184
	v_exp_f32_e32 v185, v185
	v_exp_f32_e32 v186, v186
	v_exp_f32_e32 v187, v187
	v_pk_fma_f32 v[188:189], v[224:225], s[24:25], v[236:237] op_sel_hi:[1,0,0]
	v_pk_fma_f32 v[190:191], v[226:227], s[24:25], v[236:237] op_sel_hi:[1,0,0]
	v_pk_fma_f32 v[192:193], v[126:127], s[24:25], v[236:237] op_sel_hi:[1,0,0]
	v_pk_fma_f32 v[194:195], v[128:129], s[24:25], v[236:237] op_sel_hi:[1,0,0]
	v_pk_add_f32 v[180:181], v[180:181], 1.0 op_sel_hi:[1,0]
	v_pk_add_f32 v[182:183], v[182:183], 1.0 op_sel_hi:[1,0]
	v_pk_add_f32 v[184:185], v[184:185], 1.0 op_sel_hi:[1,0]
	v_pk_add_f32 v[186:187], v[186:187], 1.0 op_sel_hi:[1,0]
	v_rcp_f32_e32 v180, v180
	v_rcp_f32_e32 v181, v181
	v_rcp_f32_e32 v182, v182
	v_rcp_f32_e32 v183, v183
	v_rcp_f32_e32 v184, v184
	v_rcp_f32_e32 v185, v185
	v_rcp_f32_e32 v186, v186
	v_rcp_f32_e32 v187, v187
	v_pk_fma_f32 v[188:189], v[224:225], v[188:189], s[22:23] op_sel_hi:[1,1,0]
	v_pk_fma_f32 v[190:191], v[226:227], v[190:191], s[22:23] op_sel_hi:[1,1,0]
	v_pk_fma_f32 v[192:193], v[126:127], v[192:193], s[22:23] op_sel_hi:[1,1,0]
	v_pk_fma_f32 v[194:195], v[128:129], v[194:195], s[22:23] op_sel_hi:[1,1,0]
	v_pk_fma_f32 v[188:189], v[224:225], v[188:189], -2.0 op_sel_hi:[1,1,0]
	v_pk_fma_f32 v[190:191], v[226:227], v[190:191], -2.0 op_sel_hi:[1,1,0]
	v_pk_fma_f32 v[192:193], v[126:127], v[192:193], -2.0 op_sel_hi:[1,1,0]
	v_pk_fma_f32 v[194:195], v[128:129], v[194:195], -2.0 op_sel_hi:[1,1,0]
	v_pk_fma_f32 v[188:189], v[224:225], v[188:189], -2.0 op_sel_hi:[1,1,0]
	v_pk_fma_f32 v[190:191], v[226:227], v[190:191], -2.0 op_sel_hi:[1,1,0]
	v_pk_fma_f32 v[192:193], v[126:127], v[192:193], -2.0 op_sel_hi:[1,1,0]
	v_pk_fma_f32 v[194:195], v[128:129], v[194:195], -2.0 op_sel_hi:[1,1,0]
	v_pk_mul_f32 v[188:189], v[224:225], v[188:189]
	v_pk_mul_f32 v[190:191], v[226:227], v[190:191]
	v_pk_mul_f32 v[192:193], v[126:127], v[192:193]
	v_pk_mul_f32 v[194:195], v[128:129], v[194:195]
	v_mul_f32_e32 v196, s17, v224
	v_mul_f32_e32 v197, s17, v225
	v_mul_f32_e32 v198, s17, v226
	v_mul_f32_e32 v199, s17, v227
	v_mul_f32_e32 v200, s17, v126
	v_mul_f32_e32 v201, s17, v127
	v_mul_f32_e32 v202, s17, v128
	v_mul_f32_e32 v203, s17, v129
	v_exp_f32_e32 v196, v196
	v_exp_f32_e32 v197, v197
	v_exp_f32_e32 v198, v198
	v_exp_f32_e32 v199, v199
	v_exp_f32_e32 v200, v200
	v_exp_f32_e32 v201, v201
	v_exp_f32_e32 v202, v202
	v_exp_f32_e32 v203, v203
	v_pk_add_f32 v[196:197], v[196:197], 1.0 op_sel_hi:[1,0] neg_lo:[1,0] neg_hi:[1,0]
	v_pk_add_f32 v[198:199], v[198:199], 1.0 op_sel_hi:[1,0] neg_lo:[1,0] neg_hi:[1,0]
	v_pk_add_f32 v[200:201], v[200:201], 1.0 op_sel_hi:[1,0] neg_lo:[1,0] neg_hi:[1,0]
	v_pk_add_f32 v[202:203], v[202:203], 1.0 op_sel_hi:[1,0] neg_lo:[1,0] neg_hi:[1,0]
	v_cmp_lt_f32_e32 vcc, s13, v224
	s_nop 1
	v_cndmask_b32_e32 v188, v196, v188, vcc
	v_cmp_lt_f32_e32 vcc, s13, v225
	s_nop 1
	v_cndmask_b32_e32 v189, v197, v189, vcc
	v_cmp_lt_f32_e32 vcc, s13, v226
	s_nop 1
	v_cndmask_b32_e32 v190, v198, v190, vcc
	v_cmp_lt_f32_e32 vcc, s13, v227
	s_nop 1
	v_cndmask_b32_e32 v191, v199, v191, vcc
	v_cmp_lt_f32_e32 vcc, s13, v126
	s_nop 1
	v_cndmask_b32_e32 v192, v200, v192, vcc
	v_cmp_lt_f32_e32 vcc, s13, v127
	s_nop 1
	v_cndmask_b32_e32 v193, v201, v193, vcc
	v_cmp_lt_f32_e32 vcc, s13, v128
	s_nop 1
	v_cndmask_b32_e32 v194, v202, v194, vcc
	v_cmp_lt_f32_e32 vcc, s13, v129
	s_nop 1
	v_cndmask_b32_e32 v195, v203, v195, vcc
	v_pk_mul_f32 v[228:229], v[224:225], s[74:75] op_sel_hi:[1,0] neg_lo:[0,1] neg_hi:[0,1]
	v_pk_mul_f32 v[230:231], v[226:227], s[74:75] op_sel_hi:[1,0] neg_lo:[0,1] neg_hi:[0,1]
	v_pk_mul_f32 v[232:233], v[126:127], s[74:75] op_sel_hi:[1,0] neg_lo:[0,1] neg_hi:[0,1]
	v_pk_mul_f32 v[234:235], v[128:129], s[74:75] op_sel_hi:[1,0] neg_lo:[0,1] neg_hi:[0,1]
	v_sqrt_f32_e32 v188, v188
	v_sqrt_f32_e32 v189, v189
	v_sqrt_f32_e32 v190, v190
	v_sqrt_f32_e32 v191, v191
	v_sqrt_f32_e32 v192, v192
	v_sqrt_f32_e32 v193, v193
	v_sqrt_f32_e32 v194, v194
	v_sqrt_f32_e32 v195, v195
	v_exp_f32_e32 v228, v228
	v_exp_f32_e32 v229, v229
	v_exp_f32_e32 v230, v230
	v_exp_f32_e32 v231, v231
	v_exp_f32_e32 v232, v232
	v_exp_f32_e32 v233, v233
	v_exp_f32_e32 v234, v234
	v_exp_f32_e32 v235, v235
	s_waitcnt vmcnt(15)
; __device__ __forceinline__ unsigned cvt_pk_bf16(float lo, float hi) { unsigned r; asm volatile("v_cvt_pk_bf16_f32 %0, %1, %2" : "=v"(r) : "v"(lo), "v"(hi)); return r; }
; __device__ __forceinline__ float bf_lo(unsigned w) { return __uint_as_float(w << 16); }
; __device__ __forceinline__ float bf_hi(unsigned w) { return __uint_as_float(w & 0xffff0000u); }
; __device__ __forceinline__ float fexp(float x) { return __builtin_amdgcn_exp2f(1.44269504f * x); }
;     __device__ __forceinline__ void operator()(AccMut acc, const Unit& u, int sw) const {
;     ...
;                         const f32x2 z = (f32x2){acc[ai][1][m][n][2 * jp], acc[ai][1][m][n][2 * jp + 1]} * (-1.44269504f);
;                         f32x2 e; e.x = __builtin_amdgcn_exp2f(z.x); e.y = __builtin_amdgcn_exp2f(z.y); e = e + 1.0f;
;                         f32x2 ig; ig.x = __builtin_amdgcn_rcpf(e.x); ig.y = __builtin_amdgcn_rcpf(e.y);
;                         const f32x2 x2 = (f32x2){acc[ai][0][m][n][2 * jp], acc[ai][0][m][n][2 * jp + 1]} * 2.0f;
;                         f32x2 ser = x2 * (1.0f / 120.0f) + (1.0f / 24.0f); ser = ser * x2 + (1.0f / 6.0f); ser = ser * x2 + 0.5f; ser = ser * x2 + 1.0f; ser = ser * (-x2);
;                         f32x2 em = ser;
;                         if (__builtin_expect(__builtin_amdgcn_ballot_w64(x2.x <= -0.25f || x2.y <= -0.25f) != 0ull, 0)) {
;                             em.x = (x2.x > -0.25f) ? ser.x : (1.0f - fexp(x2.x)); em.y = (x2.y > -0.25f) ? ser.y : (1.0f - fexp(x2.y)); }
;                         const unsigned wv = xw[2 * n + jp];
;                         f32x2 sq; sq.x = __builtin_amdgcn_sqrtf(em.x); sq.y = __builtin_amdgcn_sqrtf(em.y);
;                         const f32x2 b2 = sq * ig * (f32x2){bf_lo(wv), bf_hi(wv)};
;                         bt[4 * n + 2 * jp] = b2.x; bt[4 * n + 2 * jp + 1] = b2.y; }
;                 u32x4 w; w.x = cvt_pk_bf16(bt[0], bt[1]); w.y = cvt_pk_bf16(bt[2], bt[3]); w.z = cvt_pk_bf16(bt[4], bt[5]); w.w = cvt_pk_bf16(bt[6], bt[7]);
;                 *(u32x4*)(BT + off) = w; }
	v_lshlrev_b32_e32 v196, 16, v140
	v_and_b32_e32 v197, 0xffff0000, v140
	v_lshlrev_b32_e32 v198, 16, v141
	v_and_b32_e32 v199, 0xffff0000, v141
	v_lshlrev_b32_e32 v200, 16, v142
	v_and_b32_e32 v201, 0xffff0000, v142
	v_lshlrev_b32_e32 v202, 16, v143
	v_and_b32_e32 v203, 0xffff0000, v143
	v_pk_mul_f32 v[188:189], v[188:189], v[180:181]
	v_pk_mul_f32 v[190:191], v[190:191], v[182:183]
	v_pk_mul_f32 v[192:193], v[192:193], v[184:185]
	v_pk_mul_f32 v[194:195], v[194:195], v[186:187]
	v_pk_mul_f32 v[188:189], v[188:189], v[196:197]
	v_pk_mul_f32 v[190:191], v[190:191], v[198:199]
	v_pk_mul_f32 v[192:193], v[192:193], v[200:201]
	v_pk_mul_f32 v[194:195], v[194:195], v[202:203]
	v_cvt_pk_bf16_f32 v212, v188, v189
	v_cvt_pk_bf16_f32 v213, v190, v191
	v_cvt_pk_bf16_f32 v214, v192, v193
	v_cvt_pk_bf16_f32 v215, v194, v195
	global_store_dwordx4 v169, v[212:215], s[10:11] nt
	v_pk_fma_f32 v[216:217], v[228:229], v[216:217], v[188:189]
	v_pk_fma_f32 v[218:219], v[230:231], v[218:219], v[190:191]
	v_pk_fma_f32 v[240:241], v[232:233], v[240:241], v[192:193]
	v_pk_fma_f32 v[242:243], v[234:235], v[242:243], v[194:195]
	v_pk_mul_f32 v[58:59], v[58:59], v[228:229]
	v_pk_mul_f32 v[60:61], v[60:61], v[230:231]
	v_pk_mul_f32 v[66:67], v[66:67], v[232:233]
	v_pk_mul_f32 v[68:69], v[68:69], v[234:235]
	v_pk_add_f32 v[204:205], v[204:205], v[224:225]
	v_pk_add_f32 v[206:207], v[206:207], v[226:227]
	v_pk_add_f32 v[220:221], v[220:221], v[126:127]
	v_pk_add_f32 v[222:223], v[222:223], v[128:129]
	v_pk_mul_f32 v[180:181], v[42:43], s[74:75] op_sel_hi:[1,0]
	v_pk_mul_f32 v[182:183], v[44:45], s[74:75] op_sel_hi:[1,0]
	v_pk_mul_f32 v[184:185], v[46:47], s[74:75] op_sel_hi:[1,0]
	v_pk_mul_f32 v[186:187], v[48:49], s[74:75] op_sel_hi:[1,0]
	v_exp_f32_e32 v180, v180
	v_exp_f32_e32 v181, v181
	v_exp_f32_e32 v182, v182
	v_exp_f32_e32 v183, v183
	v_exp_f32_e32 v184, v184
	v_exp_f32_e32 v185, v185
	v_exp_f32_e32 v186, v186
	v_exp_f32_e32 v187, v187
	v_pk_fma_f32 v[188:189], v[122:123], s[24:25], v[236:237] op_sel_hi:[1,0,0]
	v_pk_fma_f32 v[190:191], v[124:125], s[24:25], v[236:237] op_sel_hi:[1,0,0]
	v_pk_fma_f32 v[192:193], v[118:119], s[24:25], v[236:237] op_sel_hi:[1,0,0]
	v_pk_fma_f32 v[194:195], v[120:121], s[24:25], v[236:237] op_sel_hi:[1,0,0]
	v_pk_add_f32 v[180:181], v[180:181], 1.0 op_sel_hi:[1,0]
	v_pk_add_f32 v[182:183], v[182:183], 1.0 op_sel_hi:[1,0]
	v_pk_add_f32 v[184:185], v[184:185], 1.0 op_sel_hi:[1,0]
	v_pk_add_f32 v[186:187], v[186:187], 1.0 op_sel_hi:[1,0]
	v_rcp_f32_e32 v180, v180
	v_rcp_f32_e32 v181, v181
	v_rcp_f32_e32 v182, v182
	v_rcp_f32_e32 v183, v183
	v_rcp_f32_e32 v184, v184
	v_rcp_f32_e32 v185, v185
	v_rcp_f32_e32 v186, v186
	v_rcp_f32_e32 v187, v187
	v_pk_fma_f32 v[188:189], v[122:123], v[188:189], s[22:23] op_sel_hi:[1,1,0]
	v_pk_fma_f32 v[190:191], v[124:125], v[190:191], s[22:23] op_sel_hi:[1,1,0]
	v_pk_fma_f32 v[192:193], v[118:119], v[192:193], s[22:23] op_sel_hi:[1,1,0]
	v_pk_fma_f32 v[194:195], v[120:121], v[194:195], s[22:23] op_sel_hi:[1,1,0]
	v_pk_fma_f32 v[188:189], v[122:123], v[188:189], -2.0 op_sel_hi:[1,1,0]
	v_pk_fma_f32 v[190:191], v[124:125], v[190:191], -2.0 op_sel_hi:[1,1,0]
	v_pk_fma_f32 v[192:193], v[118:119], v[192:193], -2.0 op_sel_hi:[1,1,0]
	v_pk_fma_f32 v[194:195], v[120:121], v[194:195], -2.0 op_sel_hi:[1,1,0]
	v_pk_fma_f32 v[188:189], v[122:123], v[188:189], -2.0 op_sel_hi:[1,1,0]
	v_pk_fma_f32 v[190:191], v[124:125], v[190:191], -2.0 op_sel_hi:[1,1,0]
	v_pk_fma_f32 v[192:193], v[118:119], v[192:193], -2.0 op_sel_hi:[1,1,0]
	v_pk_fma_f32 v[194:195], v[120:121], v[194:195], -2.0 op_sel_hi:[1,1,0]
	v_pk_mul_f32 v[188:189], v[122:123], v[188:189]
	v_pk_mul_f32 v[190:191], v[124:125], v[190:191]
	v_pk_mul_f32 v[192:193], v[118:119], v[192:193]
	v_pk_mul_f32 v[194:195], v[120:121], v[194:195]
	v_mul_f32_e32 v196, s17, v122
	v_mul_f32_e32 v197, s17, v123
	v_mul_f32_e32 v198, s17, v124
	v_mul_f32_e32 v199, s17, v125
	v_mul_f32_e32 v200, s17, v118
	v_mul_f32_e32 v201, s17, v119
	v_mul_f32_e32 v202, s17, v120
	v_mul_f32_e32 v203, s17, v121
	v_exp_f32_e32 v196, v196
	v_exp_f32_e32 v197, v197
	v_exp_f32_e32 v198, v198
	v_exp_f32_e32 v199, v199
	v_exp_f32_e32 v200, v200
	v_exp_f32_e32 v201, v201
	v_exp_f32_e32 v202, v202
	v_exp_f32_e32 v203, v203
	v_pk_add_f32 v[196:197], v[196:197], 1.0 op_sel_hi:[1,0] neg_lo:[1,0] neg_hi:[1,0]
	v_pk_add_f32 v[198:199], v[198:199], 1.0 op_sel_hi:[1,0] neg_lo:[1,0] neg_hi:[1,0]
	v_pk_add_f32 v[200:201], v[200:201], 1.0 op_sel_hi:[1,0] neg_lo:[1,0] neg_hi:[1,0]
	v_pk_add_f32 v[202:203], v[202:203], 1.0 op_sel_hi:[1,0] neg_lo:[1,0] neg_hi:[1,0]
	v_cmp_lt_f32_e32 vcc, s13, v122
	s_nop 1
	v_cndmask_b32_e32 v188, v196, v188, vcc
	v_cmp_lt_f32_e32 vcc, s13, v123
	s_nop 1
	v_cndmask_b32_e32 v189, v197, v189, vcc
	v_cmp_lt_f32_e32 vcc, s13, v124
	s_nop 1
	v_cndmask_b32_e32 v190, v198, v190, vcc
	v_cmp_lt_f32_e32 vcc, s13, v125
	s_nop 1
	v_cndmask_b32_e32 v191, v199, v191, vcc
	v_cmp_lt_f32_e32 vcc, s13, v118
	s_nop 1
	v_cndmask_b32_e32 v192, v200, v192, vcc
	v_cmp_lt_f32_e32 vcc, s13, v119
	s_nop 1
	v_cndmask_b32_e32 v193, v201, v193, vcc
	v_cmp_lt_f32_e32 vcc, s13, v120
	s_nop 1
	v_cndmask_b32_e32 v194, v202, v194, vcc
	v_cmp_lt_f32_e32 vcc, s13, v121
	s_nop 1
	v_cndmask_b32_e32 v195, v203, v195, vcc
	v_pk_mul_f32 v[228:229], v[122:123], s[74:75] op_sel_hi:[1,0] neg_lo:[0,1] neg_hi:[0,1]
	v_pk_mul_f32 v[230:231], v[124:125], s[74:75] op_sel_hi:[1,0] neg_lo:[0,1] neg_hi:[0,1]
	v_pk_mul_f32 v[232:233], v[118:119], s[74:75] op_sel_hi:[1,0] neg_lo:[0,1] neg_hi:[0,1]
	v_pk_mul_f32 v[234:235], v[120:121], s[74:75] op_sel_hi:[1,0] neg_lo:[0,1] neg_hi:[0,1]
	v_sqrt_f32_e32 v188, v188
	v_sqrt_f32_e32 v189, v189
	v_sqrt_f32_e32 v190, v190
	v_sqrt_f32_e32 v191, v191
	v_sqrt_f32_e32 v192, v192
	v_sqrt_f32_e32 v193, v193
	v_sqrt_f32_e32 v194, v194
	v_sqrt_f32_e32 v195, v195
	v_exp_f32_e32 v228, v228
	v_exp_f32_e32 v229, v229
	v_exp_f32_e32 v230, v230
	v_exp_f32_e32 v231, v231
	v_exp_f32_e32 v232, v232
	v_exp_f32_e32 v233, v233
	v_exp_f32_e32 v234, v234
	v_exp_f32_e32 v235, v235
	s_waitcnt vmcnt(15)
; __device__ __forceinline__ unsigned cvt_pk_bf16(float lo, float hi) { unsigned r; asm volatile("v_cvt_pk_bf16_f32 %0, %1, %2" : "=v"(r) : "v"(lo), "v"(hi)); return r; }
; __device__ __forceinline__ float bf_lo(unsigned w) { return __uint_as_float(w << 16); }
; __device__ __forceinline__ float bf_hi(unsigned w) { return __uint_as_float(w & 0xffff0000u); }
; __device__ __forceinline__ float fexp(float x) { return __builtin_amdgcn_exp2f(1.44269504f * x); }
;     __device__ __forceinline__ void operator()(AccMut acc, const Unit& u, int sw) const {
;     ...
;                         const f32x2 z = (f32x2){acc[ai][1][m][n][2 * jp], acc[ai][1][m][n][2 * jp + 1]} * (-1.44269504f);
;                         f32x2 e; e.x = __builtin_amdgcn_exp2f(z.x); e.y = __builtin_amdgcn_exp2f(z.y); e = e + 1.0f;
;                         f32x2 ig; ig.x = __builtin_amdgcn_rcpf(e.x); ig.y = __builtin_amdgcn_rcpf(e.y);
;                         const f32x2 x2 = (f32x2){acc[ai][0][m][n][2 * jp], acc[ai][0][m][n][2 * jp + 1]} * 2.0f;
;                         f32x2 ser = x2 * (1.0f / 120.0f) + (1.0f / 24.0f); ser = ser * x2 + (1.0f / 6.0f); ser = ser * x2 + 0.5f; ser = ser * x2 + 1.0f; ser = ser * (-x2);
;                         f32x2 em = ser;
;                         if (__builtin_expect(__builtin_amdgcn_ballot_w64(x2.x <= -0.25f || x2.y <= -0.25f) != 0ull, 0)) {
;                             em.x = (x2.x > -0.25f) ? ser.x : (1.0f - fexp(x2.x)); em.y = (x2.y > -0.25f) ? ser.y : (1.0f - fexp(x2.y)); }
;                         const unsigned wv = xw[2 * n + jp];
;                         f32x2 sq; sq.x = __builtin_amdgcn_sqrtf(em.x); sq.y = __builtin_amdgcn_sqrtf(em.y);
;                         const f32x2 b2 = sq * ig * (f32x2){bf_lo(wv), bf_hi(wv)};
;                         bt[4 * n + 2 * jp] = b2.x; bt[4 * n + 2 * jp + 1] = b2.y; }
;                 u32x4 w; w.x = cvt_pk_bf16(bt[0], bt[1]); w.y = cvt_pk_bf16(bt[2], bt[3]); w.z = cvt_pk_bf16(bt[4], bt[5]); w.w = cvt_pk_bf16(bt[6], bt[7]);
;                 *(u32x4*)(BT + off) = w; }
	v_lshlrev_b32_e32 v196, 16, v144
	v_and_b32_e32 v197, 0xffff0000, v144
	v_lshlrev_b32_e32 v198, 16, v145
	v_and_b32_e32 v199, 0xffff0000, v145
	v_lshlrev_b32_e32 v200, 16, v146
	v_and_b32_e32 v201, 0xffff0000, v146
	v_lshlrev_b32_e32 v202, 16, v147
	v_and_b32_e32 v203, 0xffff0000, v147
	v_pk_mul_f32 v[188:189], v[188:189], v[180:181]
	v_pk_mul_f32 v[190:191], v[190:191], v[182:183]
	v_pk_mul_f32 v[192:193], v[192:193], v[184:185]
	v_pk_mul_f32 v[194:195], v[194:195], v[186:187]
	v_pk_mul_f32 v[188:189], v[188:189], v[196:197]
	v_pk_mul_f32 v[190:191], v[190:191], v[198:199]
	v_pk_mul_f32 v[192:193], v[192:193], v[200:201]
	v_pk_mul_f32 v[194:195], v[194:195], v[202:203]
	v_cvt_pk_bf16_f32 v208, v188, v189
	v_cvt_pk_bf16_f32 v209, v190, v191
	v_cvt_pk_bf16_f32 v210, v192, v193
	v_cvt_pk_bf16_f32 v211, v194, v195
	global_store_dwordx4 v172, v[208:211], s[10:11] nt
	v_pk_fma_f32 v[216:217], v[228:229], v[216:217], v[188:189]
	v_pk_fma_f32 v[218:219], v[230:231], v[218:219], v[190:191]
	v_pk_fma_f32 v[240:241], v[232:233], v[240:241], v[192:193]
	v_pk_fma_f32 v[242:243], v[234:235], v[242:243], v[194:195]
	v_pk_mul_f32 v[58:59], v[58:59], v[228:229]
	v_pk_mul_f32 v[60:61], v[60:61], v[230:231]
	v_pk_mul_f32 v[66:67], v[66:67], v[232:233]
	v_pk_mul_f32 v[68:69], v[68:69], v[234:235]
	v_pk_add_f32 v[204:205], v[204:205], v[122:123]
	v_pk_add_f32 v[206:207], v[206:207], v[124:125]
	v_pk_add_f32 v[220:221], v[220:221], v[118:119]
	v_pk_add_f32 v[222:223], v[222:223], v[120:121]
	v_pk_mul_f32 v[180:181], v[34:35], s[74:75] op_sel_hi:[1,0]
	v_pk_mul_f32 v[182:183], v[36:37], s[74:75] op_sel_hi:[1,0]
	v_pk_mul_f32 v[184:185], v[38:39], s[74:75] op_sel_hi:[1,0]
	v_pk_mul_f32 v[186:187], v[40:41], s[74:75] op_sel_hi:[1,0]
	v_exp_f32_e32 v180, v180
	v_exp_f32_e32 v181, v181
	v_exp_f32_e32 v182, v182
	v_exp_f32_e32 v183, v183
	v_exp_f32_e32 v184, v184
	v_exp_f32_e32 v185, v185
	v_exp_f32_e32 v186, v186
	v_exp_f32_e32 v187, v187
	v_pk_fma_f32 v[188:189], v[114:115], s[24:25], v[236:237] op_sel_hi:[1,0,0]
	v_pk_fma_f32 v[190:191], v[116:117], s[24:25], v[236:237] op_sel_hi:[1,0,0]
	v_pk_fma_f32 v[192:193], v[106:107], s[24:25], v[236:237] op_sel_hi:[1,0,0]
	v_pk_fma_f32 v[194:195], v[108:109], s[24:25], v[236:237] op_sel_hi:[1,0,0]
	v_pk_add_f32 v[180:181], v[180:181], 1.0 op_sel_hi:[1,0]
	v_pk_add_f32 v[182:183], v[182:183], 1.0 op_sel_hi:[1,0]
	v_pk_add_f32 v[184:185], v[184:185], 1.0 op_sel_hi:[1,0]
	v_pk_add_f32 v[186:187], v[186:187], 1.0 op_sel_hi:[1,0]
	v_rcp_f32_e32 v180, v180
	v_rcp_f32_e32 v181, v181
	v_rcp_f32_e32 v182, v182
	v_rcp_f32_e32 v183, v183
	v_rcp_f32_e32 v184, v184
	v_rcp_f32_e32 v185, v185
	v_rcp_f32_e32 v186, v186
	v_rcp_f32_e32 v187, v187
	v_pk_fma_f32 v[188:189], v[114:115], v[188:189], s[22:23] op_sel_hi:[1,1,0]
	v_pk_fma_f32 v[190:191], v[116:117], v[190:191], s[22:23] op_sel_hi:[1,1,0]
	v_pk_fma_f32 v[192:193], v[106:107], v[192:193], s[22:23] op_sel_hi:[1,1,0]
	v_pk_fma_f32 v[194:195], v[108:109], v[194:195], s[22:23] op_sel_hi:[1,1,0]
	v_pk_fma_f32 v[188:189], v[114:115], v[188:189], -2.0 op_sel_hi:[1,1,0]
	v_pk_fma_f32 v[190:191], v[116:117], v[190:191], -2.0 op_sel_hi:[1,1,0]
	v_pk_fma_f32 v[192:193], v[106:107], v[192:193], -2.0 op_sel_hi:[1,1,0]
	v_pk_fma_f32 v[194:195], v[108:109], v[194:195], -2.0 op_sel_hi:[1,1,0]
	v_pk_fma_f32 v[188:189], v[114:115], v[188:189], -2.0 op_sel_hi:[1,1,0]
	v_pk_fma_f32 v[190:191], v[116:117], v[190:191], -2.0 op_sel_hi:[1,1,0]
	v_pk_fma_f32 v[192:193], v[106:107], v[192:193], -2.0 op_sel_hi:[1,1,0]
	v_pk_fma_f32 v[194:195], v[108:109], v[194:195], -2.0 op_sel_hi:[1,1,0]
	v_pk_mul_f32 v[188:189], v[114:115], v[188:189]
	v_pk_mul_f32 v[190:191], v[116:117], v[190:191]
	v_pk_mul_f32 v[192:193], v[106:107], v[192:193]
	v_pk_mul_f32 v[194:195], v[108:109], v[194:195]
	v_mul_f32_e32 v196, s17, v114
	v_mul_f32_e32 v197, s17, v115
	v_mul_f32_e32 v198, s17, v116
	v_mul_f32_e32 v199, s17, v117
	v_mul_f32_e32 v200, s17, v106
	v_mul_f32_e32 v201, s17, v107
	v_mul_f32_e32 v202, s17, v108
	v_mul_f32_e32 v203, s17, v109
	v_exp_f32_e32 v196, v196
	v_exp_f32_e32 v197, v197
	v_exp_f32_e32 v198, v198
	v_exp_f32_e32 v199, v199
	v_exp_f32_e32 v200, v200
	v_exp_f32_e32 v201, v201
	v_exp_f32_e32 v202, v202
	v_exp_f32_e32 v203, v203
	v_pk_add_f32 v[196:197], v[196:197], 1.0 op_sel_hi:[1,0] neg_lo:[1,0] neg_hi:[1,0]
	v_pk_add_f32 v[198:199], v[198:199], 1.0 op_sel_hi:[1,0] neg_lo:[1,0] neg_hi:[1,0]
	v_pk_add_f32 v[200:201], v[200:201], 1.0 op_sel_hi:[1,0] neg_lo:[1,0] neg_hi:[1,0]
	v_pk_add_f32 v[202:203], v[202:203], 1.0 op_sel_hi:[1,0] neg_lo:[1,0] neg_hi:[1,0]
	v_cmp_lt_f32_e32 vcc, s13, v114
	s_nop 1
	v_cndmask_b32_e32 v188, v196, v188, vcc
	v_cmp_lt_f32_e32 vcc, s13, v115
	s_nop 1
	v_cndmask_b32_e32 v189, v197, v189, vcc
	v_cmp_lt_f32_e32 vcc, s13, v116
	s_nop 1
	v_cndmask_b32_e32 v190, v198, v190, vcc
	v_cmp_lt_f32_e32 vcc, s13, v117
	s_nop 1
	v_cndmask_b32_e32 v191, v199, v191, vcc
	v_cmp_lt_f32_e32 vcc, s13, v106
	s_nop 1
	v_cndmask_b32_e32 v192, v200, v192, vcc
	v_cmp_lt_f32_e32 vcc, s13, v107
	s_nop 1
	v_cndmask_b32_e32 v193, v201, v193, vcc
	v_cmp_lt_f32_e32 vcc, s13, v108
	s_nop 1
	v_cndmask_b32_e32 v194, v202, v194, vcc
	v_cmp_lt_f32_e32 vcc, s13, v109
	s_nop 1
	v_cndmask_b32_e32 v195, v203, v195, vcc
	v_pk_mul_f32 v[228:229], v[114:115], s[74:75] op_sel_hi:[1,0] neg_lo:[0,1] neg_hi:[0,1]
	v_pk_mul_f32 v[230:231], v[116:117], s[74:75] op_sel_hi:[1,0] neg_lo:[0,1] neg_hi:[0,1]
	v_pk_mul_f32 v[232:233], v[106:107], s[74:75] op_sel_hi:[1,0] neg_lo:[0,1] neg_hi:[0,1]
	v_pk_mul_f32 v[234:235], v[108:109], s[74:75] op_sel_hi:[1,0] neg_lo:[0,1] neg_hi:[0,1]
	v_sqrt_f32_e32 v188, v188
	v_sqrt_f32_e32 v189, v189
	v_sqrt_f32_e32 v190, v190
	v_sqrt_f32_e32 v191, v191
	v_sqrt_f32_e32 v192, v192
	v_sqrt_f32_e32 v193, v193
	v_sqrt_f32_e32 v194, v194
	v_sqrt_f32_e32 v195, v195
	v_exp_f32_e32 v228, v228
	v_exp_f32_e32 v229, v229
	v_exp_f32_e32 v230, v230
	v_exp_f32_e32 v231, v231
	v_exp_f32_e32 v232, v232
	v_exp_f32_e32 v233, v233
	v_exp_f32_e32 v234, v234
	v_exp_f32_e32 v235, v235
	s_waitcnt vmcnt(15)
; __device__ __forceinline__ float bf_lo(unsigned w) { return __uint_as_float(w << 16); }
;     __device__ __forceinline__ void operator()(AccMut acc, const Unit& u, int sw) const {
;     ...
;                         const f32x2 z = (f32x2){acc[ai][1][m][n][2 * jp], acc[ai][1][m][n][2 * jp + 1]} * (-1.44269504f);
;                         f32x2 e; e.x = __builtin_amdgcn_exp2f(z.x); e.y = __builtin_amdgcn_exp2f(z.y); e = e + 1.0f;
;                         f32x2 ig; ig.x = __builtin_amdgcn_rcpf(e.x); ig.y = __builtin_amdgcn_rcpf(e.y);
;                         const f32x2 x2 = (f32x2){acc[ai][0][m][n][2 * jp], acc[ai][0][m][n][2 * jp + 1]} * 2.0f;
;                         f32x2 ser = x2 * (1.0f / 120.0f) + (1.0f / 24.0f); ser = ser * x2 + (1.0f / 6.0f); ser = ser * x2 + 0.5f; ser = ser * x2 + 1.0f; ser = ser * (-x2);
;                         f32x2 em = ser;
;                         if (__builtin_expect(__builtin_amdgcn_ballot_w64(x2.x <= -0.25f || x2.y <= -0.25f) != 0ull, 0)) {
;                             em.x = (x2.x > -0.25f) ? ser.x : (1.0f - fexp(x2.x)); em.y = (x2.y > -0.25f) ? ser.y : (1.0f - fexp(x2.y)); }
;                         const unsigned wv = xw[2 * n + jp];
;                         f32x2 sq; sq.x = __builtin_amdgcn_sqrtf(em.x); sq.y = __builtin_amdgcn_sqrtf(em.y);
;                         const f32x2 b2 = sq * ig * (f32x2){bf_lo(wv), bf_hi(wv)};
;                         bt[4 * n + 2 * jp] = b2.x; bt[4 * n + 2 * jp + 1] = b2.y; }
;                 u32x4 w; w.x = cvt_pk_bf16(bt[0], bt[1]); w.y = cvt_pk_bf16(bt[2], bt[3]); w.z = cvt_pk_bf16(bt[4], bt[5]); w.w = cvt_pk_bf16(bt[6], bt[7]);
;                 *(u32x4*)(BT + off) = w; }
; __device__ __forceinline__ void scan1_phase(const bf16_t* LA, const bf16_t* BT, int sw, View vw) {
;     ...
;             for (int i = 0; i < 8; ++i) {
;                 const float l0 = bf_lo(lw[i].x), l1 = bf_hi(lw[i].x), l2 = bf_lo(lw[i].y), l3 = bf_hi(lw[i].y);
;                 S[0] += l0; S[1] += l1; S[2] += l2; S[3] += l3;
;                 Hc[0] = fexp(l0) * Hc[0] + bf_lo(bw[i].x); Hc[1] = fexp(l1) * Hc[1] + bf_hi(bw[i].x); Hc[2] = fexp(l2) * Hc[2] + bf_lo(bw[i].y); Hc[3] = fexp(l3) * Hc[3] + bf_hi(bw[i].y); }
;         }
;         *(f32x4*)(CP + (size_t)bq * E + 4 * quad) = (f32x4){S[0], S[1], S[2], S[3]};
;         *(f32x4*)(CH + (size_t)bq * E + 4 * quad) = (f32x4){Hc[0], Hc[1], Hc[2], Hc[3]};
	v_lshlrev_b32_e32 v196, 16, v148
	v_and_b32_e32 v197, 0xffff0000, v148
	v_lshlrev_b32_e32 v198, 16, v149
	v_and_b32_e32 v199, 0xffff0000, v149
	v_lshlrev_b32_e32 v200, 16, v150
	v_and_b32_e32 v201, 0xffff0000, v150
	v_lshlrev_b32_e32 v202, 16, v151
	v_and_b32_e32 v203, 0xffff0000, v151
	v_pk_mul_f32 v[188:189], v[188:189], v[180:181]
	v_pk_mul_f32 v[190:191], v[190:191], v[182:183]
	v_pk_mul_f32 v[192:193], v[192:193], v[184:185]
	v_pk_mul_f32 v[194:195], v[194:195], v[186:187]
	v_pk_mul_f32 v[188:189], v[188:189], v[196:197]
	v_pk_mul_f32 v[190:191], v[190:191], v[198:199]
	v_pk_mul_f32 v[192:193], v[192:193], v[200:201]
	v_pk_mul_f32 v[194:195], v[194:195], v[202:203]
	v_cvt_pk_bf16_f32 v212, v188, v189
	v_cvt_pk_bf16_f32 v213, v190, v191
	v_cvt_pk_bf16_f32 v214, v192, v193
	v_cvt_pk_bf16_f32 v215, v194, v195
	global_store_dwordx4 v173, v[212:215], s[10:11] nt
	v_pk_fma_f32 v[216:217], v[228:229], v[216:217], v[188:189]
	v_pk_fma_f32 v[218:219], v[230:231], v[218:219], v[190:191]
	v_pk_fma_f32 v[240:241], v[232:233], v[240:241], v[192:193]
	v_pk_fma_f32 v[242:243], v[234:235], v[242:243], v[194:195]
	v_pk_mul_f32 v[58:59], v[58:59], v[228:229]
	v_pk_mul_f32 v[60:61], v[60:61], v[230:231]
	v_pk_mul_f32 v[66:67], v[66:67], v[232:233]
	v_pk_mul_f32 v[68:69], v[68:69], v[234:235]
	v_pk_add_f32 v[204:205], v[204:205], v[114:115]
	v_pk_add_f32 v[206:207], v[206:207], v[116:117]
	v_pk_add_f32 v[220:221], v[220:221], v[106:107]
	v_pk_add_f32 v[222:223], v[222:223], v[108:109]
	v_fmac_f32_dpp v216, v216, v58 row_shr:1 row_mask:0xf bank_mask:0xf
	v_fmac_f32_dpp v217, v217, v59 row_shr:1 row_mask:0xf bank_mask:0xf
	v_fmac_f32_dpp v218, v218, v60 row_shr:1 row_mask:0xf bank_mask:0xf
	v_fmac_f32_dpp v219, v219, v61 row_shr:1 row_mask:0xf bank_mask:0xf
	v_fmac_f32_dpp v240, v240, v66 row_shr:1 row_mask:0xf bank_mask:0xf
	v_fmac_f32_dpp v241, v241, v67 row_shr:1 row_mask:0xf bank_mask:0xf
	v_fmac_f32_dpp v242, v242, v68 row_shr:1 row_mask:0xf bank_mask:0xf
	v_fmac_f32_dpp v243, v243, v69 row_shr:1 row_mask:0xf bank_mask:0xf
	v_mul_f32_dpp v58, v58, v58 row_shr:1 row_mask:0xf bank_mask:0xf
	v_mul_f32_dpp v59, v59, v59 row_shr:1 row_mask:0xf bank_mask:0xf
	v_mul_f32_dpp v60, v60, v60 row_shr:1 row_mask:0xf bank_mask:0xf
	v_mul_f32_dpp v61, v61, v61 row_shr:1 row_mask:0xf bank_mask:0xf
	v_mul_f32_dpp v66, v66, v66 row_shr:1 row_mask:0xf bank_mask:0xf
	v_mul_f32_dpp v67, v67, v67 row_shr:1 row_mask:0xf bank_mask:0xf
	v_mul_f32_dpp v68, v68, v68 row_shr:1 row_mask:0xf bank_mask:0xf
	v_mul_f32_dpp v69, v69, v69 row_shr:1 row_mask:0xf bank_mask:0xf
	v_add_f32_dpp v204, v204, v204 row_shr:1 row_mask:0xf bank_mask:0xf
	v_add_f32_dpp v205, v205, v205 row_shr:1 row_mask:0xf bank_mask:0xf
	v_add_f32_dpp v206, v206, v206 row_shr:1 row_mask:0xf bank_mask:0xf
	v_add_f32_dpp v207, v207, v207 row_shr:1 row_mask:0xf bank_mask:0xf
	v_add_f32_dpp v220, v220, v220 row_shr:1 row_mask:0xf bank_mask:0xf
	v_add_f32_dpp v221, v221, v221 row_shr:1 row_mask:0xf bank_mask:0xf
	v_add_f32_dpp v222, v222, v222 row_shr:1 row_mask:0xf bank_mask:0xf
	v_add_f32_dpp v223, v223, v223 row_shr:1 row_mask:0xf bank_mask:0xf
	v_fmac_f32_dpp v216, v216, v58 row_shr:2 row_mask:0xf bank_mask:0xf
	v_fmac_f32_dpp v217, v217, v59 row_shr:2 row_mask:0xf bank_mask:0xf
	v_fmac_f32_dpp v218, v218, v60 row_shr:2 row_mask:0xf bank_mask:0xf
	v_fmac_f32_dpp v219, v219, v61 row_shr:2 row_mask:0xf bank_mask:0xf
	v_fmac_f32_dpp v240, v240, v66 row_shr:2 row_mask:0xf bank_mask:0xf
	v_fmac_f32_dpp v241, v241, v67 row_shr:2 row_mask:0xf bank_mask:0xf
	v_fmac_f32_dpp v242, v242, v68 row_shr:2 row_mask:0xf bank_mask:0xf
	v_fmac_f32_dpp v243, v243, v69 row_shr:2 row_mask:0xf bank_mask:0xf
	v_mul_f32_dpp v58, v58, v58 row_shr:2 row_mask:0xf bank_mask:0xf
	v_mul_f32_dpp v59, v59, v59 row_shr:2 row_mask:0xf bank_mask:0xf
	v_mul_f32_dpp v60, v60, v60 row_shr:2 row_mask:0xf bank_mask:0xf
	v_mul_f32_dpp v61, v61, v61 row_shr:2 row_mask:0xf bank_mask:0xf
	v_mul_f32_dpp v66, v66, v66 row_shr:2 row_mask:0xf bank_mask:0xf
	v_mul_f32_dpp v67, v67, v67 row_shr:2 row_mask:0xf bank_mask:0xf
	v_mul_f32_dpp v68, v68, v68 row_shr:2 row_mask:0xf bank_mask:0xf
	v_mul_f32_dpp v69, v69, v69 row_shr:2 row_mask:0xf bank_mask:0xf
	v_add_f32_dpp v204, v204, v204 row_shr:2 row_mask:0xf bank_mask:0xf
	v_add_f32_dpp v205, v205, v205 row_shr:2 row_mask:0xf bank_mask:0xf
	v_add_f32_dpp v206, v206, v206 row_shr:2 row_mask:0xf bank_mask:0xf
	v_add_f32_dpp v207, v207, v207 row_shr:2 row_mask:0xf bank_mask:0xf
	v_add_f32_dpp v220, v220, v220 row_shr:2 row_mask:0xf bank_mask:0xf
	v_add_f32_dpp v221, v221, v221 row_shr:2 row_mask:0xf bank_mask:0xf
	v_add_f32_dpp v222, v222, v222 row_shr:2 row_mask:0xf bank_mask:0xf
	v_add_f32_dpp v223, v223, v223 row_shr:2 row_mask:0xf bank_mask:0xf
	v_fmac_f32_dpp v216, v216, v58 row_shr:4 row_mask:0xf bank_mask:0xf
	v_fmac_f32_dpp v217, v217, v59 row_shr:4 row_mask:0xf bank_mask:0xf
	v_fmac_f32_dpp v218, v218, v60 row_shr:4 row_mask:0xf bank_mask:0xf
	v_fmac_f32_dpp v219, v219, v61 row_shr:4 row_mask:0xf bank_mask:0xf
	v_fmac_f32_dpp v240, v240, v66 row_shr:4 row_mask:0xf bank_mask:0xf
	v_fmac_f32_dpp v241, v241, v67 row_shr:4 row_mask:0xf bank_mask:0xf
	v_fmac_f32_dpp v242, v242, v68 row_shr:4 row_mask:0xf bank_mask:0xf
	v_fmac_f32_dpp v243, v243, v69 row_shr:4 row_mask:0xf bank_mask:0xf
	v_mul_f32_dpp v58, v58, v58 row_shr:4 row_mask:0xf bank_mask:0xf
	v_mul_f32_dpp v59, v59, v59 row_shr:4 row_mask:0xf bank_mask:0xf
	v_mul_f32_dpp v60, v60, v60 row_shr:4 row_mask:0xf bank_mask:0xf
	v_mul_f32_dpp v61, v61, v61 row_shr:4 row_mask:0xf bank_mask:0xf
	v_mul_f32_dpp v66, v66, v66 row_shr:4 row_mask:0xf bank_mask:0xf
; __device__ __forceinline__ float bf_lo(unsigned w) { return __uint_as_float(w << 16); }
; __device__ __forceinline__ float bf_hi(unsigned w) { return __uint_as_float(w & 0xffff0000u); }
; __device__ __forceinline__ float fexp(float x) { return __builtin_amdgcn_exp2f(1.44269504f * x); }
;     __device__ __forceinline__ void operator()(AccMut acc, const Unit& u, int sw) const {
;     ...
;                         const f32x2 z = (f32x2){acc[ai][1][m][n][2 * jp], acc[ai][1][m][n][2 * jp + 1]} * (-1.44269504f);
;                         f32x2 e; e.x = __builtin_amdgcn_exp2f(z.x); e.y = __builtin_amdgcn_exp2f(z.y); e = e + 1.0f;
;                         f32x2 ig; ig.x = __builtin_amdgcn_rcpf(e.x); ig.y = __builtin_amdgcn_rcpf(e.y);
;                         const f32x2 x2 = (f32x2){acc[ai][0][m][n][2 * jp], acc[ai][0][m][n][2 * jp + 1]} * 2.0f;
;                         f32x2 ser = x2 * (1.0f / 120.0f) + (1.0f / 24.0f); ser = ser * x2 + (1.0f / 6.0f); ser = ser * x2 + 0.5f; ser = ser * x2 + 1.0f; ser = ser * (-x2);
;                         f32x2 em = ser;
;                         if (__builtin_expect(__builtin_amdgcn_ballot_w64(x2.x <= -0.25f || x2.y <= -0.25f) != 0ull, 0)) {
;                             em.x = (x2.x > -0.25f) ? ser.x : (1.0f - fexp(x2.x)); em.y = (x2.y > -0.25f) ? ser.y : (1.0f - fexp(x2.y)); }
;                         const unsigned wv = xw[2 * n + jp];
;                         f32x2 sq; sq.x = __builtin_amdgcn_sqrtf(em.x); sq.y = __builtin_amdgcn_sqrtf(em.y);
; __device__ __forceinline__ void scan1_phase(const bf16_t* LA, const bf16_t* BT, int sw, View vw) {
;     ...
;             for (int i = 0; i < 8; ++i) {
;                 const float l0 = bf_lo(lw[i].x), l1 = bf_hi(lw[i].x), l2 = bf_lo(lw[i].y), l3 = bf_hi(lw[i].y);
;                 S[0] += l0; S[1] += l1; S[2] += l2; S[3] += l3;
;                 Hc[0] = fexp(l0) * Hc[0] + bf_lo(bw[i].x); Hc[1] = fexp(l1) * Hc[1] + bf_hi(bw[i].x); Hc[2] = fexp(l2) * Hc[2] + bf_lo(bw[i].y); Hc[3] = fexp(l3) * Hc[3] + bf_hi(bw[i].y); }
;         }
;         *(f32x4*)(CP + (size_t)bq * E + 4 * quad) = (f32x4){S[0], S[1], S[2], S[3]};
;         *(f32x4*)(CH + (size_t)bq * E + 4 * quad) = (f32x4){Hc[0], Hc[1], Hc[2], Hc[3]};
	v_mul_f32_dpp v67, v67, v67 row_shr:4 row_mask:0xf bank_mask:0xf
	v_mul_f32_dpp v68, v68, v68 row_shr:4 row_mask:0xf bank_mask:0xf
	v_mul_f32_dpp v69, v69, v69 row_shr:4 row_mask:0xf bank_mask:0xf
	v_add_f32_dpp v204, v204, v204 row_shr:4 row_mask:0xf bank_mask:0xf
	v_add_f32_dpp v205, v205, v205 row_shr:4 row_mask:0xf bank_mask:0xf
	v_add_f32_dpp v206, v206, v206 row_shr:4 row_mask:0xf bank_mask:0xf
	v_add_f32_dpp v207, v207, v207 row_shr:4 row_mask:0xf bank_mask:0xf
	v_add_f32_dpp v220, v220, v220 row_shr:4 row_mask:0xf bank_mask:0xf
	v_add_f32_dpp v221, v221, v221 row_shr:4 row_mask:0xf bank_mask:0xf
	v_add_f32_dpp v222, v222, v222 row_shr:4 row_mask:0xf bank_mask:0xf
	v_add_f32_dpp v223, v223, v223 row_shr:4 row_mask:0xf bank_mask:0xf
	v_fmac_f32_dpp v216, v216, v58 row_shr:8 row_mask:0xf bank_mask:0xf
	v_fmac_f32_dpp v217, v217, v59 row_shr:8 row_mask:0xf bank_mask:0xf
	v_fmac_f32_dpp v218, v218, v60 row_shr:8 row_mask:0xf bank_mask:0xf
	v_fmac_f32_dpp v219, v219, v61 row_shr:8 row_mask:0xf bank_mask:0xf
	v_fmac_f32_dpp v240, v240, v66 row_shr:8 row_mask:0xf bank_mask:0xf
	v_fmac_f32_dpp v241, v241, v67 row_shr:8 row_mask:0xf bank_mask:0xf
	v_fmac_f32_dpp v242, v242, v68 row_shr:8 row_mask:0xf bank_mask:0xf
	v_fmac_f32_dpp v243, v243, v69 row_shr:8 row_mask:0xf bank_mask:0xf
	v_add_f32_dpp v204, v204, v204 row_shr:8 row_mask:0xf bank_mask:0xf
	v_add_f32_dpp v205, v205, v205 row_shr:8 row_mask:0xf bank_mask:0xf
	v_add_f32_dpp v206, v206, v206 row_shr:8 row_mask:0xf bank_mask:0xf
	v_add_f32_dpp v207, v207, v207 row_shr:8 row_mask:0xf bank_mask:0xf
	v_add_f32_dpp v220, v220, v220 row_shr:8 row_mask:0xf bank_mask:0xf
	v_add_f32_dpp v221, v221, v221 row_shr:8 row_mask:0xf bank_mask:0xf
	v_add_f32_dpp v222, v222, v222 row_shr:8 row_mask:0xf bank_mask:0xf
	v_add_f32_dpp v223, v223, v223 row_shr:8 row_mask:0xf bank_mask:0xf
	v_mbcnt_lo_u32_b32 v180, -1, 0
	v_mbcnt_hi_u32_b32 v180, -1, v180
	v_and_b32_e32 v180, 15, v180
	v_cmp_eq_u32_e32 vcc, 15, v180
	v_add_u32_e32 v181, 0x0, v239
	v_add_u32_e32 v182, 0x400000, v239
	s_mov_b64 exec, vcc
	global_store_dwordx4 v181, v[204:207], s[26:27]
	global_store_dwordx4 v181, v[220:223], s[26:27] offset:16
	global_store_dwordx4 v182, v[216:219], s[26:27]
	global_store_dwordx4 v182, v[240:243], s[26:27] offset:16
	s_mov_b64 exec, -1
	v_pk_mul_f32 v[180:181], v[26:27], s[74:75] op_sel_hi:[1,0]
	v_pk_mul_f32 v[182:183], v[28:29], s[74:75] op_sel_hi:[1,0]
	v_pk_mul_f32 v[184:185], v[30:31], s[74:75] op_sel_hi:[1,0]
	v_pk_mul_f32 v[186:187], v[32:33], s[74:75] op_sel_hi:[1,0]
	v_exp_f32_e32 v180, v180
	v_exp_f32_e32 v181, v181
	v_exp_f32_e32 v182, v182
	v_exp_f32_e32 v183, v183
	v_exp_f32_e32 v184, v184
	v_exp_f32_e32 v185, v185
	v_exp_f32_e32 v186, v186
	v_exp_f32_e32 v187, v187
	v_pk_fma_f32 v[188:189], v[110:111], s[24:25], v[236:237] op_sel_hi:[1,0,0]
	v_pk_fma_f32 v[190:191], v[112:113], s[24:25], v[236:237] op_sel_hi:[1,0,0]
	v_pk_fma_f32 v[192:193], v[102:103], s[24:25], v[236:237] op_sel_hi:[1,0,0]
	v_pk_fma_f32 v[194:195], v[104:105], s[24:25], v[236:237] op_sel_hi:[1,0,0]
	v_pk_add_f32 v[180:181], v[180:181], 1.0 op_sel_hi:[1,0]
	v_pk_add_f32 v[182:183], v[182:183], 1.0 op_sel_hi:[1,0]
	v_pk_add_f32 v[184:185], v[184:185], 1.0 op_sel_hi:[1,0]
	v_pk_add_f32 v[186:187], v[186:187], 1.0 op_sel_hi:[1,0]
	v_rcp_f32_e32 v180, v180
	v_rcp_f32_e32 v181, v181
	v_rcp_f32_e32 v182, v182
	v_rcp_f32_e32 v183, v183
	v_rcp_f32_e32 v184, v184
	v_rcp_f32_e32 v185, v185
	v_rcp_f32_e32 v186, v186
	v_rcp_f32_e32 v187, v187
	v_pk_fma_f32 v[188:189], v[110:111], v[188:189], s[22:23] op_sel_hi:[1,1,0]
	v_pk_fma_f32 v[190:191], v[112:113], v[190:191], s[22:23] op_sel_hi:[1,1,0]
	v_pk_fma_f32 v[192:193], v[102:103], v[192:193], s[22:23] op_sel_hi:[1,1,0]
	v_pk_fma_f32 v[194:195], v[104:105], v[194:195], s[22:23] op_sel_hi:[1,1,0]
	v_pk_fma_f32 v[188:189], v[110:111], v[188:189], -2.0 op_sel_hi:[1,1,0]
	v_pk_fma_f32 v[190:191], v[112:113], v[190:191], -2.0 op_sel_hi:[1,1,0]
	v_pk_fma_f32 v[192:193], v[102:103], v[192:193], -2.0 op_sel_hi:[1,1,0]
	v_pk_fma_f32 v[194:195], v[104:105], v[194:195], -2.0 op_sel_hi:[1,1,0]
	v_pk_fma_f32 v[188:189], v[110:111], v[188:189], -2.0 op_sel_hi:[1,1,0]
	v_pk_fma_f32 v[190:191], v[112:113], v[190:191], -2.0 op_sel_hi:[1,1,0]
	v_pk_fma_f32 v[192:193], v[102:103], v[192:193], -2.0 op_sel_hi:[1,1,0]
	v_pk_fma_f32 v[194:195], v[104:105], v[194:195], -2.0 op_sel_hi:[1,1,0]
	v_pk_mul_f32 v[188:189], v[110:111], v[188:189]
	v_pk_mul_f32 v[190:191], v[112:113], v[190:191]
	v_pk_mul_f32 v[192:193], v[102:103], v[192:193]
	v_pk_mul_f32 v[194:195], v[104:105], v[194:195]
	v_mul_f32_e32 v196, s17, v110
	v_mul_f32_e32 v197, s17, v111
	v_mul_f32_e32 v198, s17, v112
	v_mul_f32_e32 v199, s17, v113
	v_mul_f32_e32 v200, s17, v102
	v_mul_f32_e32 v201, s17, v103
	v_mul_f32_e32 v202, s17, v104
	v_mul_f32_e32 v203, s17, v105
	v_exp_f32_e32 v196, v196
	v_exp_f32_e32 v197, v197
	v_exp_f32_e32 v198, v198
	v_exp_f32_e32 v199, v199
	v_exp_f32_e32 v200, v200
	v_exp_f32_e32 v201, v201
	v_exp_f32_e32 v202, v202
	v_exp_f32_e32 v203, v203
	v_pk_add_f32 v[196:197], v[196:197], 1.0 op_sel_hi:[1,0] neg_lo:[1,0] neg_hi:[1,0]
	v_pk_add_f32 v[198:199], v[198:199], 1.0 op_sel_hi:[1,0] neg_lo:[1,0] neg_hi:[1,0]
	v_pk_add_f32 v[200:201], v[200:201], 1.0 op_sel_hi:[1,0] neg_lo:[1,0] neg_hi:[1,0]
	v_pk_add_f32 v[202:203], v[202:203], 1.0 op_sel_hi:[1,0] neg_lo:[1,0] neg_hi:[1,0]
	v_cmp_lt_f32_e32 vcc, s13, v110
	s_nop 1
	v_cndmask_b32_e32 v188, v196, v188, vcc
	v_cmp_lt_f32_e32 vcc, s13, v111
	s_nop 1
	v_cndmask_b32_e32 v189, v197, v189, vcc
	v_cmp_lt_f32_e32 vcc, s13, v112
	s_nop 1
	v_cndmask_b32_e32 v190, v198, v190, vcc
	v_cmp_lt_f32_e32 vcc, s13, v113
	s_nop 1
	v_cndmask_b32_e32 v191, v199, v191, vcc
	v_cmp_lt_f32_e32 vcc, s13, v102
	s_nop 1
	v_cndmask_b32_e32 v192, v200, v192, vcc
	v_cmp_lt_f32_e32 vcc, s13, v103
	s_nop 1
	v_cndmask_b32_e32 v193, v201, v193, vcc
	v_cmp_lt_f32_e32 vcc, s13, v104
	s_nop 1
	v_cndmask_b32_e32 v194, v202, v194, vcc
	v_cmp_lt_f32_e32 vcc, s13, v105
	s_nop 1
	v_cndmask_b32_e32 v195, v203, v195, vcc
	v_pk_mul_f32 v[228:229], v[110:111], s[74:75] op_sel_hi:[1,0] neg_lo:[0,1] neg_hi:[0,1]
	v_pk_mul_f32 v[230:231], v[112:113], s[74:75] op_sel_hi:[1,0] neg_lo:[0,1] neg_hi:[0,1]
	v_pk_mul_f32 v[232:233], v[102:103], s[74:75] op_sel_hi:[1,0] neg_lo:[0,1] neg_hi:[0,1]
	v_pk_mul_f32 v[234:235], v[104:105], s[74:75] op_sel_hi:[1,0] neg_lo:[0,1] neg_hi:[0,1]
	v_sqrt_f32_e32 v188, v188
	v_sqrt_f32_e32 v189, v189
	v_sqrt_f32_e32 v190, v190
	v_sqrt_f32_e32 v191, v191
	v_sqrt_f32_e32 v192, v192
	v_sqrt_f32_e32 v193, v193
	v_sqrt_f32_e32 v194, v194
	v_sqrt_f32_e32 v195, v195
	v_exp_f32_e32 v26, v228
	v_exp_f32_e32 v27, v229
	v_exp_f32_e32 v28, v230
	v_exp_f32_e32 v29, v231
	v_exp_f32_e32 v30, v232
	v_exp_f32_e32 v31, v233
	v_exp_f32_e32 v32, v234
	v_exp_f32_e32 v33, v235
	s_waitcnt vmcnt(19)
; __device__ __forceinline__ unsigned cvt_pk_bf16(float lo, float hi) { unsigned r; asm volatile("v_cvt_pk_bf16_f32 %0, %1, %2" : "=v"(r) : "v"(lo), "v"(hi)); return r; }
; __device__ __forceinline__ float bf_lo(unsigned w) { return __uint_as_float(w << 16); }
; __device__ __forceinline__ float bf_hi(unsigned w) { return __uint_as_float(w & 0xffff0000u); }
; __device__ __forceinline__ float fexp(float x) { return __builtin_amdgcn_exp2f(1.44269504f * x); }
;     __device__ __forceinline__ void operator()(AccMut acc, const Unit& u, int sw) const {
;     ...
;                         const f32x2 z = (f32x2){acc[ai][1][m][n][2 * jp], acc[ai][1][m][n][2 * jp + 1]} * (-1.44269504f);
;                         f32x2 e; e.x = __builtin_amdgcn_exp2f(z.x); e.y = __builtin_amdgcn_exp2f(z.y); e = e + 1.0f;
;                         f32x2 ig; ig.x = __builtin_amdgcn_rcpf(e.x); ig.y = __builtin_amdgcn_rcpf(e.y);
;                         const f32x2 x2 = (f32x2){acc[ai][0][m][n][2 * jp], acc[ai][0][m][n][2 * jp + 1]} * 2.0f;
;                         f32x2 ser = x2 * (1.0f / 120.0f) + (1.0f / 24.0f); ser = ser * x2 + (1.0f / 6.0f); ser = ser * x2 + 0.5f; ser = ser * x2 + 1.0f; ser = ser * (-x2);
;                         f32x2 em = ser;
;                         if (__builtin_expect(__builtin_amdgcn_ballot_w64(x2.x <= -0.25f || x2.y <= -0.25f) != 0ull, 0)) {
;                             em.x = (x2.x > -0.25f) ? ser.x : (1.0f - fexp(x2.x)); em.y = (x2.y > -0.25f) ? ser.y : (1.0f - fexp(x2.y)); }
;                         const unsigned wv = xw[2 * n + jp];
;                         f32x2 sq; sq.x = __builtin_amdgcn_sqrtf(em.x); sq.y = __builtin_amdgcn_sqrtf(em.y);
;                         const f32x2 b2 = sq * ig * (f32x2){bf_lo(wv), bf_hi(wv)};
;                         bt[4 * n + 2 * jp] = b2.x; bt[4 * n + 2 * jp + 1] = b2.y; }
;                 u32x4 w; w.x = cvt_pk_bf16(bt[0], bt[1]); w.y = cvt_pk_bf16(bt[2], bt[3]); w.z = cvt_pk_bf16(bt[4], bt[5]); w.w = cvt_pk_bf16(bt[6], bt[7]);
;                 *(u32x4*)(BT + off) = w; }
	v_lshlrev_b32_e32 v196, 16, v152
	v_and_b32_e32 v197, 0xffff0000, v152
	v_lshlrev_b32_e32 v198, 16, v153
	v_and_b32_e32 v199, 0xffff0000, v153
	v_lshlrev_b32_e32 v200, 16, v154
	v_and_b32_e32 v201, 0xffff0000, v154
	v_lshlrev_b32_e32 v202, 16, v155
	v_and_b32_e32 v203, 0xffff0000, v155
	v_pk_mul_f32 v[188:189], v[188:189], v[180:181]
	v_pk_mul_f32 v[190:191], v[190:191], v[182:183]
	v_pk_mul_f32 v[192:193], v[192:193], v[184:185]
	v_pk_mul_f32 v[194:195], v[194:195], v[186:187]
	v_pk_mul_f32 v[216:217], v[188:189], v[196:197]
	v_pk_mul_f32 v[218:219], v[190:191], v[198:199]
	v_pk_mul_f32 v[240:241], v[192:193], v[200:201]
	v_pk_mul_f32 v[242:243], v[194:195], v[202:203]
	v_cvt_pk_bf16_f32 v208, v216, v217
	v_cvt_pk_bf16_f32 v209, v218, v219
	v_cvt_pk_bf16_f32 v210, v240, v241
	v_cvt_pk_bf16_f32 v211, v242, v243
	global_store_dwordx4 v176, v[208:211], s[10:11] nt
	v_pk_mul_f32 v[180:181], v[18:19], s[74:75] op_sel_hi:[1,0]
	v_pk_mul_f32 v[182:183], v[20:21], s[74:75] op_sel_hi:[1,0]
	v_pk_mul_f32 v[184:185], v[22:23], s[74:75] op_sel_hi:[1,0]
	v_pk_mul_f32 v[186:187], v[24:25], s[74:75] op_sel_hi:[1,0]
	v_exp_f32_e32 v180, v180
	v_exp_f32_e32 v181, v181
	v_exp_f32_e32 v182, v182
	v_exp_f32_e32 v183, v183
	v_exp_f32_e32 v184, v184
	v_exp_f32_e32 v185, v185
	v_exp_f32_e32 v186, v186
	v_exp_f32_e32 v187, v187
	v_pk_fma_f32 v[188:189], v[98:99], s[24:25], v[236:237] op_sel_hi:[1,0,0]
	v_pk_fma_f32 v[190:191], v[100:101], s[24:25], v[236:237] op_sel_hi:[1,0,0]
	v_pk_fma_f32 v[192:193], v[94:95], s[24:25], v[236:237] op_sel_hi:[1,0,0]
	v_pk_fma_f32 v[194:195], v[96:97], s[24:25], v[236:237] op_sel_hi:[1,0,0]
	v_pk_add_f32 v[180:181], v[180:181], 1.0 op_sel_hi:[1,0]
	v_pk_add_f32 v[182:183], v[182:183], 1.0 op_sel_hi:[1,0]
	v_pk_add_f32 v[184:185], v[184:185], 1.0 op_sel_hi:[1,0]
	v_pk_add_f32 v[186:187], v[186:187], 1.0 op_sel_hi:[1,0]
	v_rcp_f32_e32 v180, v180
	v_rcp_f32_e32 v181, v181
	v_rcp_f32_e32 v182, v182
	v_rcp_f32_e32 v183, v183
	v_rcp_f32_e32 v184, v184
	v_rcp_f32_e32 v185, v185
	v_rcp_f32_e32 v186, v186
	v_rcp_f32_e32 v187, v187
	v_pk_fma_f32 v[188:189], v[98:99], v[188:189], s[22:23] op_sel_hi:[1,1,0]
	v_pk_fma_f32 v[190:191], v[100:101], v[190:191], s[22:23] op_sel_hi:[1,1,0]
	v_pk_fma_f32 v[192:193], v[94:95], v[192:193], s[22:23] op_sel_hi:[1,1,0]
	v_pk_fma_f32 v[194:195], v[96:97], v[194:195], s[22:23] op_sel_hi:[1,1,0]
	v_pk_fma_f32 v[188:189], v[98:99], v[188:189], -2.0 op_sel_hi:[1,1,0]
	v_pk_fma_f32 v[190:191], v[100:101], v[190:191], -2.0 op_sel_hi:[1,1,0]
	v_pk_fma_f32 v[192:193], v[94:95], v[192:193], -2.0 op_sel_hi:[1,1,0]
	v_pk_fma_f32 v[194:195], v[96:97], v[194:195], -2.0 op_sel_hi:[1,1,0]
	v_pk_fma_f32 v[188:189], v[98:99], v[188:189], -2.0 op_sel_hi:[1,1,0]
	v_pk_fma_f32 v[190:191], v[100:101], v[190:191], -2.0 op_sel_hi:[1,1,0]
	v_pk_fma_f32 v[192:193], v[94:95], v[192:193], -2.0 op_sel_hi:[1,1,0]
	v_pk_fma_f32 v[194:195], v[96:97], v[194:195], -2.0 op_sel_hi:[1,1,0]
	v_pk_mul_f32 v[188:189], v[98:99], v[188:189]
	v_pk_mul_f32 v[190:191], v[100:101], v[190:191]
	v_pk_mul_f32 v[192:193], v[94:95], v[192:193]
	v_pk_mul_f32 v[194:195], v[96:97], v[194:195]
	v_mul_f32_e32 v196, s17, v98
	v_mul_f32_e32 v197, s17, v99
	v_mul_f32_e32 v198, s17, v100
	v_mul_f32_e32 v199, s17, v101
	v_mul_f32_e32 v200, s17, v94
	v_mul_f32_e32 v201, s17, v95
	v_mul_f32_e32 v202, s17, v96
	v_mul_f32_e32 v203, s17, v97
	v_exp_f32_e32 v196, v196
	v_exp_f32_e32 v197, v197
	v_exp_f32_e32 v198, v198
	v_exp_f32_e32 v199, v199
	v_exp_f32_e32 v200, v200
	v_exp_f32_e32 v201, v201
	v_exp_f32_e32 v202, v202
	v_exp_f32_e32 v203, v203
	v_pk_add_f32 v[196:197], v[196:197], 1.0 op_sel_hi:[1,0] neg_lo:[1,0] neg_hi:[1,0]
	v_pk_add_f32 v[198:199], v[198:199], 1.0 op_sel_hi:[1,0] neg_lo:[1,0] neg_hi:[1,0]
	v_pk_add_f32 v[200:201], v[200:201], 1.0 op_sel_hi:[1,0] neg_lo:[1,0] neg_hi:[1,0]
	v_pk_add_f32 v[202:203], v[202:203], 1.0 op_sel_hi:[1,0] neg_lo:[1,0] neg_hi:[1,0]
	v_cmp_lt_f32_e32 vcc, s13, v98
	s_nop 1
	v_cndmask_b32_e32 v188, v196, v188, vcc
	v_cmp_lt_f32_e32 vcc, s13, v99
	s_nop 1
	v_cndmask_b32_e32 v189, v197, v189, vcc
	v_cmp_lt_f32_e32 vcc, s13, v100
	s_nop 1
	v_cndmask_b32_e32 v190, v198, v190, vcc
	v_cmp_lt_f32_e32 vcc, s13, v101
	s_nop 1
	v_cndmask_b32_e32 v191, v199, v191, vcc
	v_cmp_lt_f32_e32 vcc, s13, v94
	s_nop 1
	v_cndmask_b32_e32 v192, v200, v192, vcc
	v_cmp_lt_f32_e32 vcc, s13, v95
	s_nop 1
	v_cndmask_b32_e32 v193, v201, v193, vcc
	v_cmp_lt_f32_e32 vcc, s13, v96
	s_nop 1
	v_cndmask_b32_e32 v194, v202, v194, vcc
	v_cmp_lt_f32_e32 vcc, s13, v97
	s_nop 1
	v_cndmask_b32_e32 v195, v203, v195, vcc
	v_pk_mul_f32 v[228:229], v[98:99], s[74:75] op_sel_hi:[1,0] neg_lo:[0,1] neg_hi:[0,1]
	v_pk_mul_f32 v[230:231], v[100:101], s[74:75] op_sel_hi:[1,0] neg_lo:[0,1] neg_hi:[0,1]
	v_pk_mul_f32 v[232:233], v[94:95], s[74:75] op_sel_hi:[1,0] neg_lo:[0,1] neg_hi:[0,1]
	v_pk_mul_f32 v[234:235], v[96:97], s[74:75] op_sel_hi:[1,0] neg_lo:[0,1] neg_hi:[0,1]
	v_sqrt_f32_e32 v188, v188
	v_sqrt_f32_e32 v189, v189
	v_sqrt_f32_e32 v190, v190
	v_sqrt_f32_e32 v191, v191
	v_sqrt_f32_e32 v192, v192
	v_sqrt_f32_e32 v193, v193
	v_sqrt_f32_e32 v194, v194
	v_sqrt_f32_e32 v195, v195
	v_exp_f32_e32 v228, v228
	v_exp_f32_e32 v229, v229
	v_exp_f32_e32 v230, v230
	v_exp_f32_e32 v231, v231
	v_exp_f32_e32 v232, v232
	v_exp_f32_e32 v233, v233
	v_exp_f32_e32 v234, v234
	v_exp_f32_e32 v235, v235
	s_waitcnt vmcnt(19)
; __device__ __forceinline__ unsigned cvt_pk_bf16(float lo, float hi) { unsigned r; asm volatile("v_cvt_pk_bf16_f32 %0, %1, %2" : "=v"(r) : "v"(lo), "v"(hi)); return r; }
; __device__ __forceinline__ float bf_lo(unsigned w) { return __uint_as_float(w << 16); }
; __device__ __forceinline__ float bf_hi(unsigned w) { return __uint_as_float(w & 0xffff0000u); }
; __device__ __forceinline__ float fexp(float x) { return __builtin_amdgcn_exp2f(1.44269504f * x); }
;     __device__ __forceinline__ void operator()(AccMut acc, const Unit& u, int sw) const {
;     ...
;                         const f32x2 z = (f32x2){acc[ai][1][m][n][2 * jp], acc[ai][1][m][n][2 * jp + 1]} * (-1.44269504f);
;                         f32x2 e; e.x = __builtin_amdgcn_exp2f(z.x); e.y = __builtin_amdgcn_exp2f(z.y); e = e + 1.0f;
;                         f32x2 ig; ig.x = __builtin_amdgcn_rcpf(e.x); ig.y = __builtin_amdgcn_rcpf(e.y);
;                         const f32x2 x2 = (f32x2){acc[ai][0][m][n][2 * jp], acc[ai][0][m][n][2 * jp + 1]} * 2.0f;
;                         f32x2 ser = x2 * (1.0f / 120.0f) + (1.0f / 24.0f); ser = ser * x2 + (1.0f / 6.0f); ser = ser * x2 + 0.5f; ser = ser * x2 + 1.0f; ser = ser * (-x2);
;                         f32x2 em = ser;
;                         if (__builtin_expect(__builtin_amdgcn_ballot_w64(x2.x <= -0.25f || x2.y <= -0.25f) != 0ull, 0)) {
;                             em.x = (x2.x > -0.25f) ? ser.x : (1.0f - fexp(x2.x)); em.y = (x2.y > -0.25f) ? ser.y : (1.0f - fexp(x2.y)); }
;                         const unsigned wv = xw[2 * n + jp];
;                         f32x2 sq; sq.x = __builtin_amdgcn_sqrtf(em.x); sq.y = __builtin_amdgcn_sqrtf(em.y);
;                         const f32x2 b2 = sq * ig * (f32x2){bf_lo(wv), bf_hi(wv)};
;                         bt[4 * n + 2 * jp] = b2.x; bt[4 * n + 2 * jp + 1] = b2.y; }
;                 u32x4 w; w.x = cvt_pk_bf16(bt[0], bt[1]); w.y = cvt_pk_bf16(bt[2], bt[3]); w.z = cvt_pk_bf16(bt[4], bt[5]); w.w = cvt_pk_bf16(bt[6], bt[7]);
;                 *(u32x4*)(BT + off) = w; }
	v_lshlrev_b32_e32 v196, 16, v156
	v_and_b32_e32 v197, 0xffff0000, v156
	v_lshlrev_b32_e32 v198, 16, v157
	v_and_b32_e32 v199, 0xffff0000, v157
	v_lshlrev_b32_e32 v200, 16, v158
	v_and_b32_e32 v201, 0xffff0000, v158
	v_lshlrev_b32_e32 v202, 16, v159
	v_and_b32_e32 v203, 0xffff0000, v159
	v_pk_mul_f32 v[188:189], v[188:189], v[180:181]
	v_pk_mul_f32 v[190:191], v[190:191], v[182:183]
	v_pk_mul_f32 v[192:193], v[192:193], v[184:185]
	v_pk_mul_f32 v[194:195], v[194:195], v[186:187]
	v_pk_mul_f32 v[188:189], v[188:189], v[196:197]
	v_pk_mul_f32 v[190:191], v[190:191], v[198:199]
	v_pk_mul_f32 v[192:193], v[192:193], v[200:201]
	v_pk_mul_f32 v[194:195], v[194:195], v[202:203]
	v_cvt_pk_bf16_f32 v212, v188, v189
	v_cvt_pk_bf16_f32 v213, v190, v191
	v_cvt_pk_bf16_f32 v214, v192, v193
	v_cvt_pk_bf16_f32 v215, v194, v195
	global_store_dwordx4 v177, v[212:215], s[10:11] nt
	v_pk_fma_f32 v[216:217], v[228:229], v[216:217], v[188:189]
	v_pk_fma_f32 v[218:219], v[230:231], v[218:219], v[190:191]
	v_pk_fma_f32 v[240:241], v[232:233], v[240:241], v[192:193]
	v_pk_fma_f32 v[242:243], v[234:235], v[242:243], v[194:195]
	v_pk_mul_f32 v[26:27], v[26:27], v[228:229]
	v_pk_mul_f32 v[28:29], v[28:29], v[230:231]
	v_pk_mul_f32 v[30:31], v[30:31], v[232:233]
	v_pk_mul_f32 v[32:33], v[32:33], v[234:235]
	v_pk_add_f32 v[110:111], v[110:111], v[98:99]
	v_pk_add_f32 v[112:113], v[112:113], v[100:101]
	v_pk_add_f32 v[102:103], v[102:103], v[94:95]
	v_pk_add_f32 v[104:105], v[104:105], v[96:97]
	v_pk_mul_f32 v[180:181], v[10:11], s[74:75] op_sel_hi:[1,0]
	v_pk_mul_f32 v[182:183], v[12:13], s[74:75] op_sel_hi:[1,0]
	v_pk_mul_f32 v[184:185], v[14:15], s[74:75] op_sel_hi:[1,0]
	v_pk_mul_f32 v[186:187], v[16:17], s[74:75] op_sel_hi:[1,0]
	v_exp_f32_e32 v180, v180
	v_exp_f32_e32 v181, v181
	v_exp_f32_e32 v182, v182
	v_exp_f32_e32 v183, v183
	v_exp_f32_e32 v184, v184
	v_exp_f32_e32 v185, v185
	v_exp_f32_e32 v186, v186
	v_exp_f32_e32 v187, v187
	v_pk_fma_f32 v[188:189], v[90:91], s[24:25], v[236:237] op_sel_hi:[1,0,0]
	v_pk_fma_f32 v[190:191], v[92:93], s[24:25], v[236:237] op_sel_hi:[1,0,0]
	v_pk_fma_f32 v[192:193], v[86:87], s[24:25], v[236:237] op_sel_hi:[1,0,0]
	v_pk_fma_f32 v[194:195], v[88:89], s[24:25], v[236:237] op_sel_hi:[1,0,0]
	v_pk_add_f32 v[180:181], v[180:181], 1.0 op_sel_hi:[1,0]
	v_pk_add_f32 v[182:183], v[182:183], 1.0 op_sel_hi:[1,0]
	v_pk_add_f32 v[184:185], v[184:185], 1.0 op_sel_hi:[1,0]
	v_pk_add_f32 v[186:187], v[186:187], 1.0 op_sel_hi:[1,0]
	v_rcp_f32_e32 v180, v180
	v_rcp_f32_e32 v181, v181
	v_rcp_f32_e32 v182, v182
	v_rcp_f32_e32 v183, v183
	v_rcp_f32_e32 v184, v184
	v_rcp_f32_e32 v185, v185
	v_rcp_f32_e32 v186, v186
	v_rcp_f32_e32 v187, v187
	v_pk_fma_f32 v[188:189], v[90:91], v[188:189], s[22:23] op_sel_hi:[1,1,0]
	v_pk_fma_f32 v[190:191], v[92:93], v[190:191], s[22:23] op_sel_hi:[1,1,0]
	v_pk_fma_f32 v[192:193], v[86:87], v[192:193], s[22:23] op_sel_hi:[1,1,0]
	v_pk_fma_f32 v[194:195], v[88:89], v[194:195], s[22:23] op_sel_hi:[1,1,0]
	v_pk_fma_f32 v[188:189], v[90:91], v[188:189], -2.0 op_sel_hi:[1,1,0]
	v_pk_fma_f32 v[190:191], v[92:93], v[190:191], -2.0 op_sel_hi:[1,1,0]
	v_pk_fma_f32 v[192:193], v[86:87], v[192:193], -2.0 op_sel_hi:[1,1,0]
	v_pk_fma_f32 v[194:195], v[88:89], v[194:195], -2.0 op_sel_hi:[1,1,0]
	v_pk_fma_f32 v[188:189], v[90:91], v[188:189], -2.0 op_sel_hi:[1,1,0]
	v_pk_fma_f32 v[190:191], v[92:93], v[190:191], -2.0 op_sel_hi:[1,1,0]
	v_pk_fma_f32 v[192:193], v[86:87], v[192:193], -2.0 op_sel_hi:[1,1,0]
	v_pk_fma_f32 v[194:195], v[88:89], v[194:195], -2.0 op_sel_hi:[1,1,0]
	v_pk_mul_f32 v[188:189], v[90:91], v[188:189]
	v_pk_mul_f32 v[190:191], v[92:93], v[190:191]
	v_pk_mul_f32 v[192:193], v[86:87], v[192:193]
	v_pk_mul_f32 v[194:195], v[88:89], v[194:195]
	v_mul_f32_e32 v196, s17, v90
	v_mul_f32_e32 v197, s17, v91
	v_mul_f32_e32 v198, s17, v92
	v_mul_f32_e32 v199, s17, v93
	v_mul_f32_e32 v200, s17, v86
	v_mul_f32_e32 v201, s17, v87
	v_mul_f32_e32 v202, s17, v88
	v_mul_f32_e32 v203, s17, v89
	v_exp_f32_e32 v196, v196
	v_exp_f32_e32 v197, v197
	v_exp_f32_e32 v198, v198
	v_exp_f32_e32 v199, v199
	v_exp_f32_e32 v200, v200
	v_exp_f32_e32 v201, v201
	v_exp_f32_e32 v202, v202
	v_exp_f32_e32 v203, v203
	v_pk_add_f32 v[196:197], v[196:197], 1.0 op_sel_hi:[1,0] neg_lo:[1,0] neg_hi:[1,0]
	v_pk_add_f32 v[198:199], v[198:199], 1.0 op_sel_hi:[1,0] neg_lo:[1,0] neg_hi:[1,0]
	v_pk_add_f32 v[200:201], v[200:201], 1.0 op_sel_hi:[1,0] neg_lo:[1,0] neg_hi:[1,0]
	v_pk_add_f32 v[202:203], v[202:203], 1.0 op_sel_hi:[1,0] neg_lo:[1,0] neg_hi:[1,0]
	v_cmp_lt_f32_e32 vcc, s13, v90
	s_nop 1
	v_cndmask_b32_e32 v188, v196, v188, vcc
	v_cmp_lt_f32_e32 vcc, s13, v91
	s_nop 1
	v_cndmask_b32_e32 v189, v197, v189, vcc
	v_cmp_lt_f32_e32 vcc, s13, v92
	s_nop 1
	v_cndmask_b32_e32 v190, v198, v190, vcc
	v_cmp_lt_f32_e32 vcc, s13, v93
	s_nop 1
	v_cndmask_b32_e32 v191, v199, v191, vcc
	v_cmp_lt_f32_e32 vcc, s13, v86
	s_nop 1
	v_cndmask_b32_e32 v192, v200, v192, vcc
	v_cmp_lt_f32_e32 vcc, s13, v87
	s_nop 1
	v_cndmask_b32_e32 v193, v201, v193, vcc
	v_cmp_lt_f32_e32 vcc, s13, v88
	s_nop 1
	v_cndmask_b32_e32 v194, v202, v194, vcc
	v_cmp_lt_f32_e32 vcc, s13, v89
	s_nop 1
	v_cndmask_b32_e32 v195, v203, v195, vcc
	v_pk_mul_f32 v[228:229], v[90:91], s[74:75] op_sel_hi:[1,0] neg_lo:[0,1] neg_hi:[0,1]
	v_pk_mul_f32 v[230:231], v[92:93], s[74:75] op_sel_hi:[1,0] neg_lo:[0,1] neg_hi:[0,1]
	v_pk_mul_f32 v[232:233], v[86:87], s[74:75] op_sel_hi:[1,0] neg_lo:[0,1] neg_hi:[0,1]
	v_pk_mul_f32 v[234:235], v[88:89], s[74:75] op_sel_hi:[1,0] neg_lo:[0,1] neg_hi:[0,1]
	v_sqrt_f32_e32 v188, v188
	v_sqrt_f32_e32 v189, v189
	v_sqrt_f32_e32 v190, v190
	v_sqrt_f32_e32 v191, v191
	v_sqrt_f32_e32 v192, v192
	v_sqrt_f32_e32 v193, v193
	v_sqrt_f32_e32 v194, v194
	v_sqrt_f32_e32 v195, v195
	v_exp_f32_e32 v228, v228
	v_exp_f32_e32 v229, v229
	v_exp_f32_e32 v230, v230
	v_exp_f32_e32 v231, v231
	v_exp_f32_e32 v232, v232
	v_exp_f32_e32 v233, v233
	v_exp_f32_e32 v234, v234
	v_exp_f32_e32 v235, v235
	s_waitcnt vmcnt(19)
; __device__ __forceinline__ unsigned cvt_pk_bf16(float lo, float hi) { unsigned r; asm volatile("v_cvt_pk_bf16_f32 %0, %1, %2" : "=v"(r) : "v"(lo), "v"(hi)); return r; }
; __device__ __forceinline__ float bf_lo(unsigned w) { return __uint_as_float(w << 16); }
; __device__ __forceinline__ float bf_hi(unsigned w) { return __uint_as_float(w & 0xffff0000u); }
; __device__ __forceinline__ float fexp(float x) { return __builtin_amdgcn_exp2f(1.44269504f * x); }
;     __device__ __forceinline__ void operator()(AccMut acc, const Unit& u, int sw) const {
;     ...
;                         const f32x2 z = (f32x2){acc[ai][1][m][n][2 * jp], acc[ai][1][m][n][2 * jp + 1]} * (-1.44269504f);
;                         f32x2 e; e.x = __builtin_amdgcn_exp2f(z.x); e.y = __builtin_amdgcn_exp2f(z.y); e = e + 1.0f;
;                         f32x2 ig; ig.x = __builtin_amdgcn_rcpf(e.x); ig.y = __builtin_amdgcn_rcpf(e.y);
;                         const f32x2 x2 = (f32x2){acc[ai][0][m][n][2 * jp], acc[ai][0][m][n][2 * jp + 1]} * 2.0f;
;                         f32x2 ser = x2 * (1.0f / 120.0f) + (1.0f / 24.0f); ser = ser * x2 + (1.0f / 6.0f); ser = ser * x2 + 0.5f; ser = ser * x2 + 1.0f; ser = ser * (-x2);
;                         f32x2 em = ser;
;                         if (__builtin_expect(__builtin_amdgcn_ballot_w64(x2.x <= -0.25f || x2.y <= -0.25f) != 0ull, 0)) {
;                             em.x = (x2.x > -0.25f) ? ser.x : (1.0f - fexp(x2.x)); em.y = (x2.y > -0.25f) ? ser.y : (1.0f - fexp(x2.y)); }
;                         const unsigned wv = xw[2 * n + jp];
;                         f32x2 sq; sq.x = __builtin_amdgcn_sqrtf(em.x); sq.y = __builtin_amdgcn_sqrtf(em.y);
;                         const f32x2 b2 = sq * ig * (f32x2){bf_lo(wv), bf_hi(wv)};
;                         bt[4 * n + 2 * jp] = b2.x; bt[4 * n + 2 * jp + 1] = b2.y; }
;                 u32x4 w; w.x = cvt_pk_bf16(bt[0], bt[1]); w.y = cvt_pk_bf16(bt[2], bt[3]); w.z = cvt_pk_bf16(bt[4], bt[5]); w.w = cvt_pk_bf16(bt[6], bt[7]);
;                 *(u32x4*)(BT + off) = w; }
	v_lshlrev_b32_e32 v196, 16, v160
	v_and_b32_e32 v197, 0xffff0000, v160
	v_lshlrev_b32_e32 v198, 16, v161
	v_and_b32_e32 v199, 0xffff0000, v161
	v_lshlrev_b32_e32 v200, 16, v162
	v_and_b32_e32 v201, 0xffff0000, v162
	v_lshlrev_b32_e32 v202, 16, v163
	v_and_b32_e32 v203, 0xffff0000, v163
	v_pk_mul_f32 v[188:189], v[188:189], v[180:181]
	v_pk_mul_f32 v[190:191], v[190:191], v[182:183]
	v_pk_mul_f32 v[192:193], v[192:193], v[184:185]
	v_pk_mul_f32 v[194:195], v[194:195], v[186:187]
	v_pk_mul_f32 v[188:189], v[188:189], v[196:197]
	v_pk_mul_f32 v[190:191], v[190:191], v[198:199]
	v_pk_mul_f32 v[192:193], v[192:193], v[200:201]
	v_pk_mul_f32 v[194:195], v[194:195], v[202:203]
	v_cvt_pk_bf16_f32 v208, v188, v189
	v_cvt_pk_bf16_f32 v209, v190, v191
	v_cvt_pk_bf16_f32 v210, v192, v193
	v_cvt_pk_bf16_f32 v211, v194, v195
	global_store_dwordx4 v178, v[208:211], s[10:11] nt
	v_pk_fma_f32 v[216:217], v[228:229], v[216:217], v[188:189]
	v_pk_fma_f32 v[218:219], v[230:231], v[218:219], v[190:191]
	v_pk_fma_f32 v[240:241], v[232:233], v[240:241], v[192:193]
	v_pk_fma_f32 v[242:243], v[234:235], v[242:243], v[194:195]
	v_pk_mul_f32 v[26:27], v[26:27], v[228:229]
	v_pk_mul_f32 v[28:29], v[28:29], v[230:231]
	v_pk_mul_f32 v[30:31], v[30:31], v[232:233]
	v_pk_mul_f32 v[32:33], v[32:33], v[234:235]
	v_pk_add_f32 v[110:111], v[110:111], v[90:91]
	v_pk_add_f32 v[112:113], v[112:113], v[92:93]
	v_pk_add_f32 v[102:103], v[102:103], v[86:87]
	v_pk_add_f32 v[104:105], v[104:105], v[88:89]
	v_pk_mul_f32 v[180:181], v[2:3], s[74:75] op_sel_hi:[1,0]
	v_pk_mul_f32 v[182:183], v[4:5], s[74:75] op_sel_hi:[1,0]
	v_pk_mul_f32 v[184:185], v[6:7], s[74:75] op_sel_hi:[1,0]
	v_pk_mul_f32 v[186:187], v[8:9], s[74:75] op_sel_hi:[1,0]
	v_exp_f32_e32 v180, v180
	v_exp_f32_e32 v181, v181
	v_exp_f32_e32 v182, v182
	v_exp_f32_e32 v183, v183
	v_exp_f32_e32 v184, v184
	v_exp_f32_e32 v185, v185
	v_exp_f32_e32 v186, v186
	v_exp_f32_e32 v187, v187
	v_pk_fma_f32 v[188:189], v[74:75], s[24:25], v[236:237] op_sel_hi:[1,0,0]
	v_pk_fma_f32 v[190:191], v[76:77], s[24:25], v[236:237] op_sel_hi:[1,0,0]
	v_pk_fma_f32 v[192:193], v[70:71], s[24:25], v[236:237] op_sel_hi:[1,0,0]
	v_pk_fma_f32 v[194:195], v[72:73], s[24:25], v[236:237] op_sel_hi:[1,0,0]
	v_pk_add_f32 v[180:181], v[180:181], 1.0 op_sel_hi:[1,0]
	v_pk_add_f32 v[182:183], v[182:183], 1.0 op_sel_hi:[1,0]
	v_pk_add_f32 v[184:185], v[184:185], 1.0 op_sel_hi:[1,0]
	v_pk_add_f32 v[186:187], v[186:187], 1.0 op_sel_hi:[1,0]
	v_rcp_f32_e32 v180, v180
	v_rcp_f32_e32 v181, v181
	v_rcp_f32_e32 v182, v182
	v_rcp_f32_e32 v183, v183
	v_rcp_f32_e32 v184, v184
	v_rcp_f32_e32 v185, v185
	v_rcp_f32_e32 v186, v186
	v_rcp_f32_e32 v187, v187
	v_pk_fma_f32 v[188:189], v[74:75], v[188:189], s[22:23] op_sel_hi:[1,1,0]
	v_pk_fma_f32 v[190:191], v[76:77], v[190:191], s[22:23] op_sel_hi:[1,1,0]
	v_pk_fma_f32 v[192:193], v[70:71], v[192:193], s[22:23] op_sel_hi:[1,1,0]
	v_pk_fma_f32 v[194:195], v[72:73], v[194:195], s[22:23] op_sel_hi:[1,1,0]
	v_pk_fma_f32 v[188:189], v[74:75], v[188:189], -2.0 op_sel_hi:[1,1,0]
	v_pk_fma_f32 v[190:191], v[76:77], v[190:191], -2.0 op_sel_hi:[1,1,0]
	v_pk_fma_f32 v[192:193], v[70:71], v[192:193], -2.0 op_sel_hi:[1,1,0]
	v_pk_fma_f32 v[194:195], v[72:73], v[194:195], -2.0 op_sel_hi:[1,1,0]
	v_pk_fma_f32 v[188:189], v[74:75], v[188:189], -2.0 op_sel_hi:[1,1,0]
	v_pk_fma_f32 v[190:191], v[76:77], v[190:191], -2.0 op_sel_hi:[1,1,0]
	v_pk_fma_f32 v[192:193], v[70:71], v[192:193], -2.0 op_sel_hi:[1,1,0]
	v_pk_fma_f32 v[194:195], v[72:73], v[194:195], -2.0 op_sel_hi:[1,1,0]
	v_pk_mul_f32 v[188:189], v[74:75], v[188:189]
	v_pk_mul_f32 v[190:191], v[76:77], v[190:191]
	v_pk_mul_f32 v[192:193], v[70:71], v[192:193]
	v_pk_mul_f32 v[194:195], v[72:73], v[194:195]
	v_mul_f32_e32 v196, s17, v74
	v_mul_f32_e32 v197, s17, v75
	v_mul_f32_e32 v198, s17, v76
	v_mul_f32_e32 v199, s17, v77
	v_mul_f32_e32 v200, s17, v70
	v_mul_f32_e32 v201, s17, v71
	v_mul_f32_e32 v202, s17, v72
	v_mul_f32_e32 v203, s17, v73
	v_exp_f32_e32 v196, v196
	v_exp_f32_e32 v197, v197
	v_exp_f32_e32 v198, v198
	v_exp_f32_e32 v199, v199
	v_exp_f32_e32 v200, v200
	v_exp_f32_e32 v201, v201
	v_exp_f32_e32 v202, v202
	v_exp_f32_e32 v203, v203
	v_pk_add_f32 v[196:197], v[196:197], 1.0 op_sel_hi:[1,0] neg_lo:[1,0] neg_hi:[1,0]
	v_pk_add_f32 v[198:199], v[198:199], 1.0 op_sel_hi:[1,0] neg_lo:[1,0] neg_hi:[1,0]
	v_pk_add_f32 v[200:201], v[200:201], 1.0 op_sel_hi:[1,0] neg_lo:[1,0] neg_hi:[1,0]
	v_pk_add_f32 v[202:203], v[202:203], 1.0 op_sel_hi:[1,0] neg_lo:[1,0] neg_hi:[1,0]
	v_cmp_lt_f32_e32 vcc, s13, v74
	s_nop 1
	v_cndmask_b32_e32 v188, v196, v188, vcc
	v_cmp_lt_f32_e32 vcc, s13, v75
	s_nop 1
	v_cndmask_b32_e32 v189, v197, v189, vcc
	v_cmp_lt_f32_e32 vcc, s13, v76
	s_nop 1
	v_cndmask_b32_e32 v190, v198, v190, vcc
	v_cmp_lt_f32_e32 vcc, s13, v77
	s_nop 1
	v_cndmask_b32_e32 v191, v199, v191, vcc
	v_cmp_lt_f32_e32 vcc, s13, v70
	s_nop 1
	v_cndmask_b32_e32 v192, v200, v192, vcc
	v_cmp_lt_f32_e32 vcc, s13, v71
	s_nop 1
	v_cndmask_b32_e32 v193, v201, v193, vcc
	v_cmp_lt_f32_e32 vcc, s13, v72
	s_nop 1
	v_cndmask_b32_e32 v194, v202, v194, vcc
	v_cmp_lt_f32_e32 vcc, s13, v73
	s_nop 1
	v_cndmask_b32_e32 v195, v203, v195, vcc
	v_pk_mul_f32 v[228:229], v[74:75], s[74:75] op_sel_hi:[1,0] neg_lo:[0,1] neg_hi:[0,1]
	v_pk_mul_f32 v[230:231], v[76:77], s[74:75] op_sel_hi:[1,0] neg_lo:[0,1] neg_hi:[0,1]
	v_pk_mul_f32 v[232:233], v[70:71], s[74:75] op_sel_hi:[1,0] neg_lo:[0,1] neg_hi:[0,1]
	v_pk_mul_f32 v[234:235], v[72:73], s[74:75] op_sel_hi:[1,0] neg_lo:[0,1] neg_hi:[0,1]
	v_sqrt_f32_e32 v188, v188
	v_sqrt_f32_e32 v189, v189
	v_sqrt_f32_e32 v190, v190
	v_sqrt_f32_e32 v191, v191
	v_sqrt_f32_e32 v192, v192
	v_sqrt_f32_e32 v193, v193
	v_sqrt_f32_e32 v194, v194
	v_sqrt_f32_e32 v195, v195
	v_exp_f32_e32 v228, v228
	v_exp_f32_e32 v229, v229
	v_exp_f32_e32 v230, v230
	v_exp_f32_e32 v231, v231
	v_exp_f32_e32 v232, v232
	v_exp_f32_e32 v233, v233
	v_exp_f32_e32 v234, v234
	v_exp_f32_e32 v235, v235
	s_waitcnt vmcnt(19)
; __device__ __forceinline__ unsigned cvt_pk_bf16(float lo, float hi) { unsigned r; asm volatile("v_cvt_pk_bf16_f32 %0, %1, %2" : "=v"(r) : "v"(lo), "v"(hi)); return r; }
; __device__ __forceinline__ float bf_lo(unsigned w) { return __uint_as_float(w << 16); }
;     __device__ __forceinline__ void operator()(AccMut acc, const Unit& u, int sw) const {
;     ...
;                         const f32x2 z = (f32x2){acc[ai][1][m][n][2 * jp], acc[ai][1][m][n][2 * jp + 1]} * (-1.44269504f);
;                         f32x2 e; e.x = __builtin_amdgcn_exp2f(z.x); e.y = __builtin_amdgcn_exp2f(z.y); e = e + 1.0f;
;                         f32x2 ig; ig.x = __builtin_amdgcn_rcpf(e.x); ig.y = __builtin_amdgcn_rcpf(e.y);
;                         const f32x2 x2 = (f32x2){acc[ai][0][m][n][2 * jp], acc[ai][0][m][n][2 * jp + 1]} * 2.0f;
;                         f32x2 ser = x2 * (1.0f / 120.0f) + (1.0f / 24.0f); ser = ser * x2 + (1.0f / 6.0f); ser = ser * x2 + 0.5f; ser = ser * x2 + 1.0f; ser = ser * (-x2);
;                         f32x2 em = ser;
;                         if (__builtin_expect(__builtin_amdgcn_ballot_w64(x2.x <= -0.25f || x2.y <= -0.25f) != 0ull, 0)) {
;                             em.x = (x2.x > -0.25f) ? ser.x : (1.0f - fexp(x2.x)); em.y = (x2.y > -0.25f) ? ser.y : (1.0f - fexp(x2.y)); }
;                         const unsigned wv = xw[2 * n + jp];
;                         f32x2 sq; sq.x = __builtin_amdgcn_sqrtf(em.x); sq.y = __builtin_amdgcn_sqrtf(em.y);
;                         const f32x2 b2 = sq * ig * (f32x2){bf_lo(wv), bf_hi(wv)};
;                         bt[4 * n + 2 * jp] = b2.x; bt[4 * n + 2 * jp + 1] = b2.y; }
;                 u32x4 w; w.x = cvt_pk_bf16(bt[0], bt[1]); w.y = cvt_pk_bf16(bt[2], bt[3]); w.z = cvt_pk_bf16(bt[4], bt[5]); w.w = cvt_pk_bf16(bt[6], bt[7]);
;                 *(u32x4*)(BT + off) = w; }
; __device__ __forceinline__ void scan1_phase(const bf16_t* LA, const bf16_t* BT, int sw, View vw) {
;     ...
;             for (int i = 0; i < 8; ++i) {
;                 const float l0 = bf_lo(lw[i].x), l1 = bf_hi(lw[i].x), l2 = bf_lo(lw[i].y), l3 = bf_hi(lw[i].y);
;                 S[0] += l0; S[1] += l1; S[2] += l2; S[3] += l3;
;                 Hc[0] = fexp(l0) * Hc[0] + bf_lo(bw[i].x); Hc[1] = fexp(l1) * Hc[1] + bf_hi(bw[i].x); Hc[2] = fexp(l2) * Hc[2] + bf_lo(bw[i].y); Hc[3] = fexp(l3) * Hc[3] + bf_hi(bw[i].y); }
	v_lshlrev_b32_e32 v196, 16, v164
	v_and_b32_e32 v197, 0xffff0000, v164
	v_lshlrev_b32_e32 v198, 16, v165
	v_and_b32_e32 v199, 0xffff0000, v165
	v_lshlrev_b32_e32 v200, 16, v166
	v_and_b32_e32 v201, 0xffff0000, v166
	v_lshlrev_b32_e32 v202, 16, v167
	v_and_b32_e32 v203, 0xffff0000, v167
	v_pk_mul_f32 v[188:189], v[188:189], v[180:181]
	v_pk_mul_f32 v[190:191], v[190:191], v[182:183]
	v_pk_mul_f32 v[192:193], v[192:193], v[184:185]
	v_pk_mul_f32 v[194:195], v[194:195], v[186:187]
	v_pk_mul_f32 v[188:189], v[188:189], v[196:197]
	v_pk_mul_f32 v[190:191], v[190:191], v[198:199]
	v_pk_mul_f32 v[192:193], v[192:193], v[200:201]
	v_pk_mul_f32 v[194:195], v[194:195], v[202:203]
	v_cvt_pk_bf16_f32 v212, v188, v189
	v_cvt_pk_bf16_f32 v213, v190, v191
	v_cvt_pk_bf16_f32 v214, v192, v193
	v_cvt_pk_bf16_f32 v215, v194, v195
	global_store_dwordx4 v179, v[212:215], s[10:11] nt
	v_pk_fma_f32 v[216:217], v[228:229], v[216:217], v[188:189]
	v_pk_fma_f32 v[218:219], v[230:231], v[218:219], v[190:191]
	v_pk_fma_f32 v[240:241], v[232:233], v[240:241], v[192:193]
	v_pk_fma_f32 v[242:243], v[234:235], v[242:243], v[194:195]
	v_pk_mul_f32 v[26:27], v[26:27], v[228:229]
	v_pk_mul_f32 v[28:29], v[28:29], v[230:231]
	v_pk_mul_f32 v[30:31], v[30:31], v[232:233]
	v_pk_mul_f32 v[32:33], v[32:33], v[234:235]
	v_pk_add_f32 v[110:111], v[110:111], v[74:75]
	v_pk_add_f32 v[112:113], v[112:113], v[76:77]
	v_pk_add_f32 v[102:103], v[102:103], v[70:71]
	v_pk_add_f32 v[104:105], v[104:105], v[72:73]
	v_fmac_f32_dpp v216, v216, v26 row_shr:1 row_mask:0xf bank_mask:0xf
	v_fmac_f32_dpp v217, v217, v27 row_shr:1 row_mask:0xf bank_mask:0xf
	v_fmac_f32_dpp v218, v218, v28 row_shr:1 row_mask:0xf bank_mask:0xf
	v_fmac_f32_dpp v219, v219, v29 row_shr:1 row_mask:0xf bank_mask:0xf
	v_fmac_f32_dpp v240, v240, v30 row_shr:1 row_mask:0xf bank_mask:0xf
	v_fmac_f32_dpp v241, v241, v31 row_shr:1 row_mask:0xf bank_mask:0xf
	v_fmac_f32_dpp v242, v242, v32 row_shr:1 row_mask:0xf bank_mask:0xf
	v_fmac_f32_dpp v243, v243, v33 row_shr:1 row_mask:0xf bank_mask:0xf
	v_mul_f32_dpp v26, v26, v26 row_shr:1 row_mask:0xf bank_mask:0xf
	v_mul_f32_dpp v27, v27, v27 row_shr:1 row_mask:0xf bank_mask:0xf
	v_mul_f32_dpp v28, v28, v28 row_shr:1 row_mask:0xf bank_mask:0xf
	v_mul_f32_dpp v29, v29, v29 row_shr:1 row_mask:0xf bank_mask:0xf
	v_mul_f32_dpp v30, v30, v30 row_shr:1 row_mask:0xf bank_mask:0xf
	v_mul_f32_dpp v31, v31, v31 row_shr:1 row_mask:0xf bank_mask:0xf
	v_mul_f32_dpp v32, v32, v32 row_shr:1 row_mask:0xf bank_mask:0xf
	v_mul_f32_dpp v33, v33, v33 row_shr:1 row_mask:0xf bank_mask:0xf
	v_add_f32_dpp v110, v110, v110 row_shr:1 row_mask:0xf bank_mask:0xf
	v_add_f32_dpp v111, v111, v111 row_shr:1 row_mask:0xf bank_mask:0xf
	v_add_f32_dpp v112, v112, v112 row_shr:1 row_mask:0xf bank_mask:0xf
	v_add_f32_dpp v113, v113, v113 row_shr:1 row_mask:0xf bank_mask:0xf
	v_add_f32_dpp v102, v102, v102 row_shr:1 row_mask:0xf bank_mask:0xf
	v_add_f32_dpp v103, v103, v103 row_shr:1 row_mask:0xf bank_mask:0xf
	v_add_f32_dpp v104, v104, v104 row_shr:1 row_mask:0xf bank_mask:0xf
	v_add_f32_dpp v105, v105, v105 row_shr:1 row_mask:0xf bank_mask:0xf
	v_fmac_f32_dpp v216, v216, v26 row_shr:2 row_mask:0xf bank_mask:0xf
	v_fmac_f32_dpp v217, v217, v27 row_shr:2 row_mask:0xf bank_mask:0xf
	v_fmac_f32_dpp v218, v218, v28 row_shr:2 row_mask:0xf bank_mask:0xf
	v_fmac_f32_dpp v219, v219, v29 row_shr:2 row_mask:0xf bank_mask:0xf
	v_fmac_f32_dpp v240, v240, v30 row_shr:2 row_mask:0xf bank_mask:0xf
	v_fmac_f32_dpp v241, v241, v31 row_shr:2 row_mask:0xf bank_mask:0xf
	v_fmac_f32_dpp v242, v242, v32 row_shr:2 row_mask:0xf bank_mask:0xf
	v_fmac_f32_dpp v243, v243, v33 row_shr:2 row_mask:0xf bank_mask:0xf
	v_mul_f32_dpp v26, v26, v26 row_shr:2 row_mask:0xf bank_mask:0xf
	v_mul_f32_dpp v27, v27, v27 row_shr:2 row_mask:0xf bank_mask:0xf
	v_mul_f32_dpp v28, v28, v28 row_shr:2 row_mask:0xf bank_mask:0xf
	v_mul_f32_dpp v29, v29, v29 row_shr:2 row_mask:0xf bank_mask:0xf
	v_mul_f32_dpp v30, v30, v30 row_shr:2 row_mask:0xf bank_mask:0xf
; __device__ __forceinline__ float bf_lo(unsigned w) { return __uint_as_float(w << 16); }
; __device__ __forceinline__ float bf_hi(unsigned w) { return __uint_as_float(w & 0xffff0000u); }
; __device__ __forceinline__ float fexp(float x) { return __builtin_amdgcn_exp2f(1.44269504f * x); }
; __device__ __forceinline__ void scan1_phase(const bf16_t* LA, const bf16_t* BT, int sw, View vw) {
;     ...
;             for (int i = 0; i < 8; ++i) {
;                 const float l0 = bf_lo(lw[i].x), l1 = bf_hi(lw[i].x), l2 = bf_lo(lw[i].y), l3 = bf_hi(lw[i].y);
;                 S[0] += l0; S[1] += l1; S[2] += l2; S[3] += l3;
;                 Hc[0] = fexp(l0) * Hc[0] + bf_lo(bw[i].x); Hc[1] = fexp(l1) * Hc[1] + bf_hi(bw[i].x); Hc[2] = fexp(l2) * Hc[2] + bf_lo(bw[i].y); Hc[3] = fexp(l3) * Hc[3] + bf_hi(bw[i].y); }
;         }
;         *(f32x4*)(CP + (size_t)bq * E + 4 * quad) = (f32x4){S[0], S[1], S[2], S[3]};
;         *(f32x4*)(CH + (size_t)bq * E + 4 * quad) = (f32x4){Hc[0], Hc[1], Hc[2], Hc[3]};
	v_mul_f32_dpp v31, v31, v31 row_shr:2 row_mask:0xf bank_mask:0xf
	v_mul_f32_dpp v32, v32, v32 row_shr:2 row_mask:0xf bank_mask:0xf
	v_mul_f32_dpp v33, v33, v33 row_shr:2 row_mask:0xf bank_mask:0xf
	v_add_f32_dpp v110, v110, v110 row_shr:2 row_mask:0xf bank_mask:0xf
	v_add_f32_dpp v111, v111, v111 row_shr:2 row_mask:0xf bank_mask:0xf
	v_add_f32_dpp v112, v112, v112 row_shr:2 row_mask:0xf bank_mask:0xf
	v_add_f32_dpp v113, v113, v113 row_shr:2 row_mask:0xf bank_mask:0xf
	v_add_f32_dpp v102, v102, v102 row_shr:2 row_mask:0xf bank_mask:0xf
	v_add_f32_dpp v103, v103, v103 row_shr:2 row_mask:0xf bank_mask:0xf
	v_add_f32_dpp v104, v104, v104 row_shr:2 row_mask:0xf bank_mask:0xf
	v_add_f32_dpp v105, v105, v105 row_shr:2 row_mask:0xf bank_mask:0xf
	v_fmac_f32_dpp v216, v216, v26 row_shr:4 row_mask:0xf bank_mask:0xf
	v_fmac_f32_dpp v217, v217, v27 row_shr:4 row_mask:0xf bank_mask:0xf
	v_fmac_f32_dpp v218, v218, v28 row_shr:4 row_mask:0xf bank_mask:0xf
	v_fmac_f32_dpp v219, v219, v29 row_shr:4 row_mask:0xf bank_mask:0xf
	v_fmac_f32_dpp v240, v240, v30 row_shr:4 row_mask:0xf bank_mask:0xf
	v_fmac_f32_dpp v241, v241, v31 row_shr:4 row_mask:0xf bank_mask:0xf
	v_fmac_f32_dpp v242, v242, v32 row_shr:4 row_mask:0xf bank_mask:0xf
	v_fmac_f32_dpp v243, v243, v33 row_shr:4 row_mask:0xf bank_mask:0xf
	v_mul_f32_dpp v26, v26, v26 row_shr:4 row_mask:0xf bank_mask:0xf
	v_mul_f32_dpp v27, v27, v27 row_shr:4 row_mask:0xf bank_mask:0xf
	v_mul_f32_dpp v28, v28, v28 row_shr:4 row_mask:0xf bank_mask:0xf
	v_mul_f32_dpp v29, v29, v29 row_shr:4 row_mask:0xf bank_mask:0xf
	v_mul_f32_dpp v30, v30, v30 row_shr:4 row_mask:0xf bank_mask:0xf
	v_mul_f32_dpp v31, v31, v31 row_shr:4 row_mask:0xf bank_mask:0xf
	v_mul_f32_dpp v32, v32, v32 row_shr:4 row_mask:0xf bank_mask:0xf
	v_mul_f32_dpp v33, v33, v33 row_shr:4 row_mask:0xf bank_mask:0xf
	v_add_f32_dpp v110, v110, v110 row_shr:4 row_mask:0xf bank_mask:0xf
	v_add_f32_dpp v111, v111, v111 row_shr:4 row_mask:0xf bank_mask:0xf
	v_add_f32_dpp v112, v112, v112 row_shr:4 row_mask:0xf bank_mask:0xf
	v_add_f32_dpp v113, v113, v113 row_shr:4 row_mask:0xf bank_mask:0xf
	v_add_f32_dpp v102, v102, v102 row_shr:4 row_mask:0xf bank_mask:0xf
	v_add_f32_dpp v103, v103, v103 row_shr:4 row_mask:0xf bank_mask:0xf
	v_add_f32_dpp v104, v104, v104 row_shr:4 row_mask:0xf bank_mask:0xf
	v_add_f32_dpp v105, v105, v105 row_shr:4 row_mask:0xf bank_mask:0xf
	v_fmac_f32_dpp v216, v216, v26 row_shr:8 row_mask:0xf bank_mask:0xf
	v_fmac_f32_dpp v217, v217, v27 row_shr:8 row_mask:0xf bank_mask:0xf
	v_fmac_f32_dpp v218, v218, v28 row_shr:8 row_mask:0xf bank_mask:0xf
	v_fmac_f32_dpp v219, v219, v29 row_shr:8 row_mask:0xf bank_mask:0xf
	v_fmac_f32_dpp v240, v240, v30 row_shr:8 row_mask:0xf bank_mask:0xf
	v_fmac_f32_dpp v241, v241, v31 row_shr:8 row_mask:0xf bank_mask:0xf
	v_fmac_f32_dpp v242, v242, v32 row_shr:8 row_mask:0xf bank_mask:0xf
	v_fmac_f32_dpp v243, v243, v33 row_shr:8 row_mask:0xf bank_mask:0xf
	v_add_f32_dpp v110, v110, v110 row_shr:8 row_mask:0xf bank_mask:0xf
	v_add_f32_dpp v111, v111, v111 row_shr:8 row_mask:0xf bank_mask:0xf
	v_add_f32_dpp v112, v112, v112 row_shr:8 row_mask:0xf bank_mask:0xf
	v_add_f32_dpp v113, v113, v113 row_shr:8 row_mask:0xf bank_mask:0xf
	v_add_f32_dpp v102, v102, v102 row_shr:8 row_mask:0xf bank_mask:0xf
	v_add_f32_dpp v103, v103, v103 row_shr:8 row_mask:0xf bank_mask:0xf
	v_add_f32_dpp v104, v104, v104 row_shr:8 row_mask:0xf bank_mask:0xf
	v_add_f32_dpp v105, v105, v105 row_shr:8 row_mask:0xf bank_mask:0xf
	v_mbcnt_lo_u32_b32 v180, -1, 0
	v_mbcnt_hi_u32_b32 v180, -1, v180
	v_and_b32_e32 v180, 15, v180
	v_cmp_eq_u32_e32 vcc, 15, v180
	v_add_u32_e32 v181, 0x4000, v239
	v_add_u32_e32 v182, 0x404000, v239
	s_mov_b64 exec, vcc
	global_store_dwordx4 v181, v[110:113], s[26:27]
	global_store_dwordx4 v181, v[102:105], s[26:27] offset:16
	global_store_dwordx4 v182, v[216:219], s[26:27]
	global_store_dwordx4 v182, v[240:243], s[26:27] offset:16
	s_mov_b64 exec, -1
	s_branch .Lgate_epi_done
